# adds: merged vmcnt/lgkmcnt wait in front of each K-loop load-segment barrier
# baseline (speedup 1.0000x reference)
; #define PG8_STAGE(bufoff, gbase, voff) do { _Pragma("unroll") for (int _i = 0; _i < 2; ++_i) \
;         __builtin_amdgcn_global_load_lds((const unsigned*)((const char*)(gbase) + (voff)[_i]), (PG8_LAS unsigned*)(lds + (bufoff) + ldsw + _i * 8192), 16, 0, 0); } while (0)
; #define PG8_LDA(dst, b, h) do { _Pragma("unroll") for (int m = 0; m < 4; ++m) _Pragma("unroll") for (int k = 0; k < 2; ++k) dst[m][k] = *(const PG8_LAS bf16x8*)(lds + PG8_SA(b, h) + aoff + m * 2048 + k * 1024); } while (0)
; #define PG8_LDB(dst, b, h) do { _Pragma("unroll") for (int n = 0; n < 2; ++n) _Pragma("unroll") for (int k = 0; k < 2; ++k) dst[n][k] = *(const PG8_LAS bf16x8*)(lds + PG8_SB(b, h) + boff + n * 2048 + k * 1024); } while (0)
; #define PG8_MMA(ai, bj, At, Bt) do { __builtin_amdgcn_s_setprio(1); _Pragma("unroll") for (int m = 0; m < 4; ++m) _Pragma("unroll") for (int n = 0; n < 2; ++n) _Pragma("unroll") for (int k = 0; k < 2; ++k) \
;         acc[ai][bj][m][n] = __builtin_amdgcn_mfma_f32_16x16x32_bf16(Bt[n][k], At[m][k], acc[ai][bj][m][n], 0, 0, 0); __builtin_amdgcn_s_setprio(0); } while (0)
; #define PG8_WAIT_V(n) asm volatile("s_waitcnt vmcnt(" #n ")" ::: "memory")
; #define PG8_WAIT_L(n) asm volatile("s_waitcnt lgkmcnt(" #n ")" ::: "memory")
; #define PG8_BAR __builtin_amdgcn_s_barrier()
; #define PG8_SCHED __builtin_amdgcn_sched_barrier(0)
; template <class Epi, class Sched, bool ALIGN_EPI = false, bool SP2 = false, bool ACHUNK = false>
; __device__ __forceinline__ void gemm_phase(PG8_LAS unsigned char* lds, const Gemm g, const Sched& S, const Epi& E) {
;     ...
;             PG8_LDB(B0, 0, 0); PG8_LDB(B1, 0, 1); PG8_SCHED; PG8_LDA(At, 0, 0); PG8_STAGE(PG8_SA(1, 1), a1 + hstepA, voffA);
;             PG8_WAIT_V(8); PG8_WAIT_L(0); PG8_BAR; PG8_MMA(0, 0, At, B0); PG8_MMA(0, 1, At, B1); PG8_BAR; PG8_SCHED;
;             PG8_LDA(At, 0, 1); PG8_STAGE(PG8_SB(0, 0), b2, voffB); PG8_STAGE(PG8_SB(0, 1), b2 + hstepB, voffB); PG8_STAGE(PG8_SA(0, 0), a2, voffA);
;             PG8_WAIT_V(8); PG8_WAIT_L(0); PG8_BAR; PG8_MMA(1, 0, At, B0); PG8_MMA(1, 1, At, B1); PG8_BAR; PG8_SCHED;
.Lnl_dn:
	s_add_i32 s47, 0, 0x14000
	ds_read_b128 v[142:145], v151
	ds_read_b128 v[152:155], v151 offset:1024
	ds_read_b128 v[156:159], v151 offset:2048
	ds_read_b128 v[160:163], v151 offset:3072
	v_add_u32_e32 v151, s47, v147
	ds_read_b128 v[164:167], v151
	ds_read_b128 v[168:171], v151 offset:1024
	ds_read_b128 v[172:175], v151 offset:2048
	ds_read_b128 v[176:179], v151 offset:3072
	v_lshl_add_u64 v[192:193], s[20:21], 0, v[138:139]
	s_add_i32 m0, s23, 0xc000
	ds_read_b128 v[180:183], v150
	ds_read_b128 v[184:187], v150 offset:1024
	ds_read_b128 v[188:191], v150 offset:2048
	ds_read_b128 v[198:201], v150 offset:3072
	ds_read_b128 v[202:205], v150 offset:4096
	ds_read_b128 v[206:209], v150 offset:5120
	ds_read_b128 v[210:213], v150 offset:6144
	ds_read_b128 v[214:217], v150 offset:7168
	global_load_lds_dwordx4 v[192:193], off
	v_lshl_add_u64 v[192:193], s[20:21], 0, v[140:141]
	s_add_i32 m0, s23, 0xe000
	s_nop 0
	global_load_lds_dwordx4 v[192:193], off
	s_waitcnt vmcnt(8) lgkmcnt(0)
	s_barrier
	s_setprio 1
	v_mfma_f32_16x16x32_bf16 v[120:123], v[142:145], v[180:183], v[120:123]
	v_mfma_f32_16x16x32_bf16 v[128:131], v[156:159], v[180:183], v[128:131]
	v_mfma_f32_16x16x32_bf16 v[104:107], v[142:145], v[188:191], v[104:107]
	v_mfma_f32_16x16x32_bf16 v[112:115], v[156:159], v[188:191], v[112:115]
	v_mfma_f32_16x16x32_bf16 v[88:91], v[142:145], v[202:205], v[88:91]
	v_mfma_f32_16x16x32_bf16 v[96:99], v[156:159], v[202:205], v[96:99]
	v_mfma_f32_16x16x32_bf16 v[72:75], v[142:145], v[210:213], v[72:75]
	v_mfma_f32_16x16x32_bf16 v[80:83], v[156:159], v[210:213], v[80:83]
	v_mfma_f32_16x16x32_bf16 v[120:123], v[152:155], v[184:187], v[120:123]
	v_mfma_f32_16x16x32_bf16 v[128:131], v[160:163], v[184:187], v[128:131]
	v_mfma_f32_16x16x32_bf16 v[104:107], v[152:155], v[198:201], v[104:107]
	v_mfma_f32_16x16x32_bf16 v[112:115], v[160:163], v[198:201], v[112:115]
	v_mfma_f32_16x16x32_bf16 v[88:91], v[152:155], v[206:209], v[88:91]
	v_mfma_f32_16x16x32_bf16 v[96:99], v[160:163], v[206:209], v[96:99]
	v_mfma_f32_16x16x32_bf16 v[72:75], v[152:155], v[214:217], v[72:75]
	v_mfma_f32_16x16x32_bf16 v[80:83], v[160:163], v[214:217], v[80:83]
	s_setprio 0
	s_setprio 1
	v_mfma_f32_16x16x32_bf16 v[116:119], v[164:167], v[180:183], v[116:119]
	v_mfma_f32_16x16x32_bf16 v[124:127], v[172:175], v[180:183], v[124:127]
	v_mfma_f32_16x16x32_bf16 v[100:103], v[164:167], v[188:191], v[100:103]
	v_mfma_f32_16x16x32_bf16 v[108:111], v[172:175], v[188:191], v[108:111]
	v_mfma_f32_16x16x32_bf16 v[84:87], v[164:167], v[202:205], v[84:87]
	v_mfma_f32_16x16x32_bf16 v[92:95], v[172:175], v[202:205], v[92:95]
	v_mfma_f32_16x16x32_bf16 v[68:71], v[164:167], v[210:213], v[68:71]
	v_mfma_f32_16x16x32_bf16 v[76:79], v[172:175], v[210:213], v[76:79]
	v_mfma_f32_16x16x32_bf16 v[116:119], v[168:171], v[184:187], v[116:119]
	v_mfma_f32_16x16x32_bf16 v[124:127], v[176:179], v[184:187], v[124:127]
	v_mfma_f32_16x16x32_bf16 v[100:103], v[168:171], v[198:201], v[100:103]
	v_mfma_f32_16x16x32_bf16 v[108:111], v[176:179], v[198:201], v[108:111]
	v_mfma_f32_16x16x32_bf16 v[84:87], v[168:171], v[206:209], v[84:87]
	v_mfma_f32_16x16x32_bf16 v[92:95], v[176:179], v[206:209], v[92:95]
	v_mfma_f32_16x16x32_bf16 v[68:71], v[168:171], v[214:217], v[68:71]
	v_mfma_f32_16x16x32_bf16 v[76:79], v[176:179], v[214:217], v[76:79]
	s_setprio 0
	s_barrier
	s_add_i32 s50, s50, s22
	v_lshl_add_u64 v[192:193], s[48:49], 0, v[2:3]
	s_mov_b32 m0, s50
	ds_read_b128 v[180:183], v150 offset:16384
	ds_read_b128 v[184:187], v150 offset:17408
	ds_read_b128 v[188:191], v150 offset:18432
	ds_read_b128 v[198:201], v150 offset:19456
	ds_read_b128 v[202:205], v150 offset:20480
	ds_read_b128 v[206:209], v150 offset:21504
	ds_read_b128 v[210:213], v150 offset:22528
	ds_read_b128 v[214:217], v150 offset:23552
	global_load_lds_dwordx4 v[192:193], off
	s_add_i32 m0, s50, 0x2000
	v_lshl_add_u64 v[218:219], s[48:49], 0, v[136:137]
	s_add_u32 s48, s48, s2
	s_addc_u32 s49, s49, s3
	s_add_i32 s47, s47, s22
	global_load_lds_dwordx4 v[218:219], off
	v_lshl_add_u64 v[220:221], s[48:49], 0, v[2:3]
	s_mov_b32 m0, s47
	v_lshl_add_u64 v[222:223], s[48:49], 0, v[136:137]
	global_load_lds_dwordx4 v[220:221], off
	s_add_i32 m0, s47, 0x2000
	v_lshl_add_u64 v[224:225], s[18:19], 0, v[132:133]
	global_load_lds_dwordx4 v[222:223], off
	s_mov_b32 m0, s23
	v_lshl_add_u64 v[232:233], s[18:19], 0, v[134:135]
	global_load_lds_dwordx4 v[224:225], off
	s_mov_b32 m0, s24
	s_nop 0
	global_load_lds_dwordx4 v[232:233], off
	s_waitcnt vmcnt(8) lgkmcnt(0)
	s_barrier
; #define PG8_STAGE(bufoff, gbase, voff) do { _Pragma("unroll") for (int _i = 0; _i < 2; ++_i) \
;         __builtin_amdgcn_global_load_lds((const unsigned*)((const char*)(gbase) + (voff)[_i]), (PG8_LAS unsigned*)(lds + (bufoff) + ldsw + _i * 8192), 16, 0, 0); } while (0)
; #define PG8_LDA(dst, b, h) do { _Pragma("unroll") for (int m = 0; m < 4; ++m) _Pragma("unroll") for (int k = 0; k < 2; ++k) dst[m][k] = *(const PG8_LAS bf16x8*)(lds + PG8_SA(b, h) + aoff + m * 2048 + k * 1024); } while (0)
; #define PG8_LDB(dst, b, h) do { _Pragma("unroll") for (int n = 0; n < 2; ++n) _Pragma("unroll") for (int k = 0; k < 2; ++k) dst[n][k] = *(const PG8_LAS bf16x8*)(lds + PG8_SB(b, h) + boff + n * 2048 + k * 1024); } while (0)
; #define PG8_MMA(ai, bj, At, Bt) do { __builtin_amdgcn_s_setprio(1); _Pragma("unroll") for (int m = 0; m < 4; ++m) _Pragma("unroll") for (int n = 0; n < 2; ++n) _Pragma("unroll") for (int k = 0; k < 2; ++k) \
;         acc[ai][bj][m][n] = __builtin_amdgcn_mfma_f32_16x16x32_bf16(Bt[n][k], At[m][k], acc[ai][bj][m][n], 0, 0, 0); __builtin_amdgcn_s_setprio(0); } while (0)
; #define PG8_WAIT_V(n) asm volatile("s_waitcnt vmcnt(" #n ")" ::: "memory")
; #define PG8_WAIT_L(n) asm volatile("s_waitcnt lgkmcnt(" #n ")" ::: "memory")
; #define PG8_BAR __builtin_amdgcn_s_barrier()
; #define PG8_SCHED __builtin_amdgcn_sched_barrier(0)
; template <class Epi, class Sched, bool ALIGN_EPI = false, bool SP2 = false, bool ACHUNK = false>
; __device__ __forceinline__ void gemm_phase(PG8_LAS unsigned char* lds, const Gemm g, const Sched& S, const Epi& E) {
;     ...
;             PG8_WAIT_V(8); PG8_WAIT_L(0); PG8_BAR; PG8_MMA(1, 0, At, B0); PG8_MMA(1, 1, At, B1); PG8_BAR; PG8_SCHED;
;             PG8_LDB(B0, 1, 0); PG8_LDB(B1, 1, 1); PG8_SCHED; PG8_LDA(At, 1, 0); PG8_STAGE(PG8_SA(0, 1), a2 + hstepA, voffA);
;             PG8_WAIT_V(8); PG8_WAIT_L(0); PG8_BAR; PG8_MMA(0, 0, At, B0); PG8_MMA(0, 1, At, B1); PG8_BAR; PG8_SCHED;
	s_setprio 1
	v_mfma_f32_16x16x32_bf16 v[56:59], v[142:145], v[180:183], v[56:59]
	v_mfma_f32_16x16x32_bf16 v[64:67], v[156:159], v[180:183], v[64:67]
	v_mfma_f32_16x16x32_bf16 v[40:43], v[142:145], v[188:191], v[40:43]
	v_mfma_f32_16x16x32_bf16 v[48:51], v[156:159], v[188:191], v[48:51]
	v_mfma_f32_16x16x32_bf16 v[24:27], v[142:145], v[202:205], v[24:27]
	v_mfma_f32_16x16x32_bf16 v[32:35], v[156:159], v[202:205], v[32:35]
	v_mfma_f32_16x16x32_bf16 v[8:11], v[142:145], v[210:213], v[8:11]
	v_mfma_f32_16x16x32_bf16 v[16:19], v[156:159], v[210:213], v[16:19]
	v_mfma_f32_16x16x32_bf16 v[56:59], v[152:155], v[184:187], v[56:59]
	v_mfma_f32_16x16x32_bf16 v[64:67], v[160:163], v[184:187], v[64:67]
	v_mfma_f32_16x16x32_bf16 v[40:43], v[152:155], v[198:201], v[40:43]
	v_mfma_f32_16x16x32_bf16 v[48:51], v[160:163], v[198:201], v[48:51]
	v_mfma_f32_16x16x32_bf16 v[24:27], v[152:155], v[206:209], v[24:27]
	v_mfma_f32_16x16x32_bf16 v[32:35], v[160:163], v[206:209], v[32:35]
	v_mfma_f32_16x16x32_bf16 v[8:11], v[152:155], v[214:217], v[8:11]
	v_mfma_f32_16x16x32_bf16 v[16:19], v[160:163], v[214:217], v[16:19]
	s_setprio 0
	s_setprio 1
	v_mfma_f32_16x16x32_bf16 v[52:55], v[164:167], v[180:183], v[52:55]
	v_mfma_f32_16x16x32_bf16 v[60:63], v[172:175], v[180:183], v[60:63]
	v_mfma_f32_16x16x32_bf16 v[36:39], v[164:167], v[188:191], v[36:39]
	v_mfma_f32_16x16x32_bf16 v[44:47], v[172:175], v[188:191], v[44:47]
	v_mfma_f32_16x16x32_bf16 v[20:23], v[164:167], v[202:205], v[20:23]
	v_mfma_f32_16x16x32_bf16 v[28:31], v[172:175], v[202:205], v[28:31]
	v_mfma_f32_16x16x32_bf16 v[4:7], v[164:167], v[210:213], v[4:7]
	v_mfma_f32_16x16x32_bf16 v[12:15], v[172:175], v[210:213], v[12:15]
	v_mfma_f32_16x16x32_bf16 v[52:55], v[168:171], v[184:187], v[52:55]
	v_mfma_f32_16x16x32_bf16 v[60:63], v[176:179], v[184:187], v[60:63]
	v_mfma_f32_16x16x32_bf16 v[36:39], v[168:171], v[198:201], v[36:39]
	v_mfma_f32_16x16x32_bf16 v[44:47], v[176:179], v[198:201], v[44:47]
	v_mfma_f32_16x16x32_bf16 v[20:23], v[168:171], v[206:209], v[20:23]
	v_mfma_f32_16x16x32_bf16 v[28:31], v[176:179], v[206:209], v[28:31]
	v_mfma_f32_16x16x32_bf16 v[4:7], v[168:171], v[214:217], v[4:7]
	v_mfma_f32_16x16x32_bf16 v[12:15], v[176:179], v[214:217], v[12:15]
	s_setprio 0
	s_barrier
	s_add_i32 s47, 0, 0x18000
	v_add_u32_e32 v151, s47, v147
	s_add_i32 s48, 0, 0x1c000
	ds_read_b128 v[142:145], v151
	ds_read_b128 v[152:155], v151 offset:1024
	ds_read_b128 v[156:159], v151 offset:2048
	ds_read_b128 v[160:163], v151 offset:3072
	v_add_u32_e32 v151, s48, v147
	ds_read_b128 v[164:167], v151
	ds_read_b128 v[168:171], v151 offset:1024
	ds_read_b128 v[172:175], v151 offset:2048
	ds_read_b128 v[176:179], v151 offset:3072
	s_add_u32 s18, s18, s2
	s_addc_u32 s19, s19, s3
	s_mov_b32 m0, s25
	v_lshl_add_u64 v[234:235], s[18:19], 0, v[132:133]
	ds_read_b128 v[180:183], v150 offset:32768
	ds_read_b128 v[184:187], v150 offset:33792
	ds_read_b128 v[188:191], v150 offset:34816
	ds_read_b128 v[198:201], v150 offset:35840
	ds_read_b128 v[202:205], v150 offset:36864
	ds_read_b128 v[206:209], v150 offset:37888
	ds_read_b128 v[210:213], v150 offset:38912
	ds_read_b128 v[214:217], v150 offset:39936
	global_load_lds_dwordx4 v[234:235], off
	v_lshl_add_u64 v[234:235], s[18:19], 0, v[134:135]
	s_mov_b32 m0, s26
	s_nop 0
	global_load_lds_dwordx4 v[234:235], off
	s_waitcnt vmcnt(8) lgkmcnt(0)
	s_barrier
	s_setprio 1
	v_mfma_f32_16x16x32_bf16 v[120:123], v[142:145], v[180:183], v[120:123]
	v_mfma_f32_16x16x32_bf16 v[128:131], v[156:159], v[180:183], v[128:131]
	v_mfma_f32_16x16x32_bf16 v[104:107], v[142:145], v[188:191], v[104:107]
	v_mfma_f32_16x16x32_bf16 v[112:115], v[156:159], v[188:191], v[112:115]
	v_mfma_f32_16x16x32_bf16 v[88:91], v[142:145], v[202:205], v[88:91]
	v_mfma_f32_16x16x32_bf16 v[96:99], v[156:159], v[202:205], v[96:99]
	v_mfma_f32_16x16x32_bf16 v[72:75], v[142:145], v[210:213], v[72:75]
	v_mfma_f32_16x16x32_bf16 v[80:83], v[156:159], v[210:213], v[80:83]
	v_mfma_f32_16x16x32_bf16 v[120:123], v[152:155], v[184:187], v[120:123]
	v_mfma_f32_16x16x32_bf16 v[128:131], v[160:163], v[184:187], v[128:131]
	v_mfma_f32_16x16x32_bf16 v[104:107], v[152:155], v[198:201], v[104:107]
	v_mfma_f32_16x16x32_bf16 v[112:115], v[160:163], v[198:201], v[112:115]
	v_mfma_f32_16x16x32_bf16 v[88:91], v[152:155], v[206:209], v[88:91]
	v_mfma_f32_16x16x32_bf16 v[96:99], v[160:163], v[206:209], v[96:99]
	v_mfma_f32_16x16x32_bf16 v[72:75], v[152:155], v[214:217], v[72:75]
	v_mfma_f32_16x16x32_bf16 v[80:83], v[160:163], v[214:217], v[80:83]
	s_setprio 0
	s_setprio 1
	v_mfma_f32_16x16x32_bf16 v[116:119], v[164:167], v[180:183], v[116:119]
	v_mfma_f32_16x16x32_bf16 v[124:127], v[172:175], v[180:183], v[124:127]
	v_mfma_f32_16x16x32_bf16 v[100:103], v[164:167], v[188:191], v[100:103]
	v_mfma_f32_16x16x32_bf16 v[108:111], v[172:175], v[188:191], v[108:111]
	v_mfma_f32_16x16x32_bf16 v[84:87], v[164:167], v[202:205], v[84:87]
	v_mfma_f32_16x16x32_bf16 v[92:95], v[172:175], v[202:205], v[92:95]
	v_mfma_f32_16x16x32_bf16 v[68:71], v[164:167], v[210:213], v[68:71]
	v_mfma_f32_16x16x32_bf16 v[76:79], v[172:175], v[210:213], v[76:79]
	v_mfma_f32_16x16x32_bf16 v[116:119], v[168:171], v[184:187], v[116:119]
	v_mfma_f32_16x16x32_bf16 v[124:127], v[176:179], v[184:187], v[124:127]
	v_mfma_f32_16x16x32_bf16 v[100:103], v[168:171], v[198:201], v[100:103]
	v_mfma_f32_16x16x32_bf16 v[108:111], v[176:179], v[198:201], v[108:111]
	v_mfma_f32_16x16x32_bf16 v[84:87], v[168:171], v[206:209], v[84:87]
	v_mfma_f32_16x16x32_bf16 v[92:95], v[176:179], v[206:209], v[92:95]
	v_mfma_f32_16x16x32_bf16 v[68:71], v[168:171], v[214:217], v[68:71]
	v_mfma_f32_16x16x32_bf16 v[76:79], v[176:179], v[214:217], v[76:79]
	s_setprio 0
	s_barrier
; #define PG8_STAGE(bufoff, gbase, voff) do { _Pragma("unroll") for (int _i = 0; _i < 2; ++_i) \
;         __builtin_amdgcn_global_load_lds((const unsigned*)((const char*)(gbase) + (voff)[_i]), (PG8_LAS unsigned*)(lds + (bufoff) + ldsw + _i * 8192), 16, 0, 0); } while (0)
; #define PG8_LDA(dst, b, h) do { _Pragma("unroll") for (int m = 0; m < 4; ++m) _Pragma("unroll") for (int k = 0; k < 2; ++k) dst[m][k] = *(const PG8_LAS bf16x8*)(lds + PG8_SA(b, h) + aoff + m * 2048 + k * 1024); } while (0)
; #define PG8_MMA(ai, bj, At, Bt) do { __builtin_amdgcn_s_setprio(1); _Pragma("unroll") for (int m = 0; m < 4; ++m) _Pragma("unroll") for (int n = 0; n < 2; ++n) _Pragma("unroll") for (int k = 0; k < 2; ++k) \
;         acc[ai][bj][m][n] = __builtin_amdgcn_mfma_f32_16x16x32_bf16(Bt[n][k], At[m][k], acc[ai][bj][m][n], 0, 0, 0); __builtin_amdgcn_s_setprio(0); } while (0)
; #define PG8_WAIT_V(n) asm volatile("s_waitcnt vmcnt(" #n ")" ::: "memory")
; #define PG8_WAIT_L(n) asm volatile("s_waitcnt lgkmcnt(" #n ")" ::: "memory")
; #define PG8_BAR __builtin_amdgcn_s_barrier()
; #define PG8_SCHED __builtin_amdgcn_sched_barrier(0)
; template <class Epi, class Sched, bool ALIGN_EPI = false, bool SP2 = false, bool ACHUNK = false>
; __device__ __forceinline__ void gemm_phase(PG8_LAS unsigned char* lds, const Gemm g, const Sched& S, const Epi& E) {
;     ...
;         for (int t = 0; t < nt; t += 2) {
;     ...
;             PG8_LDA(At, 1, 1); PG8_STAGE(PG8_SB(1, 0), b3, voffB); PG8_STAGE(PG8_SB(1, 1), b3 + hstepB, voffB); PG8_STAGE(PG8_SA(1, 0), a3, voffA);
;             PG8_WAIT_V(8); PG8_WAIT_L(0); PG8_BAR; PG8_MMA(1, 0, At, B0); PG8_MMA(1, 1, At, B1); PG8_BAR; PG8_SCHED;
	s_add_i32 s18, s47, s22
	v_lshl_add_u64 v[192:193], v[192:193], 0, s[10:11]
	s_mov_b32 m0, s18
	ds_read_b128 v[180:183], v150 offset:49152
	ds_read_b128 v[184:187], v150 offset:50176
	ds_read_b128 v[188:191], v150 offset:51200
	ds_read_b128 v[198:201], v150 offset:52224
	ds_read_b128 v[202:205], v150 offset:53248
	ds_read_b128 v[206:209], v150 offset:54272
	ds_read_b128 v[210:213], v150 offset:55296
	ds_read_b128 v[214:217], v150 offset:56320
	global_load_lds_dwordx4 v[192:193], off
	v_lshl_add_u64 v[192:193], v[218:219], 0, s[10:11]
	s_add_i32 m0, s18, 0x2000
	s_add_i32 s18, s48, s22
	global_load_lds_dwordx4 v[192:193], off
	v_lshl_add_u64 v[192:193], v[220:221], 0, s[10:11]
	s_mov_b32 m0, s18
	s_nop 0
	global_load_lds_dwordx4 v[192:193], off
	v_lshl_add_u64 v[192:193], v[222:223], 0, s[10:11]
	s_add_i32 m0, s18, 0x2000
	s_nop 0
	global_load_lds_dwordx4 v[192:193], off
	v_lshl_add_u64 v[192:193], v[224:225], 0, s[10:11]
	s_mov_b32 m0, s27
	s_nop 0
	global_load_lds_dwordx4 v[192:193], off
	v_lshl_add_u64 v[192:193], v[232:233], 0, s[10:11]
	s_mov_b32 m0, s28
	s_nop 0
	global_load_lds_dwordx4 v[192:193], off
	s_waitcnt vmcnt(8) lgkmcnt(0)
	s_barrier
	s_setprio 1
	v_mfma_f32_16x16x32_bf16 v[56:59], v[142:145], v[180:183], v[56:59]
	v_mfma_f32_16x16x32_bf16 v[64:67], v[156:159], v[180:183], v[64:67]
	v_mfma_f32_16x16x32_bf16 v[40:43], v[142:145], v[188:191], v[40:43]
	v_mfma_f32_16x16x32_bf16 v[48:51], v[156:159], v[188:191], v[48:51]
	v_mfma_f32_16x16x32_bf16 v[24:27], v[142:145], v[202:205], v[24:27]
	v_mfma_f32_16x16x32_bf16 v[32:35], v[156:159], v[202:205], v[32:35]
	v_mfma_f32_16x16x32_bf16 v[8:11], v[142:145], v[210:213], v[8:11]
	v_mfma_f32_16x16x32_bf16 v[16:19], v[156:159], v[210:213], v[16:19]
	v_mfma_f32_16x16x32_bf16 v[56:59], v[152:155], v[184:187], v[56:59]
	v_mfma_f32_16x16x32_bf16 v[64:67], v[160:163], v[184:187], v[64:67]
	v_mfma_f32_16x16x32_bf16 v[40:43], v[152:155], v[198:201], v[40:43]
	v_mfma_f32_16x16x32_bf16 v[48:51], v[160:163], v[198:201], v[48:51]
	v_mfma_f32_16x16x32_bf16 v[24:27], v[152:155], v[206:209], v[24:27]
	v_mfma_f32_16x16x32_bf16 v[32:35], v[160:163], v[206:209], v[32:35]
	v_mfma_f32_16x16x32_bf16 v[8:11], v[152:155], v[214:217], v[8:11]
	v_mfma_f32_16x16x32_bf16 v[16:19], v[160:163], v[214:217], v[16:19]
	s_setprio 0
	s_setprio 1
	v_mfma_f32_16x16x32_bf16 v[52:55], v[164:167], v[180:183], v[52:55]
	v_mfma_f32_16x16x32_bf16 v[60:63], v[172:175], v[180:183], v[60:63]
	v_mfma_f32_16x16x32_bf16 v[36:39], v[164:167], v[188:191], v[36:39]
	v_mfma_f32_16x16x32_bf16 v[44:47], v[172:175], v[188:191], v[44:47]
	v_mfma_f32_16x16x32_bf16 v[20:23], v[164:167], v[202:205], v[20:23]
	v_mfma_f32_16x16x32_bf16 v[28:31], v[172:175], v[202:205], v[28:31]
	v_mfma_f32_16x16x32_bf16 v[4:7], v[164:167], v[210:213], v[4:7]
	v_mfma_f32_16x16x32_bf16 v[12:15], v[172:175], v[210:213], v[12:15]
	v_mfma_f32_16x16x32_bf16 v[52:55], v[168:171], v[184:187], v[52:55]
	v_mfma_f32_16x16x32_bf16 v[60:63], v[176:179], v[184:187], v[60:63]
	v_mfma_f32_16x16x32_bf16 v[36:39], v[168:171], v[198:201], v[36:39]
	v_mfma_f32_16x16x32_bf16 v[44:47], v[176:179], v[198:201], v[44:47]
	v_mfma_f32_16x16x32_bf16 v[20:23], v[168:171], v[206:209], v[20:23]
	v_mfma_f32_16x16x32_bf16 v[28:31], v[176:179], v[206:209], v[28:31]
	v_mfma_f32_16x16x32_bf16 v[4:7], v[168:171], v[214:217], v[4:7]
	v_mfma_f32_16x16x32_bf16 v[12:15], v[176:179], v[214:217], v[12:15]
	s_setprio 0
	s_barrier
	s_add_u32 s20, s20, 0x100
	s_addc_u32 s21, s21, 0
	s_add_u32 s44, s44, 0x100
	s_addc_u32 s45, s45, 0
	s_cmp_ge_i32 s46, s29
	s_mov_b32 s18, s46
	s_cbranch_scc0 .LBB0_52
	v_readlane_b32 s47, v255, 0
	s_mov_b32 s50, s94
	s_and_b64 vcc, exec, s[12:13]
	s_cbranch_vccnz .LBB0_57
	s_branch .LBB0_58

; #define PG8_STAGE(bufoff, gbase, voff) do { _Pragma("unroll") for (int _i = 0; _i < 2; ++_i) \
;         __builtin_amdgcn_global_load_lds((const unsigned*)((const char*)(gbase) + (voff)[_i]), (PG8_LAS unsigned*)(lds + (bufoff) + ldsw + _i * 8192), 16, 0, 0); } while (0)
; #define PG8_LDA(dst, b, h) do { _Pragma("unroll") for (int m = 0; m < 4; ++m) _Pragma("unroll") for (int k = 0; k < 2; ++k) dst[m][k] = *(const PG8_LAS bf16x8*)(lds + PG8_SA(b, h) + aoff + m * 2048 + k * 1024); } while (0)
; #define PG8_LDB(dst, b, h) do { _Pragma("unroll") for (int n = 0; n < 2; ++n) _Pragma("unroll") for (int k = 0; k < 2; ++k) dst[n][k] = *(const PG8_LAS bf16x8*)(lds + PG8_SB(b, h) + boff + n * 2048 + k * 1024); } while (0)
; #define PG8_WAIT_V(n) asm volatile("s_waitcnt vmcnt(" #n ")" ::: "memory")
; #define PG8_WAIT_L(n) asm volatile("s_waitcnt lgkmcnt(" #n ")" ::: "memory")
; template <class Epi, class Sched, bool ALIGN_EPI = false, bool SP2 = false, bool ACHUNK = false>
; __device__ __forceinline__ void gemm_phase(PG8_LAS unsigned char* lds, const Gemm g, const Sched& S, const Epi& E) {
;     ...
;         const bool has_next = S.next(ui + 1, nxt);
;         const char* nA = has_next ? (const char*)g.A + (size_t)nxt.pm * tstepA : cA; const char* nB = has_next ? (const char*)g.Bt + (size_t)nxt.pn * tstepB : cB;
;         for (int t = 0; t < nt; t += 2) {
;             const bool last = (t == nt - 2);
;             if constexpr (Epi::HAS_MID) { if (t == Epi::MID_T) E.mid(acc, cur, wr, wc, fr, fq, ShflDev{}); }
;             const char* a1 = cA + (size_t)(t + 1) * kstep;
;             const char* a2 = last ? nA : cA + (size_t)(t + 2) * kstep; const char* b2 = last ? nB : cB + (size_t)(t + 2) * kstep;
;             const char* a3 = a2 + kstep; const char* b3 = b2 + kstep;
;             if (last && has_next) S.a_ready(nxt);
;             if constexpr (SP2) {
;             PG8_LDB(B0, 0, 0); PG8_LDB(B1, 0, 1); PG8_SCHED; PG8_LDA(At, 0, 0); PG8_STAGE(PG8_SA(1, 1), a1 + hstepA, voffA);
;             PG8_WAIT_V(8); PG8_WAIT_L(0); PG8_BAR; PG8_MMA(0, 0, At, B0); PG8_MMA(0, 1, At, B1); PG8_BAR; PG8_SCHED;
;             PG8_LDA(At, 0, 1); PG8_STAGE(PG8_SB(0, 0), b2, voffB); PG8_STAGE(PG8_SB(0, 1), b2 + hstepB, voffB); PG8_STAGE(PG8_SA(0, 0), a2, voffA);
;             PG8_WAIT_V(8); PG8_WAIT_L(0); PG8_BAR; PG8_MMA(1, 0, At, B0); PG8_MMA(1, 1, At, B1); PG8_BAR; PG8_SCHED;
.LBB0_108:
	s_add_i32 s6, s4, 2
	s_add_u32 s7, s0, 0x80
	s_addc_u32 s5, s1, 0
	s_add_i32 s77, 0, 0x10000
	s_cmp_eq_u32 s54, s4
	s_cselect_b32 s5, s49, s5
	s_cselect_b32 s4, s48, s7
	v_add_u32_e32 v2, s77, v224
	s_cselect_b32 s79, s51, s9
	s_cselect_b32 s78, s50, s8
	s_add_i32 s7, 0, 0x14000
	s_waitcnt lgkmcnt(0)
	ds_read_b128 v[36:39], v2
	ds_read_b128 v[40:43], v2 offset:1024
	ds_read_b128 v[44:47], v2 offset:2048
	ds_read_b128 v[48:51], v2 offset:3072
	v_add_u32_e32 v2, s7, v224
	ds_read_b128 v[52:55], v2
	ds_read_b128 v[56:59], v2 offset:1024
	ds_read_b128 v[60:63], v2 offset:2048
	ds_read_b128 v[64:67], v2 offset:3072
	s_add_u32 s98, s0, s28
	s_addc_u32 s99, s1, s29
	s_add_i32 m0, s25, 0xc000
	ds_read_b128 v[164:167], v238
	ds_read_b128 v[168:171], v238 offset:1024
	ds_read_b128 v[184:187], v238 offset:2048
	ds_read_b128 v[188:191], v238 offset:3072
	ds_read_b128 v[198:201], v238 offset:4096
	ds_read_b128 v[202:205], v238 offset:5120
	ds_read_b128 v[206:209], v238 offset:6144
	ds_read_b128 v[210:213], v238 offset:7168
	global_load_lds_dwordx4 v172, s[98:99]
	s_add_i32 m0, s25, 0xe000
	s_nop 0
	global_load_lds_dwordx4 v176, s[98:99]
	s_waitcnt vmcnt(8) lgkmcnt(0)
	s_barrier
	s_setprio 1
	v_mfma_f32_16x16x32_bf16 v[148:151], v[36:39], v[164:167], v[148:151]
	v_mfma_f32_16x16x32_bf16 v[152:155], v[44:47], v[164:167], v[152:155]
	v_mfma_f32_16x16x32_bf16 v[132:135], v[36:39], v[184:187], v[132:135]
	v_mfma_f32_16x16x32_bf16 v[140:143], v[44:47], v[184:187], v[140:143]
	v_mfma_f32_16x16x32_bf16 v[136:139], v[36:39], v[198:201], v[136:139]
	v_mfma_f32_16x16x32_bf16 v[144:147], v[44:47], v[198:201], v[144:147]
	v_mfma_f32_16x16x32_bf16 v[160:163], v[36:39], v[206:209], v[160:163]
	v_mfma_f32_16x16x32_bf16 v[156:159], v[44:47], v[206:209], v[156:159]
	v_mfma_f32_16x16x32_bf16 v[148:151], v[40:43], v[168:171], v[148:151]
	v_mfma_f32_16x16x32_bf16 v[152:155], v[48:51], v[168:171], v[152:155]
	v_mfma_f32_16x16x32_bf16 v[132:135], v[40:43], v[188:191], v[132:135]
	v_mfma_f32_16x16x32_bf16 v[140:143], v[48:51], v[188:191], v[140:143]
	v_mfma_f32_16x16x32_bf16 v[136:139], v[40:43], v[202:205], v[136:139]
	v_mfma_f32_16x16x32_bf16 v[144:147], v[48:51], v[202:205], v[144:147]
	v_mfma_f32_16x16x32_bf16 v[160:163], v[40:43], v[210:213], v[160:163]
	v_mfma_f32_16x16x32_bf16 v[156:159], v[48:51], v[210:213], v[156:159]
	s_setprio 0
	s_setprio 1
	v_mfma_f32_16x16x32_bf16 v[124:127], v[52:55], v[164:167], v[124:127]
	v_mfma_f32_16x16x32_bf16 v[128:131], v[60:63], v[164:167], v[128:131]
	v_mfma_f32_16x16x32_bf16 v[116:119], v[52:55], v[184:187], v[116:119]
	v_mfma_f32_16x16x32_bf16 v[120:123], v[60:63], v[184:187], v[120:123]
	v_mfma_f32_16x16x32_bf16 v[112:115], v[52:55], v[198:201], v[112:115]
	v_mfma_f32_16x16x32_bf16 v[108:111], v[60:63], v[198:201], v[108:111]
	v_mfma_f32_16x16x32_bf16 v[104:107], v[52:55], v[206:209], v[104:107]
	v_mfma_f32_16x16x32_bf16 v[100:103], v[60:63], v[206:209], v[100:103]
	v_mfma_f32_16x16x32_bf16 v[124:127], v[56:59], v[168:171], v[124:127]
	v_mfma_f32_16x16x32_bf16 v[128:131], v[64:67], v[168:171], v[128:131]
	v_mfma_f32_16x16x32_bf16 v[116:119], v[56:59], v[188:191], v[116:119]
	v_mfma_f32_16x16x32_bf16 v[120:123], v[64:67], v[188:191], v[120:123]
	v_mfma_f32_16x16x32_bf16 v[112:115], v[56:59], v[202:205], v[112:115]
	v_mfma_f32_16x16x32_bf16 v[108:111], v[64:67], v[202:205], v[108:111]
	v_mfma_f32_16x16x32_bf16 v[104:107], v[56:59], v[210:213], v[104:107]
	v_mfma_f32_16x16x32_bf16 v[100:103], v[64:67], v[210:213], v[100:103]
	s_setprio 0
	s_barrier
	s_add_i32 s77, s77, s17
	s_add_u32 s98, s78, s18
	s_addc_u32 s99, s79, s19
	s_mov_b32 m0, s77
	ds_read_b128 v[164:167], v238 offset:16384
	ds_read_b128 v[168:171], v238 offset:17408
	ds_read_b128 v[184:187], v238 offset:18432
	ds_read_b128 v[188:191], v238 offset:19456
	ds_read_b128 v[198:201], v238 offset:20480
	ds_read_b128 v[202:205], v238 offset:21504
	ds_read_b128 v[206:209], v238 offset:22528
	ds_read_b128 v[210:213], v238 offset:23552
	global_load_lds_dwordx4 v174, s[78:79]
	s_add_i32 m0, s77, 0x2000
	s_add_i32 s7, s7, s17
	global_load_lds_dwordx4 v178, s[78:79]
	s_mov_b32 m0, s7
	s_nop 0
	global_load_lds_dwordx4 v174, s[98:99]
	s_add_i32 m0, s7, 0x2000
	s_nop 0
	global_load_lds_dwordx4 v178, s[98:99]
	s_mov_b32 m0, s25
	s_nop 0
	global_load_lds_dwordx4 v172, s[4:5]
	s_mov_b32 m0, s26
	s_nop 0
	global_load_lds_dwordx4 v176, s[4:5]
	s_waitcnt vmcnt(8) lgkmcnt(0)
	s_barrier
	s_setprio 1
	v_mfma_f32_16x16x32_bf16 v[96:99], v[36:39], v[164:167], v[96:99]
	v_mfma_f32_16x16x32_bf16 v[92:95], v[44:47], v[164:167], v[92:95]
	v_mfma_f32_16x16x32_bf16 v[88:91], v[36:39], v[184:187], v[88:91]
	v_mfma_f32_16x16x32_bf16 v[84:87], v[44:47], v[184:187], v[84:87]
	v_mfma_f32_16x16x32_bf16 v[80:83], v[36:39], v[198:201], v[80:83]
	v_mfma_f32_16x16x32_bf16 v[76:79], v[44:47], v[198:201], v[76:79]
	v_mfma_f32_16x16x32_bf16 v[36:39], v[36:39], v[206:209], v[72:75]
	v_mfma_f32_16x16x32_bf16 v[96:99], v[40:43], v[168:171], v[96:99]
	v_mfma_f32_16x16x32_bf16 v[92:95], v[48:51], v[168:171], v[92:95]
	v_mfma_f32_16x16x32_bf16 v[88:91], v[40:43], v[188:191], v[88:91]
	v_mfma_f32_16x16x32_bf16 v[84:87], v[48:51], v[188:191], v[84:87]
	v_mfma_f32_16x16x32_bf16 v[80:83], v[40:43], v[202:205], v[80:83]
	v_mfma_f32_16x16x32_bf16 v[76:79], v[48:51], v[202:205], v[76:79]
	v_mfma_f32_16x16x32_bf16 v[36:39], v[40:43], v[210:213], v[36:39]
	v_mfma_f32_16x16x32_bf16 v[40:43], v[44:47], v[206:209], v[68:71]
	v_mfma_f32_16x16x32_bf16 v[40:43], v[48:51], v[210:213], v[40:43]
	s_setprio 0
	s_setprio 1
	v_mfma_f32_16x16x32_bf16 v[28:31], v[52:55], v[164:167], v[28:31]
	v_mfma_f32_16x16x32_bf16 v[32:35], v[60:63], v[164:167], v[32:35]
	v_mfma_f32_16x16x32_bf16 v[20:23], v[52:55], v[184:187], v[20:23]
	v_mfma_f32_16x16x32_bf16 v[24:27], v[60:63], v[184:187], v[24:27]
	v_mfma_f32_16x16x32_bf16 v[16:19], v[52:55], v[198:201], v[16:19]
	v_mfma_f32_16x16x32_bf16 v[12:15], v[60:63], v[198:201], v[12:15]
	v_mfma_f32_16x16x32_bf16 v[8:11], v[52:55], v[206:209], v[8:11]
	v_mfma_f32_16x16x32_bf16 v[4:7], v[60:63], v[206:209], v[4:7]
	v_mfma_f32_16x16x32_bf16 v[28:31], v[56:59], v[168:171], v[28:31]
	v_mfma_f32_16x16x32_bf16 v[32:35], v[64:67], v[168:171], v[32:35]
	v_mfma_f32_16x16x32_bf16 v[20:23], v[56:59], v[188:191], v[20:23]
	v_mfma_f32_16x16x32_bf16 v[24:27], v[64:67], v[188:191], v[24:27]
	v_mfma_f32_16x16x32_bf16 v[16:19], v[56:59], v[202:205], v[16:19]
	v_mfma_f32_16x16x32_bf16 v[12:15], v[64:67], v[202:205], v[12:15]
	v_mfma_f32_16x16x32_bf16 v[8:11], v[56:59], v[210:213], v[8:11]
	v_mfma_f32_16x16x32_bf16 v[4:7], v[64:67], v[210:213], v[4:7]
	s_setprio 0
	s_barrier
; #define PG8_STAGE(bufoff, gbase, voff) do { _Pragma("unroll") for (int _i = 0; _i < 2; ++_i) \
;         __builtin_amdgcn_global_load_lds((const unsigned*)((const char*)(gbase) + (voff)[_i]), (PG8_LAS unsigned*)(lds + (bufoff) + ldsw + _i * 8192), 16, 0, 0); } while (0)
; #define PG8_LDA(dst, b, h) do { _Pragma("unroll") for (int m = 0; m < 4; ++m) _Pragma("unroll") for (int k = 0; k < 2; ++k) dst[m][k] = *(const PG8_LAS bf16x8*)(lds + PG8_SA(b, h) + aoff + m * 2048 + k * 1024); } while (0)
; #define PG8_LDB(dst, b, h) do { _Pragma("unroll") for (int n = 0; n < 2; ++n) _Pragma("unroll") for (int k = 0; k < 2; ++k) dst[n][k] = *(const PG8_LAS bf16x8*)(lds + PG8_SB(b, h) + boff + n * 2048 + k * 1024); } while (0)
; #define PG8_MMA(ai, bj, At, Bt) do { __builtin_amdgcn_s_setprio(1); _Pragma("unroll") for (int m = 0; m < 4; ++m) _Pragma("unroll") for (int n = 0; n < 2; ++n) _Pragma("unroll") for (int k = 0; k < 2; ++k) \
;         acc[ai][bj][m][n] = __builtin_amdgcn_mfma_f32_16x16x32_bf16(Bt[n][k], At[m][k], acc[ai][bj][m][n], 0, 0, 0); __builtin_amdgcn_s_setprio(0); } while (0)
; #define PG8_WAIT_V(n) asm volatile("s_waitcnt vmcnt(" #n ")" ::: "memory")
; #define PG8_WAIT_L(n) asm volatile("s_waitcnt lgkmcnt(" #n ")" ::: "memory")
; #define PG8_BAR __builtin_amdgcn_s_barrier()
; #define PG8_SCHED __builtin_amdgcn_sched_barrier(0)
; template <class Epi, class Sched, bool ALIGN_EPI = false, bool SP2 = false, bool ACHUNK = false>
; __device__ __forceinline__ void gemm_phase(PG8_LAS unsigned char* lds, const Gemm g, const Sched& S, const Epi& E) {
;     ...
;             PG8_LDB(B0, 1, 0); PG8_LDB(B1, 1, 1); PG8_SCHED; PG8_LDA(At, 1, 0); PG8_STAGE(PG8_SA(0, 1), a2 + hstepA, voffA);
;             PG8_WAIT_V(8); PG8_WAIT_L(0); PG8_BAR; PG8_MMA(0, 0, At, B0); PG8_MMA(0, 1, At, B1); PG8_BAR; PG8_SCHED;
;             PG8_LDA(At, 1, 1); PG8_STAGE(PG8_SB(1, 0), b3, voffB); PG8_STAGE(PG8_SB(1, 1), b3 + hstepB, voffB); PG8_STAGE(PG8_SA(1, 0), a3, voffA);
;             PG8_WAIT_V(8); PG8_WAIT_L(0); PG8_BAR; PG8_MMA(1, 0, At, B0); PG8_MMA(1, 1, At, B1); PG8_BAR; PG8_SCHED;
	s_add_i32 s7, 0, 0x18000
	v_add_u32_e32 v2, s7, v224
	s_add_i32 s77, 0, 0x1c000
	ds_read_b128 v[44:47], v2
	ds_read_b128 v[48:51], v2 offset:1024
	ds_read_b128 v[52:55], v2 offset:2048
	ds_read_b128 v[56:59], v2 offset:3072
	v_add_u32_e32 v2, s77, v224
	ds_read_b128 v[60:63], v2
	ds_read_b128 v[64:67], v2 offset:1024
	ds_read_b128 v[164:167], v2 offset:2048
	ds_read_b128 v[168:171], v2 offset:3072
	s_add_u32 s4, s4, s28
	s_addc_u32 s5, s5, s29
	s_mov_b32 m0, s27
	ds_read_b128 v[68:71], v238 offset:32768
	ds_read_b128 v[72:75], v238 offset:33792
	ds_read_b128 v[184:187], v238 offset:34816
	ds_read_b128 v[188:191], v238 offset:35840
	ds_read_b128 v[198:201], v238 offset:36864
	ds_read_b128 v[202:205], v238 offset:37888
	ds_read_b128 v[206:209], v238 offset:38912
	ds_read_b128 v[210:213], v238 offset:39936
	global_load_lds_dwordx4 v172, s[4:5]
	s_mov_b32 m0, s36
	s_nop 0
	global_load_lds_dwordx4 v176, s[4:5]
	s_waitcnt vmcnt(8) lgkmcnt(0)
	s_barrier
	s_setprio 1
	v_mfma_f32_16x16x32_bf16 v[148:151], v[44:47], v[68:71], v[148:151]
	v_mfma_f32_16x16x32_bf16 v[152:155], v[52:55], v[68:71], v[152:155]
	v_mfma_f32_16x16x32_bf16 v[132:135], v[44:47], v[184:187], v[132:135]
	v_mfma_f32_16x16x32_bf16 v[140:143], v[52:55], v[184:187], v[140:143]
	v_mfma_f32_16x16x32_bf16 v[136:139], v[44:47], v[198:201], v[136:139]
	v_mfma_f32_16x16x32_bf16 v[144:147], v[52:55], v[198:201], v[144:147]
	v_mfma_f32_16x16x32_bf16 v[160:163], v[44:47], v[206:209], v[160:163]
	v_mfma_f32_16x16x32_bf16 v[156:159], v[52:55], v[206:209], v[156:159]
	v_mfma_f32_16x16x32_bf16 v[148:151], v[48:51], v[72:75], v[148:151]
	v_mfma_f32_16x16x32_bf16 v[152:155], v[56:59], v[72:75], v[152:155]
	v_mfma_f32_16x16x32_bf16 v[132:135], v[48:51], v[188:191], v[132:135]
	v_mfma_f32_16x16x32_bf16 v[140:143], v[56:59], v[188:191], v[140:143]
	v_mfma_f32_16x16x32_bf16 v[136:139], v[48:51], v[202:205], v[136:139]
	v_mfma_f32_16x16x32_bf16 v[144:147], v[56:59], v[202:205], v[144:147]
	v_mfma_f32_16x16x32_bf16 v[160:163], v[48:51], v[210:213], v[160:163]
	v_mfma_f32_16x16x32_bf16 v[156:159], v[56:59], v[210:213], v[156:159]
	s_setprio 0
	s_setprio 1
	v_mfma_f32_16x16x32_bf16 v[124:127], v[60:63], v[68:71], v[124:127]
	v_mfma_f32_16x16x32_bf16 v[68:71], v[164:167], v[68:71], v[128:131]
	v_mfma_f32_16x16x32_bf16 v[128:131], v[168:171], v[72:75], v[68:71]
	v_mfma_f32_16x16x32_bf16 v[68:71], v[60:63], v[184:187], v[116:119]
	v_mfma_f32_16x16x32_bf16 v[116:119], v[64:67], v[188:191], v[68:71]
	v_mfma_f32_16x16x32_bf16 v[68:71], v[164:167], v[184:187], v[120:123]
	v_mfma_f32_16x16x32_bf16 v[120:123], v[168:171], v[188:191], v[68:71]
	v_mfma_f32_16x16x32_bf16 v[68:71], v[60:63], v[198:201], v[112:115]
	v_mfma_f32_16x16x32_bf16 v[112:115], v[64:67], v[202:205], v[68:71]
	v_mfma_f32_16x16x32_bf16 v[68:71], v[164:167], v[198:201], v[108:111]
	v_mfma_f32_16x16x32_bf16 v[108:111], v[168:171], v[202:205], v[68:71]
	v_mfma_f32_16x16x32_bf16 v[68:71], v[60:63], v[206:209], v[104:107]
	v_mfma_f32_16x16x32_bf16 v[104:107], v[64:67], v[210:213], v[68:71]
	v_mfma_f32_16x16x32_bf16 v[68:71], v[164:167], v[206:209], v[100:103]
	v_mfma_f32_16x16x32_bf16 v[124:127], v[64:67], v[72:75], v[124:127]
	v_mfma_f32_16x16x32_bf16 v[100:103], v[168:171], v[210:213], v[68:71]
	s_setprio 0
	s_barrier
	s_sub_u32 s4, s4, s28
	s_subb_u32 s5, s5, s29
	s_add_u32 s4, s4, s10
	s_addc_u32 s5, s5, s11
	s_add_u32 s78, s78, s10
	s_addc_u32 s79, s79, s11
	s_add_u32 s98, s98, s10
	s_addc_u32 s99, s99, s11
	s_add_i32 m0, s7, s17
	ds_read_b128 v[184:187], v238 offset:49152
	ds_read_b128 v[188:191], v238 offset:50176
	ds_read_b128 v[198:201], v238 offset:51200
	ds_read_b128 v[202:205], v238 offset:52224
	ds_read_b128 v[206:209], v238 offset:53248
	ds_read_b128 v[210:213], v238 offset:54272
	ds_read_b128 v[214:217], v238 offset:55296
	ds_read_b128 v[218:221], v238 offset:56320
	global_load_lds_dwordx4 v174, s[78:79]
	s_add_i32 m0, m0, 0x2000
	s_nop 0
	global_load_lds_dwordx4 v178, s[78:79]
	s_add_i32 m0, s77, s17
	s_nop 0
	global_load_lds_dwordx4 v174, s[98:99]
	s_add_i32 m0, m0, 0x2000
	s_nop 0
	global_load_lds_dwordx4 v178, s[98:99]
	s_mov_b32 m0, s52
	s_nop 0
	global_load_lds_dwordx4 v172, s[4:5]
	s_mov_b32 m0, s53
	s_nop 0
	global_load_lds_dwordx4 v176, s[4:5]
	s_waitcnt vmcnt(8) lgkmcnt(0)
	s_barrier
	s_setprio 1
	v_mfma_f32_16x16x32_bf16 v[68:71], v[44:47], v[184:187], v[96:99]
	v_mfma_f32_16x16x32_bf16 v[96:99], v[48:51], v[188:191], v[68:71]
	v_mfma_f32_16x16x32_bf16 v[68:71], v[52:55], v[184:187], v[92:95]
	v_mfma_f32_16x16x32_bf16 v[92:95], v[56:59], v[188:191], v[68:71]
	v_mfma_f32_16x16x32_bf16 v[68:71], v[44:47], v[198:201], v[88:91]
	v_mfma_f32_16x16x32_bf16 v[88:91], v[48:51], v[202:205], v[68:71]
	v_mfma_f32_16x16x32_bf16 v[68:71], v[52:55], v[198:201], v[84:87]
	v_mfma_f32_16x16x32_bf16 v[84:87], v[56:59], v[202:205], v[68:71]
	v_mfma_f32_16x16x32_bf16 v[68:71], v[44:47], v[206:209], v[80:83]
	v_mfma_f32_16x16x32_bf16 v[36:39], v[44:47], v[214:217], v[36:39]
	v_mfma_f32_16x16x32_bf16 v[80:83], v[48:51], v[210:213], v[68:71]
	v_mfma_f32_16x16x32_bf16 v[68:71], v[52:55], v[206:209], v[76:79]
	v_mfma_f32_16x16x32_bf16 v[72:75], v[48:51], v[218:221], v[36:39]
	v_mfma_f32_16x16x32_bf16 v[36:39], v[52:55], v[214:217], v[40:43]
	v_mfma_f32_16x16x32_bf16 v[76:79], v[56:59], v[210:213], v[68:71]
	v_mfma_f32_16x16x32_bf16 v[68:71], v[56:59], v[218:221], v[36:39]
	s_setprio 0
	s_setprio 1
	v_mfma_f32_16x16x32_bf16 v[28:31], v[60:63], v[184:187], v[28:31]
	v_mfma_f32_16x16x32_bf16 v[32:35], v[164:167], v[184:187], v[32:35]
	v_mfma_f32_16x16x32_bf16 v[20:23], v[60:63], v[198:201], v[20:23]
	v_mfma_f32_16x16x32_bf16 v[24:27], v[164:167], v[198:201], v[24:27]
	v_mfma_f32_16x16x32_bf16 v[16:19], v[60:63], v[206:209], v[16:19]
	v_mfma_f32_16x16x32_bf16 v[12:15], v[164:167], v[206:209], v[12:15]
	v_mfma_f32_16x16x32_bf16 v[8:11], v[60:63], v[214:217], v[8:11]
	v_mfma_f32_16x16x32_bf16 v[4:7], v[164:167], v[214:217], v[4:7]
	v_mfma_f32_16x16x32_bf16 v[28:31], v[64:67], v[188:191], v[28:31]
	v_mfma_f32_16x16x32_bf16 v[32:35], v[168:171], v[188:191], v[32:35]
	v_mfma_f32_16x16x32_bf16 v[20:23], v[64:67], v[202:205], v[20:23]
	v_mfma_f32_16x16x32_bf16 v[24:27], v[168:171], v[202:205], v[24:27]
	v_mfma_f32_16x16x32_bf16 v[16:19], v[64:67], v[210:213], v[16:19]
	v_mfma_f32_16x16x32_bf16 v[12:15], v[168:171], v[210:213], v[12:15]
	v_mfma_f32_16x16x32_bf16 v[8:11], v[64:67], v[218:221], v[8:11]
	v_mfma_f32_16x16x32_bf16 v[4:7], v[168:171], v[218:221], v[4:7]
	s_setprio 0
	s_barrier
	s_add_u32 s8, s8, 0x100
	s_addc_u32 s9, s9, 0
	s_add_u32 s0, s0, 0x100
	s_addc_u32 s1, s1, 0
	s_cmp_ge_i32 s6, s37
	s_mov_b32 s4, s6
	s_cbranch_scc0 .LBB0_108
	v_readlane_b32 s78, v254, 23
	v_readlane_b32 s79, v254, 24

; #define PG8_STAGE(bufoff, gbase, voff) do { _Pragma("unroll") for (int _i = 0; _i < 2; ++_i) \
;         __builtin_amdgcn_global_load_lds((const unsigned*)((const char*)(gbase) + (voff)[_i]), (PG8_LAS unsigned*)(lds + (bufoff) + ldsw + _i * 8192), 16, 0, 0); } while (0)
; #define PG8_LDA(dst, b, h) do { _Pragma("unroll") for (int m = 0; m < 4; ++m) _Pragma("unroll") for (int k = 0; k < 2; ++k) dst[m][k] = *(const PG8_LAS bf16x8*)(lds + PG8_SA(b, h) + aoff + m * 2048 + k * 1024); } while (0)
; #define PG8_LDB(dst, b, h) do { _Pragma("unroll") for (int n = 0; n < 2; ++n) _Pragma("unroll") for (int k = 0; k < 2; ++k) dst[n][k] = *(const PG8_LAS bf16x8*)(lds + PG8_SB(b, h) + boff + n * 2048 + k * 1024); } while (0)
; #define PG8_MMA(ai, bj, At, Bt) do { __builtin_amdgcn_s_setprio(1); _Pragma("unroll") for (int m = 0; m < 4; ++m) _Pragma("unroll") for (int n = 0; n < 2; ++n) _Pragma("unroll") for (int k = 0; k < 2; ++k) \
;         acc[ai][bj][m][n] = __builtin_amdgcn_mfma_f32_16x16x32_bf16(Bt[n][k], At[m][k], acc[ai][bj][m][n], 0, 0, 0); __builtin_amdgcn_s_setprio(0); } while (0)
; #define PG8_WAIT_V(n) asm volatile("s_waitcnt vmcnt(" #n ")" ::: "memory")
; #define PG8_WAIT_L(n) asm volatile("s_waitcnt lgkmcnt(" #n ")" ::: "memory")
; #define PG8_BAR __builtin_amdgcn_s_barrier()
; #define PG8_SCHED __builtin_amdgcn_sched_barrier(0)
; template <class Epi, class Sched, bool ALIGN_EPI = false, bool SP2 = false, bool ACHUNK = false>
; __device__ __forceinline__ void gemm_phase(PG8_LAS unsigned char* lds, const Gemm g, const Sched& S, const Epi& E) {
;     ...
;             PG8_LDB(B0, 0, 0); PG8_LDB(B1, 0, 1); PG8_SCHED; PG8_LDA(At, 0, 0); PG8_STAGE(PG8_SA(1, 1), a1 + hstepA, voffA);
;             PG8_WAIT_V(8); PG8_WAIT_L(0); PG8_BAR; PG8_MMA(0, 0, At, B0); PG8_MMA(0, 1, At, B1); PG8_BAR; PG8_SCHED;
;             PG8_LDA(At, 0, 1); PG8_STAGE(PG8_SB(0, 0), b2, voffB); PG8_STAGE(PG8_SB(0, 1), b2 + hstepB, voffB); PG8_STAGE(PG8_SA(0, 0), a2, voffA);
;             PG8_WAIT_V(8); PG8_WAIT_L(0); PG8_BAR; PG8_MMA(1, 0, At, B0); PG8_MMA(1, 1, At, B1); PG8_BAR; PG8_SCHED;
.Lnl_wo:
	s_add_i32 s51, 0, 0x14000
	ds_read_b128 v[142:145], v151
	ds_read_b128 v[152:155], v151 offset:1024
	ds_read_b128 v[156:159], v151 offset:2048
	ds_read_b128 v[160:163], v151 offset:3072
	v_add_u32_e32 v151, s51, v147
	ds_read_b128 v[164:167], v151
	ds_read_b128 v[168:171], v151 offset:1024
	ds_read_b128 v[172:175], v151 offset:2048
	ds_read_b128 v[176:179], v151 offset:3072
	v_lshl_add_u64 v[192:193], s[20:21], 0, v[138:139]
	s_add_i32 m0, s27, 0xc000
	ds_read_b128 v[180:183], v149
	ds_read_b128 v[184:187], v149 offset:1024
	ds_read_b128 v[188:191], v149 offset:2048
	ds_read_b128 v[198:201], v149 offset:3072
	ds_read_b128 v[202:205], v149 offset:4096
	ds_read_b128 v[206:209], v149 offset:5120
	ds_read_b128 v[210:213], v149 offset:6144
	ds_read_b128 v[214:217], v149 offset:7168
	global_load_lds_dwordx4 v[192:193], off
	v_lshl_add_u64 v[192:193], s[20:21], 0, v[140:141]
	s_add_i32 m0, s27, 0xe000
	s_nop 0
	global_load_lds_dwordx4 v[192:193], off
	s_waitcnt vmcnt(8) lgkmcnt(0)
	s_barrier
	s_setprio 1
	v_mfma_f32_16x16x32_bf16 v[120:123], v[142:145], v[180:183], v[120:123]
	v_mfma_f32_16x16x32_bf16 v[128:131], v[156:159], v[180:183], v[128:131]
	v_mfma_f32_16x16x32_bf16 v[104:107], v[142:145], v[188:191], v[104:107]
	v_mfma_f32_16x16x32_bf16 v[112:115], v[156:159], v[188:191], v[112:115]
	v_mfma_f32_16x16x32_bf16 v[88:91], v[142:145], v[202:205], v[88:91]
	v_mfma_f32_16x16x32_bf16 v[96:99], v[156:159], v[202:205], v[96:99]
	v_mfma_f32_16x16x32_bf16 v[72:75], v[142:145], v[210:213], v[72:75]
	v_mfma_f32_16x16x32_bf16 v[80:83], v[156:159], v[210:213], v[80:83]
	v_mfma_f32_16x16x32_bf16 v[120:123], v[152:155], v[184:187], v[120:123]
	v_mfma_f32_16x16x32_bf16 v[128:131], v[160:163], v[184:187], v[128:131]
	v_mfma_f32_16x16x32_bf16 v[104:107], v[152:155], v[198:201], v[104:107]
	v_mfma_f32_16x16x32_bf16 v[112:115], v[160:163], v[198:201], v[112:115]
	v_mfma_f32_16x16x32_bf16 v[88:91], v[152:155], v[206:209], v[88:91]
	v_mfma_f32_16x16x32_bf16 v[96:99], v[160:163], v[206:209], v[96:99]
	v_mfma_f32_16x16x32_bf16 v[72:75], v[152:155], v[214:217], v[72:75]
	v_mfma_f32_16x16x32_bf16 v[80:83], v[160:163], v[214:217], v[80:83]
	s_setprio 0
	s_setprio 1
	v_mfma_f32_16x16x32_bf16 v[116:119], v[164:167], v[180:183], v[116:119]
	v_mfma_f32_16x16x32_bf16 v[124:127], v[172:175], v[180:183], v[124:127]
	v_mfma_f32_16x16x32_bf16 v[100:103], v[164:167], v[188:191], v[100:103]
	v_mfma_f32_16x16x32_bf16 v[108:111], v[172:175], v[188:191], v[108:111]
	v_mfma_f32_16x16x32_bf16 v[84:87], v[164:167], v[202:205], v[84:87]
	v_mfma_f32_16x16x32_bf16 v[92:95], v[172:175], v[202:205], v[92:95]
	v_mfma_f32_16x16x32_bf16 v[68:71], v[164:167], v[210:213], v[68:71]
	v_mfma_f32_16x16x32_bf16 v[76:79], v[172:175], v[210:213], v[76:79]
	v_mfma_f32_16x16x32_bf16 v[116:119], v[168:171], v[184:187], v[116:119]
	v_mfma_f32_16x16x32_bf16 v[124:127], v[176:179], v[184:187], v[124:127]
	v_mfma_f32_16x16x32_bf16 v[100:103], v[168:171], v[198:201], v[100:103]
	v_mfma_f32_16x16x32_bf16 v[108:111], v[176:179], v[198:201], v[108:111]
	v_mfma_f32_16x16x32_bf16 v[84:87], v[168:171], v[206:209], v[84:87]
	v_mfma_f32_16x16x32_bf16 v[92:95], v[176:179], v[206:209], v[92:95]
	v_mfma_f32_16x16x32_bf16 v[68:71], v[168:171], v[214:217], v[68:71]
	v_mfma_f32_16x16x32_bf16 v[76:79], v[176:179], v[214:217], v[76:79]
	s_setprio 0
	s_barrier
	s_add_i32 s54, s54, s26
	v_lshl_add_u64 v[192:193], s[52:53], 0, v[2:3]
	s_mov_b32 m0, s54
	ds_read_b128 v[180:183], v149 offset:16384
	ds_read_b128 v[184:187], v149 offset:17408
	ds_read_b128 v[188:191], v149 offset:18432
	ds_read_b128 v[198:201], v149 offset:19456
	ds_read_b128 v[202:205], v149 offset:20480
	ds_read_b128 v[206:209], v149 offset:21504
	ds_read_b128 v[210:213], v149 offset:22528
	ds_read_b128 v[214:217], v149 offset:23552
	global_load_lds_dwordx4 v[192:193], off
	s_add_i32 m0, s54, 0x2000
	v_lshl_add_u64 v[218:219], s[52:53], 0, v[136:137]
	s_add_u32 s52, s52, s4
	s_addc_u32 s53, s53, s5
	s_add_i32 s51, s51, s26
	global_load_lds_dwordx4 v[218:219], off
	v_lshl_add_u64 v[220:221], s[52:53], 0, v[2:3]
	s_mov_b32 m0, s51
	v_lshl_add_u64 v[222:223], s[52:53], 0, v[136:137]
	global_load_lds_dwordx4 v[220:221], off
	s_add_i32 m0, s51, 0x2000
	v_lshl_add_u64 v[224:225], s[22:23], 0, v[132:133]
	global_load_lds_dwordx4 v[222:223], off
	s_mov_b32 m0, s27
	v_lshl_add_u64 v[232:233], s[22:23], 0, v[134:135]
	global_load_lds_dwordx4 v[224:225], off
	s_mov_b32 m0, s28
	s_nop 0
	global_load_lds_dwordx4 v[232:233], off
	s_waitcnt vmcnt(8) lgkmcnt(0)
	s_barrier
; #define PG8_STAGE(bufoff, gbase, voff) do { _Pragma("unroll") for (int _i = 0; _i < 2; ++_i) \
;         __builtin_amdgcn_global_load_lds((const unsigned*)((const char*)(gbase) + (voff)[_i]), (PG8_LAS unsigned*)(lds + (bufoff) + ldsw + _i * 8192), 16, 0, 0); } while (0)
; #define PG8_LDA(dst, b, h) do { _Pragma("unroll") for (int m = 0; m < 4; ++m) _Pragma("unroll") for (int k = 0; k < 2; ++k) dst[m][k] = *(const PG8_LAS bf16x8*)(lds + PG8_SA(b, h) + aoff + m * 2048 + k * 1024); } while (0)
; #define PG8_LDB(dst, b, h) do { _Pragma("unroll") for (int n = 0; n < 2; ++n) _Pragma("unroll") for (int k = 0; k < 2; ++k) dst[n][k] = *(const PG8_LAS bf16x8*)(lds + PG8_SB(b, h) + boff + n * 2048 + k * 1024); } while (0)
; #define PG8_MMA(ai, bj, At, Bt) do { __builtin_amdgcn_s_setprio(1); _Pragma("unroll") for (int m = 0; m < 4; ++m) _Pragma("unroll") for (int n = 0; n < 2; ++n) _Pragma("unroll") for (int k = 0; k < 2; ++k) \
;         acc[ai][bj][m][n] = __builtin_amdgcn_mfma_f32_16x16x32_bf16(Bt[n][k], At[m][k], acc[ai][bj][m][n], 0, 0, 0); __builtin_amdgcn_s_setprio(0); } while (0)
; #define PG8_WAIT_V(n) asm volatile("s_waitcnt vmcnt(" #n ")" ::: "memory")
; #define PG8_WAIT_L(n) asm volatile("s_waitcnt lgkmcnt(" #n ")" ::: "memory")
; #define PG8_BAR __builtin_amdgcn_s_barrier()
; #define PG8_SCHED __builtin_amdgcn_sched_barrier(0)
; template <class Epi, class Sched, bool ALIGN_EPI = false, bool SP2 = false, bool ACHUNK = false>
; __device__ __forceinline__ void gemm_phase(PG8_LAS unsigned char* lds, const Gemm g, const Sched& S, const Epi& E) {
;     ...
;             PG8_WAIT_V(8); PG8_WAIT_L(0); PG8_BAR; PG8_MMA(1, 0, At, B0); PG8_MMA(1, 1, At, B1); PG8_BAR; PG8_SCHED;
;             PG8_LDB(B0, 1, 0); PG8_LDB(B1, 1, 1); PG8_SCHED; PG8_LDA(At, 1, 0); PG8_STAGE(PG8_SA(0, 1), a2 + hstepA, voffA);
;             PG8_WAIT_V(8); PG8_WAIT_L(0); PG8_BAR; PG8_MMA(0, 0, At, B0); PG8_MMA(0, 1, At, B1); PG8_BAR; PG8_SCHED;
	s_setprio 1
	v_mfma_f32_16x16x32_bf16 v[56:59], v[142:145], v[180:183], v[56:59]
	v_mfma_f32_16x16x32_bf16 v[64:67], v[156:159], v[180:183], v[64:67]
	v_mfma_f32_16x16x32_bf16 v[40:43], v[142:145], v[188:191], v[40:43]
	v_mfma_f32_16x16x32_bf16 v[48:51], v[156:159], v[188:191], v[48:51]
	v_mfma_f32_16x16x32_bf16 v[24:27], v[142:145], v[202:205], v[24:27]
	v_mfma_f32_16x16x32_bf16 v[32:35], v[156:159], v[202:205], v[32:35]
	v_mfma_f32_16x16x32_bf16 v[8:11], v[142:145], v[210:213], v[8:11]
	v_mfma_f32_16x16x32_bf16 v[16:19], v[156:159], v[210:213], v[16:19]
	v_mfma_f32_16x16x32_bf16 v[56:59], v[152:155], v[184:187], v[56:59]
	v_mfma_f32_16x16x32_bf16 v[64:67], v[160:163], v[184:187], v[64:67]
	v_mfma_f32_16x16x32_bf16 v[40:43], v[152:155], v[198:201], v[40:43]
	v_mfma_f32_16x16x32_bf16 v[48:51], v[160:163], v[198:201], v[48:51]
	v_mfma_f32_16x16x32_bf16 v[24:27], v[152:155], v[206:209], v[24:27]
	v_mfma_f32_16x16x32_bf16 v[32:35], v[160:163], v[206:209], v[32:35]
	v_mfma_f32_16x16x32_bf16 v[8:11], v[152:155], v[214:217], v[8:11]
	v_mfma_f32_16x16x32_bf16 v[16:19], v[160:163], v[214:217], v[16:19]
	s_setprio 0
	s_setprio 1
	v_mfma_f32_16x16x32_bf16 v[52:55], v[164:167], v[180:183], v[52:55]
	v_mfma_f32_16x16x32_bf16 v[60:63], v[172:175], v[180:183], v[60:63]
	v_mfma_f32_16x16x32_bf16 v[36:39], v[164:167], v[188:191], v[36:39]
	v_mfma_f32_16x16x32_bf16 v[44:47], v[172:175], v[188:191], v[44:47]
	v_mfma_f32_16x16x32_bf16 v[20:23], v[164:167], v[202:205], v[20:23]
	v_mfma_f32_16x16x32_bf16 v[28:31], v[172:175], v[202:205], v[28:31]
	v_mfma_f32_16x16x32_bf16 v[4:7], v[164:167], v[210:213], v[4:7]
	v_mfma_f32_16x16x32_bf16 v[12:15], v[172:175], v[210:213], v[12:15]
	v_mfma_f32_16x16x32_bf16 v[52:55], v[168:171], v[184:187], v[52:55]
	v_mfma_f32_16x16x32_bf16 v[60:63], v[176:179], v[184:187], v[60:63]
	v_mfma_f32_16x16x32_bf16 v[36:39], v[168:171], v[198:201], v[36:39]
	v_mfma_f32_16x16x32_bf16 v[44:47], v[176:179], v[198:201], v[44:47]
	v_mfma_f32_16x16x32_bf16 v[20:23], v[168:171], v[206:209], v[20:23]
	v_mfma_f32_16x16x32_bf16 v[28:31], v[176:179], v[206:209], v[28:31]
	v_mfma_f32_16x16x32_bf16 v[4:7], v[168:171], v[214:217], v[4:7]
	v_mfma_f32_16x16x32_bf16 v[12:15], v[176:179], v[214:217], v[12:15]
	s_setprio 0
	s_barrier
	s_add_i32 s51, 0, 0x18000
	v_add_u32_e32 v151, s51, v147
	s_add_i32 s52, 0, 0x1c000
	ds_read_b128 v[142:145], v151
	ds_read_b128 v[152:155], v151 offset:1024
	ds_read_b128 v[156:159], v151 offset:2048
	ds_read_b128 v[160:163], v151 offset:3072
	v_add_u32_e32 v151, s52, v147
	ds_read_b128 v[164:167], v151
	ds_read_b128 v[168:171], v151 offset:1024
	ds_read_b128 v[172:175], v151 offset:2048
	ds_read_b128 v[176:179], v151 offset:3072
	s_add_u32 s22, s22, s4
	s_addc_u32 s23, s23, s5
	s_mov_b32 m0, s29
	v_lshl_add_u64 v[234:235], s[22:23], 0, v[132:133]
	ds_read_b128 v[180:183], v149 offset:32768
	ds_read_b128 v[184:187], v149 offset:33792
	ds_read_b128 v[188:191], v149 offset:34816
	ds_read_b128 v[198:201], v149 offset:35840
	ds_read_b128 v[202:205], v149 offset:36864
	ds_read_b128 v[206:209], v149 offset:37888
	ds_read_b128 v[210:213], v149 offset:38912
	ds_read_b128 v[214:217], v149 offset:39936
	global_load_lds_dwordx4 v[234:235], off
	v_lshl_add_u64 v[234:235], s[22:23], 0, v[134:135]
	s_mov_b32 m0, s30
	s_nop 0
	global_load_lds_dwordx4 v[234:235], off
	s_waitcnt vmcnt(8) lgkmcnt(0)
	s_barrier
	s_setprio 1
	v_mfma_f32_16x16x32_bf16 v[120:123], v[142:145], v[180:183], v[120:123]
	v_mfma_f32_16x16x32_bf16 v[128:131], v[156:159], v[180:183], v[128:131]
	v_mfma_f32_16x16x32_bf16 v[104:107], v[142:145], v[188:191], v[104:107]
	v_mfma_f32_16x16x32_bf16 v[112:115], v[156:159], v[188:191], v[112:115]
	v_mfma_f32_16x16x32_bf16 v[88:91], v[142:145], v[202:205], v[88:91]
	v_mfma_f32_16x16x32_bf16 v[96:99], v[156:159], v[202:205], v[96:99]
	v_mfma_f32_16x16x32_bf16 v[72:75], v[142:145], v[210:213], v[72:75]
	v_mfma_f32_16x16x32_bf16 v[80:83], v[156:159], v[210:213], v[80:83]
	v_mfma_f32_16x16x32_bf16 v[120:123], v[152:155], v[184:187], v[120:123]
	v_mfma_f32_16x16x32_bf16 v[128:131], v[160:163], v[184:187], v[128:131]
	v_mfma_f32_16x16x32_bf16 v[104:107], v[152:155], v[198:201], v[104:107]
	v_mfma_f32_16x16x32_bf16 v[112:115], v[160:163], v[198:201], v[112:115]
	v_mfma_f32_16x16x32_bf16 v[88:91], v[152:155], v[206:209], v[88:91]
	v_mfma_f32_16x16x32_bf16 v[96:99], v[160:163], v[206:209], v[96:99]
	v_mfma_f32_16x16x32_bf16 v[72:75], v[152:155], v[214:217], v[72:75]
	v_mfma_f32_16x16x32_bf16 v[80:83], v[160:163], v[214:217], v[80:83]
	s_setprio 0
	s_setprio 1
	v_mfma_f32_16x16x32_bf16 v[116:119], v[164:167], v[180:183], v[116:119]
	v_mfma_f32_16x16x32_bf16 v[124:127], v[172:175], v[180:183], v[124:127]
	v_mfma_f32_16x16x32_bf16 v[100:103], v[164:167], v[188:191], v[100:103]
	v_mfma_f32_16x16x32_bf16 v[108:111], v[172:175], v[188:191], v[108:111]
	v_mfma_f32_16x16x32_bf16 v[84:87], v[164:167], v[202:205], v[84:87]
	v_mfma_f32_16x16x32_bf16 v[92:95], v[172:175], v[202:205], v[92:95]
	v_mfma_f32_16x16x32_bf16 v[68:71], v[164:167], v[210:213], v[68:71]
	v_mfma_f32_16x16x32_bf16 v[76:79], v[172:175], v[210:213], v[76:79]
	v_mfma_f32_16x16x32_bf16 v[116:119], v[168:171], v[184:187], v[116:119]
	v_mfma_f32_16x16x32_bf16 v[124:127], v[176:179], v[184:187], v[124:127]
	v_mfma_f32_16x16x32_bf16 v[100:103], v[168:171], v[198:201], v[100:103]
	v_mfma_f32_16x16x32_bf16 v[108:111], v[176:179], v[198:201], v[108:111]
	v_mfma_f32_16x16x32_bf16 v[84:87], v[168:171], v[206:209], v[84:87]
	v_mfma_f32_16x16x32_bf16 v[92:95], v[176:179], v[206:209], v[92:95]
	v_mfma_f32_16x16x32_bf16 v[68:71], v[168:171], v[214:217], v[68:71]
	v_mfma_f32_16x16x32_bf16 v[76:79], v[176:179], v[214:217], v[76:79]
	s_setprio 0
	s_barrier
; #define PG8_STAGE(bufoff, gbase, voff) do { _Pragma("unroll") for (int _i = 0; _i < 2; ++_i) \
;         __builtin_amdgcn_global_load_lds((const unsigned*)((const char*)(gbase) + (voff)[_i]), (PG8_LAS unsigned*)(lds + (bufoff) + ldsw + _i * 8192), 16, 0, 0); } while (0)
; #define PG8_LDA(dst, b, h) do { _Pragma("unroll") for (int m = 0; m < 4; ++m) _Pragma("unroll") for (int k = 0; k < 2; ++k) dst[m][k] = *(const PG8_LAS bf16x8*)(lds + PG8_SA(b, h) + aoff + m * 2048 + k * 1024); } while (0)
; #define PG8_MMA(ai, bj, At, Bt) do { __builtin_amdgcn_s_setprio(1); _Pragma("unroll") for (int m = 0; m < 4; ++m) _Pragma("unroll") for (int n = 0; n < 2; ++n) _Pragma("unroll") for (int k = 0; k < 2; ++k) \
;         acc[ai][bj][m][n] = __builtin_amdgcn_mfma_f32_16x16x32_bf16(Bt[n][k], At[m][k], acc[ai][bj][m][n], 0, 0, 0); __builtin_amdgcn_s_setprio(0); } while (0)
; #define PG8_WAIT_V(n) asm volatile("s_waitcnt vmcnt(" #n ")" ::: "memory")
; #define PG8_WAIT_L(n) asm volatile("s_waitcnt lgkmcnt(" #n ")" ::: "memory")
; #define PG8_BAR __builtin_amdgcn_s_barrier()
; #define PG8_SCHED __builtin_amdgcn_sched_barrier(0)
; template <class Epi, class Sched, bool ALIGN_EPI = false, bool SP2 = false, bool ACHUNK = false>
; __device__ __forceinline__ void gemm_phase(PG8_LAS unsigned char* lds, const Gemm g, const Sched& S, const Epi& E) {
;     ...
;         for (int t = 0; t < nt; t += 2) {
;     ...
;             PG8_LDA(At, 1, 1); PG8_STAGE(PG8_SB(1, 0), b3, voffB); PG8_STAGE(PG8_SB(1, 1), b3 + hstepB, voffB); PG8_STAGE(PG8_SA(1, 0), a3, voffA);
;             PG8_WAIT_V(8); PG8_WAIT_L(0); PG8_BAR; PG8_MMA(1, 0, At, B0); PG8_MMA(1, 1, At, B1); PG8_BAR; PG8_SCHED;
	s_add_i32 s22, s51, s26
	v_lshl_add_u64 v[192:193], v[192:193], 0, s[10:11]
	s_mov_b32 m0, s22
	ds_read_b128 v[180:183], v149 offset:49152
	ds_read_b128 v[184:187], v149 offset:50176
	ds_read_b128 v[188:191], v149 offset:51200
	ds_read_b128 v[198:201], v149 offset:52224
	ds_read_b128 v[202:205], v149 offset:53248
	ds_read_b128 v[206:209], v149 offset:54272
	ds_read_b128 v[210:213], v149 offset:55296
	ds_read_b128 v[214:217], v149 offset:56320
	global_load_lds_dwordx4 v[192:193], off
	v_lshl_add_u64 v[192:193], v[218:219], 0, s[10:11]
	s_add_i32 m0, s22, 0x2000
	s_add_i32 s22, s52, s26
	global_load_lds_dwordx4 v[192:193], off
	v_lshl_add_u64 v[192:193], v[220:221], 0, s[10:11]
	s_mov_b32 m0, s22
	s_nop 0
	global_load_lds_dwordx4 v[192:193], off
	v_lshl_add_u64 v[192:193], v[222:223], 0, s[10:11]
	s_add_i32 m0, s22, 0x2000
	s_nop 0
	global_load_lds_dwordx4 v[192:193], off
	v_lshl_add_u64 v[192:193], v[224:225], 0, s[10:11]
	s_mov_b32 m0, s31
	s_nop 0
	global_load_lds_dwordx4 v[192:193], off
	v_lshl_add_u64 v[192:193], v[232:233], 0, s[10:11]
	s_mov_b32 m0, s33
	s_nop 0
	global_load_lds_dwordx4 v[192:193], off
	s_waitcnt vmcnt(8) lgkmcnt(0)
	s_barrier
	s_setprio 1
	v_mfma_f32_16x16x32_bf16 v[56:59], v[142:145], v[180:183], v[56:59]
	v_mfma_f32_16x16x32_bf16 v[64:67], v[156:159], v[180:183], v[64:67]
	v_mfma_f32_16x16x32_bf16 v[40:43], v[142:145], v[188:191], v[40:43]
	v_mfma_f32_16x16x32_bf16 v[48:51], v[156:159], v[188:191], v[48:51]
	v_mfma_f32_16x16x32_bf16 v[24:27], v[142:145], v[202:205], v[24:27]
	v_mfma_f32_16x16x32_bf16 v[32:35], v[156:159], v[202:205], v[32:35]
	v_mfma_f32_16x16x32_bf16 v[8:11], v[142:145], v[210:213], v[8:11]
	v_mfma_f32_16x16x32_bf16 v[16:19], v[156:159], v[210:213], v[16:19]
	v_mfma_f32_16x16x32_bf16 v[56:59], v[152:155], v[184:187], v[56:59]
	v_mfma_f32_16x16x32_bf16 v[64:67], v[160:163], v[184:187], v[64:67]
	v_mfma_f32_16x16x32_bf16 v[40:43], v[152:155], v[198:201], v[40:43]
	v_mfma_f32_16x16x32_bf16 v[48:51], v[160:163], v[198:201], v[48:51]
	v_mfma_f32_16x16x32_bf16 v[24:27], v[152:155], v[206:209], v[24:27]
	v_mfma_f32_16x16x32_bf16 v[32:35], v[160:163], v[206:209], v[32:35]
	v_mfma_f32_16x16x32_bf16 v[8:11], v[152:155], v[214:217], v[8:11]
	v_mfma_f32_16x16x32_bf16 v[16:19], v[160:163], v[214:217], v[16:19]
	s_setprio 0
	s_setprio 1
	v_mfma_f32_16x16x32_bf16 v[52:55], v[164:167], v[180:183], v[52:55]
	v_mfma_f32_16x16x32_bf16 v[60:63], v[172:175], v[180:183], v[60:63]
	v_mfma_f32_16x16x32_bf16 v[36:39], v[164:167], v[188:191], v[36:39]
	v_mfma_f32_16x16x32_bf16 v[44:47], v[172:175], v[188:191], v[44:47]
	v_mfma_f32_16x16x32_bf16 v[20:23], v[164:167], v[202:205], v[20:23]
	v_mfma_f32_16x16x32_bf16 v[28:31], v[172:175], v[202:205], v[28:31]
	v_mfma_f32_16x16x32_bf16 v[4:7], v[164:167], v[210:213], v[4:7]
	v_mfma_f32_16x16x32_bf16 v[12:15], v[172:175], v[210:213], v[12:15]
	v_mfma_f32_16x16x32_bf16 v[52:55], v[168:171], v[184:187], v[52:55]
	v_mfma_f32_16x16x32_bf16 v[60:63], v[176:179], v[184:187], v[60:63]
	v_mfma_f32_16x16x32_bf16 v[36:39], v[168:171], v[198:201], v[36:39]
	v_mfma_f32_16x16x32_bf16 v[44:47], v[176:179], v[198:201], v[44:47]
	v_mfma_f32_16x16x32_bf16 v[20:23], v[168:171], v[206:209], v[20:23]
	v_mfma_f32_16x16x32_bf16 v[28:31], v[176:179], v[206:209], v[28:31]
	v_mfma_f32_16x16x32_bf16 v[4:7], v[168:171], v[214:217], v[4:7]
	v_mfma_f32_16x16x32_bf16 v[12:15], v[176:179], v[214:217], v[12:15]
	s_setprio 0
	s_barrier
	s_add_u32 s48, s48, 0x100
	s_addc_u32 s49, s49, 0
	s_add_u32 s20, s20, 0x100
	s_addc_u32 s21, s21, 0
	s_cmp_ge_i32 s50, s34
	s_mov_b32 s22, s50
	s_cbranch_scc0 .LBB0_216
	v_readlane_b32 s54, v254, 25
	v_readlane_b32 s52, v254, 27
	v_readlane_b32 s55, v254, 26
	v_readlane_b32 s53, v254, 28
	s_mov_b32 s50, s94
	s_and_b64 vcc, exec, s[16:17]
	s_cbranch_vccnz .LBB0_221
	s_branch .LBB0_222

; #define PG8_STAGE(bufoff, gbase, voff) do { _Pragma("unroll") for (int _i = 0; _i < 2; ++_i) \
;         __builtin_amdgcn_global_load_lds((const unsigned*)((const char*)(gbase) + (voff)[_i]), (PG8_LAS unsigned*)(lds + (bufoff) + ldsw + _i * 8192), 16, 0, 0); } while (0)
; #define PG8_LDA(dst, b, h) do { _Pragma("unroll") for (int m = 0; m < 4; ++m) _Pragma("unroll") for (int k = 0; k < 2; ++k) dst[m][k] = *(const PG8_LAS bf16x8*)(lds + PG8_SA(b, h) + aoff + m * 2048 + k * 1024); } while (0)
; #define PG8_LDB(dst, b, h) do { _Pragma("unroll") for (int n = 0; n < 2; ++n) _Pragma("unroll") for (int k = 0; k < 2; ++k) dst[n][k] = *(const PG8_LAS bf16x8*)(lds + PG8_SB(b, h) + boff + n * 2048 + k * 1024); } while (0)
; #define PG8_MMA(ai, bj, At, Bt) do { __builtin_amdgcn_s_setprio(1); _Pragma("unroll") for (int m = 0; m < 4; ++m) _Pragma("unroll") for (int n = 0; n < 2; ++n) _Pragma("unroll") for (int k = 0; k < 2; ++k) \
;         acc[ai][bj][m][n] = __builtin_amdgcn_mfma_f32_16x16x32_bf16(Bt[n][k], At[m][k], acc[ai][bj][m][n], 0, 0, 0); __builtin_amdgcn_s_setprio(0); } while (0)
; #define PG8_WAIT_V(n) asm volatile("s_waitcnt vmcnt(" #n ")" ::: "memory")
; #define PG8_WAIT_L(n) asm volatile("s_waitcnt lgkmcnt(" #n ")" ::: "memory")
; #define PG8_BAR __builtin_amdgcn_s_barrier()
; #define PG8_SCHED __builtin_amdgcn_sched_barrier(0)
; template <class Epi, class Sched, bool ALIGN_EPI = false, bool SP2 = false, bool ACHUNK = false>
; __device__ __forceinline__ void gemm_phase(PG8_LAS unsigned char* lds, const Gemm g, const Sched& S, const Epi& E) {
;     ...
;             PG8_LDB(B0, 0, 0); PG8_LDB(B1, 0, 1); PG8_SCHED; PG8_LDA(At, 0, 0); PG8_STAGE(PG8_SA(1, 1), a1 + hstepA, voffA);
;             PG8_WAIT_V(8); PG8_WAIT_L(0); PG8_BAR; PG8_MMA(0, 0, At, B0); PG8_MMA(0, 1, At, B1); PG8_BAR; PG8_SCHED;
;             PG8_LDA(At, 0, 1); PG8_STAGE(PG8_SB(0, 0), b2, voffB); PG8_STAGE(PG8_SB(0, 1), b2 + hstepB, voffB); PG8_STAGE(PG8_SA(0, 0), a2, voffA);
;             PG8_WAIT_V(8); PG8_WAIT_L(0); PG8_BAR; PG8_MMA(1, 0, At, B0); PG8_MMA(1, 1, At, B1); PG8_BAR; PG8_SCHED;
;             PG8_LDB(B0, 1, 0); PG8_LDB(B1, 1, 1); PG8_SCHED; PG8_LDA(At, 1, 0); PG8_STAGE(PG8_SA(0, 1), a2 + hstepA, voffA);
;             PG8_WAIT_V(8); PG8_WAIT_L(0); PG8_BAR; PG8_MMA(0, 0, At, B0); PG8_MMA(0, 1, At, B1); PG8_BAR; PG8_SCHED;
.Lnl_mg:
	s_add_i32 s54, 0, 0x14000
	ds_read_b128 v[134:137], v2
	ds_read_b128 v[138:141], v2 offset:1024
	ds_read_b128 v[142:145], v2 offset:2048
	ds_read_b128 v[146:149], v2 offset:3072
	v_add_u32_e32 v2, s54, v235
	ds_read_b128 v[150:153], v2
	ds_read_b128 v[154:157], v2 offset:1024
	ds_read_b128 v[158:161], v2 offset:2048
	ds_read_b128 v[162:165], v2 offset:3072
	v_lshl_add_u64 v[4:5], v[210:211], 0, s[6:7]
	s_add_i32 m0, s17, 0xc000
	ds_read_b128 v[166:169], v237
	ds_read_b128 v[170:173], v237 offset:1024
	ds_read_b128 v[174:177], v237 offset:2048
	ds_read_b128 v[178:181], v237 offset:3072
	ds_read_b128 v[182:185], v237 offset:4096
	ds_read_b128 v[186:189], v237 offset:5120
	ds_read_b128 v[190:193], v237 offset:6144
	ds_read_b128 v[214:217], v237 offset:7168
	global_load_lds_dwordx4 v[4:5], off
	v_lshl_add_u64 v[4:5], v[212:213], 0, s[6:7]
	s_add_i32 m0, s17, 0xe000
	s_nop 0
	global_load_lds_dwordx4 v[4:5], off
	s_waitcnt vmcnt(8) lgkmcnt(0)
	s_barrier
	s_setprio 1
	v_mfma_f32_16x16x32_bf16 v[126:129], v[134:137], v[166:169], v[126:129]
	v_mfma_f32_16x16x32_bf16 v[130:133], v[142:145], v[166:169], v[130:133]
	v_mfma_f32_16x16x32_bf16 v[114:117], v[134:137], v[174:177], v[114:117]
	v_mfma_f32_16x16x32_bf16 v[110:113], v[142:145], v[174:177], v[110:113]
	v_mfma_f32_16x16x32_bf16 v[98:101], v[134:137], v[182:185], v[98:101]
	v_mfma_f32_16x16x32_bf16 v[94:97], v[142:145], v[182:185], v[94:97]
	v_mfma_f32_16x16x32_bf16 v[82:85], v[134:137], v[190:193], v[82:85]
	v_mfma_f32_16x16x32_bf16 v[78:81], v[142:145], v[190:193], v[78:81]
	v_mfma_f32_16x16x32_bf16 v[126:129], v[138:141], v[170:173], v[126:129]
	v_mfma_f32_16x16x32_bf16 v[130:133], v[146:149], v[170:173], v[130:133]
	v_mfma_f32_16x16x32_bf16 v[114:117], v[138:141], v[178:181], v[114:117]
	v_mfma_f32_16x16x32_bf16 v[110:113], v[146:149], v[178:181], v[110:113]
	v_mfma_f32_16x16x32_bf16 v[98:101], v[138:141], v[186:189], v[98:101]
	v_mfma_f32_16x16x32_bf16 v[94:97], v[146:149], v[186:189], v[94:97]
	v_mfma_f32_16x16x32_bf16 v[82:85], v[138:141], v[214:217], v[82:85]
	v_mfma_f32_16x16x32_bf16 v[78:81], v[146:149], v[214:217], v[78:81]
	s_setprio 0
	s_setprio 1
	v_mfma_f32_16x16x32_bf16 v[122:125], v[150:153], v[166:169], v[122:125]
	v_mfma_f32_16x16x32_bf16 v[118:121], v[158:161], v[166:169], v[118:121]
	v_mfma_f32_16x16x32_bf16 v[106:109], v[150:153], v[174:177], v[106:109]
	v_mfma_f32_16x16x32_bf16 v[102:105], v[158:161], v[174:177], v[102:105]
	v_mfma_f32_16x16x32_bf16 v[90:93], v[150:153], v[182:185], v[90:93]
	v_mfma_f32_16x16x32_bf16 v[86:89], v[158:161], v[182:185], v[86:89]
	v_mfma_f32_16x16x32_bf16 v[74:77], v[150:153], v[190:193], v[74:77]
	v_mfma_f32_16x16x32_bf16 v[70:73], v[158:161], v[190:193], v[70:73]
	v_mfma_f32_16x16x32_bf16 v[122:125], v[154:157], v[170:173], v[122:125]
	v_mfma_f32_16x16x32_bf16 v[118:121], v[162:165], v[170:173], v[118:121]
	v_mfma_f32_16x16x32_bf16 v[106:109], v[154:157], v[178:181], v[106:109]
	v_mfma_f32_16x16x32_bf16 v[102:105], v[162:165], v[178:181], v[102:105]
	v_mfma_f32_16x16x32_bf16 v[90:93], v[154:157], v[186:189], v[90:93]
	v_mfma_f32_16x16x32_bf16 v[86:89], v[162:165], v[186:189], v[86:89]
	v_mfma_f32_16x16x32_bf16 v[74:77], v[154:157], v[214:217], v[74:77]
	v_mfma_f32_16x16x32_bf16 v[70:73], v[162:165], v[214:217], v[70:73]
	s_setprio 0
	s_barrier
	s_add_i32 s55, s55, s16
	v_lshl_add_u64 v[218:219], s[52:53], 0, v[200:201]
	s_mov_b32 m0, s55
	ds_read_b128 v[166:169], v237 offset:16384
	ds_read_b128 v[170:173], v237 offset:17408
	ds_read_b128 v[174:177], v237 offset:18432
	ds_read_b128 v[178:181], v237 offset:19456
	ds_read_b128 v[182:185], v237 offset:20480
	ds_read_b128 v[186:189], v237 offset:21504
	ds_read_b128 v[190:193], v237 offset:22528
	ds_read_b128 v[214:217], v237 offset:23552
	global_load_lds_dwordx4 v[218:219], off
	s_add_i32 m0, s55, 0x2000
	v_lshl_add_u64 v[220:221], s[52:53], 0, v[204:205]
	s_add_u32 s52, s52, s2
	s_addc_u32 s53, s53, s3
	s_add_i32 s54, s54, s16
	global_load_lds_dwordx4 v[220:221], off
	v_lshl_add_u64 v[222:223], s[52:53], 0, v[200:201]
	s_mov_b32 m0, s54
	v_lshl_add_u64 v[224:225], s[52:53], 0, v[204:205]
	global_load_lds_dwordx4 v[222:223], off
	s_add_i32 m0, s54, 0x2000
	v_lshl_add_u64 v[238:239], s[8:9], 0, v[198:199]
	global_load_lds_dwordx4 v[224:225], off
	s_mov_b32 m0, s17
	v_lshl_add_u64 v[240:241], s[8:9], 0, v[202:203]
	global_load_lds_dwordx4 v[238:239], off
	s_mov_b32 m0, s20
	s_nop 0
	global_load_lds_dwordx4 v[240:241], off
	s_waitcnt vmcnt(8) lgkmcnt(0)
	s_barrier
	s_setprio 1
	v_mfma_f32_16x16x32_bf16 v[66:69], v[134:137], v[166:169], v[66:69]
	v_mfma_f32_16x16x32_bf16 v[62:65], v[142:145], v[166:169], v[62:65]
	v_mfma_f32_16x16x32_bf16 v[50:53], v[134:137], v[174:177], v[50:53]
	v_mfma_f32_16x16x32_bf16 v[46:49], v[142:145], v[174:177], v[46:49]
	v_mfma_f32_16x16x32_bf16 v[34:37], v[134:137], v[182:185], v[34:37]
	v_mfma_f32_16x16x32_bf16 v[30:33], v[142:145], v[182:185], v[30:33]
	v_mfma_f32_16x16x32_bf16 v[18:21], v[134:137], v[190:193], v[18:21]
	v_mfma_f32_16x16x32_bf16 v[14:17], v[142:145], v[190:193], v[14:17]
	v_mfma_f32_16x16x32_bf16 v[66:69], v[138:141], v[170:173], v[66:69]
	v_mfma_f32_16x16x32_bf16 v[62:65], v[146:149], v[170:173], v[62:65]
	v_mfma_f32_16x16x32_bf16 v[50:53], v[138:141], v[178:181], v[50:53]
	v_mfma_f32_16x16x32_bf16 v[46:49], v[146:149], v[178:181], v[46:49]
	v_mfma_f32_16x16x32_bf16 v[34:37], v[138:141], v[186:189], v[34:37]
	v_mfma_f32_16x16x32_bf16 v[30:33], v[146:149], v[186:189], v[30:33]
	v_mfma_f32_16x16x32_bf16 v[18:21], v[138:141], v[214:217], v[18:21]
	v_mfma_f32_16x16x32_bf16 v[14:17], v[146:149], v[214:217], v[14:17]
	s_setprio 0
	s_setprio 1
	v_mfma_f32_16x16x32_bf16 v[58:61], v[150:153], v[166:169], v[58:61]
	v_mfma_f32_16x16x32_bf16 v[54:57], v[158:161], v[166:169], v[54:57]
	v_mfma_f32_16x16x32_bf16 v[42:45], v[150:153], v[174:177], v[42:45]
	v_mfma_f32_16x16x32_bf16 v[38:41], v[158:161], v[174:177], v[38:41]
	v_mfma_f32_16x16x32_bf16 v[26:29], v[150:153], v[182:185], v[26:29]
	v_mfma_f32_16x16x32_bf16 v[22:25], v[158:161], v[182:185], v[22:25]
	v_mfma_f32_16x16x32_bf16 v[10:13], v[150:153], v[190:193], v[10:13]
	v_mfma_f32_16x16x32_bf16 v[4:7], v[158:161], v[190:193], v[6:9]
	v_mfma_f32_16x16x32_bf16 v[58:61], v[154:157], v[170:173], v[58:61]
	v_mfma_f32_16x16x32_bf16 v[54:57], v[162:165], v[170:173], v[54:57]
	v_mfma_f32_16x16x32_bf16 v[42:45], v[154:157], v[178:181], v[42:45]
	v_mfma_f32_16x16x32_bf16 v[38:41], v[162:165], v[178:181], v[38:41]
	v_mfma_f32_16x16x32_bf16 v[26:29], v[154:157], v[186:189], v[26:29]
	v_mfma_f32_16x16x32_bf16 v[22:25], v[162:165], v[186:189], v[22:25]
	v_mfma_f32_16x16x32_bf16 v[10:13], v[154:157], v[214:217], v[10:13]
	v_mfma_f32_16x16x32_bf16 v[4:7], v[162:165], v[214:217], v[4:7]
	s_setprio 0
	s_barrier
; #define PG8_STAGE(bufoff, gbase, voff) do { _Pragma("unroll") for (int _i = 0; _i < 2; ++_i) \
;         __builtin_amdgcn_global_load_lds((const unsigned*)((const char*)(gbase) + (voff)[_i]), (PG8_LAS unsigned*)(lds + (bufoff) + ldsw + _i * 8192), 16, 0, 0); } while (0)
; #define PG8_LDA(dst, b, h) do { _Pragma("unroll") for (int m = 0; m < 4; ++m) _Pragma("unroll") for (int k = 0; k < 2; ++k) dst[m][k] = *(const PG8_LAS bf16x8*)(lds + PG8_SA(b, h) + aoff + m * 2048 + k * 1024); } while (0)
; #define PG8_LDB(dst, b, h) do { _Pragma("unroll") for (int n = 0; n < 2; ++n) _Pragma("unroll") for (int k = 0; k < 2; ++k) dst[n][k] = *(const PG8_LAS bf16x8*)(lds + PG8_SB(b, h) + boff + n * 2048 + k * 1024); } while (0)
; #define PG8_MMA(ai, bj, At, Bt) do { __builtin_amdgcn_s_setprio(1); _Pragma("unroll") for (int m = 0; m < 4; ++m) _Pragma("unroll") for (int n = 0; n < 2; ++n) _Pragma("unroll") for (int k = 0; k < 2; ++k) \
;         acc[ai][bj][m][n] = __builtin_amdgcn_mfma_f32_16x16x32_bf16(Bt[n][k], At[m][k], acc[ai][bj][m][n], 0, 0, 0); __builtin_amdgcn_s_setprio(0); } while (0)
; #define PG8_WAIT_V(n) asm volatile("s_waitcnt vmcnt(" #n ")" ::: "memory")
; #define PG8_WAIT_L(n) asm volatile("s_waitcnt lgkmcnt(" #n ")" ::: "memory")
; #define PG8_BAR __builtin_amdgcn_s_barrier()
; #define PG8_SCHED __builtin_amdgcn_sched_barrier(0)
; template <class Epi, class Sched, bool ALIGN_EPI = false, bool SP2 = false, bool ACHUNK = false>
; __device__ __forceinline__ void gemm_phase(PG8_LAS unsigned char* lds, const Gemm g, const Sched& S, const Epi& E) {
;     ...
;             PG8_LDB(B0, 1, 0); PG8_LDB(B1, 1, 1); PG8_SCHED; PG8_LDA(At, 1, 0); PG8_STAGE(PG8_SA(0, 1), a2 + hstepA, voffA);
;             PG8_WAIT_V(8); PG8_WAIT_L(0); PG8_BAR; PG8_MMA(0, 0, At, B0); PG8_MMA(0, 1, At, B1); PG8_BAR; PG8_SCHED;
;             PG8_LDA(At, 1, 1); PG8_STAGE(PG8_SB(1, 0), b3, voffB); PG8_STAGE(PG8_SB(1, 1), b3 + hstepB, voffB); PG8_STAGE(PG8_SA(1, 0), a3, voffA);
;             PG8_WAIT_V(8); PG8_WAIT_L(0); PG8_BAR; PG8_MMA(1, 0, At, B0); PG8_MMA(1, 1, At, B1); PG8_BAR; PG8_SCHED;
	s_add_i32 s52, 0, 0x18000
	v_add_u32_e32 v2, s52, v235
	s_add_i32 s53, 0, 0x1c000
	ds_read_b128 v[134:137], v2
	ds_read_b128 v[138:141], v2 offset:1024
	ds_read_b128 v[142:145], v2 offset:2048
	ds_read_b128 v[146:149], v2 offset:3072
	v_add_u32_e32 v2, s53, v235
	ds_read_b128 v[150:153], v2
	ds_read_b128 v[154:157], v2 offset:1024
	ds_read_b128 v[158:161], v2 offset:2048
	ds_read_b128 v[162:165], v2 offset:3072
	s_add_u32 s8, s8, s2
	s_addc_u32 s9, s9, s3
	s_mov_b32 m0, s21
	v_lshl_add_u64 v[8:9], s[8:9], 0, v[198:199]
	ds_read_b128 v[166:169], v237 offset:32768
	ds_read_b128 v[170:173], v237 offset:33792
	ds_read_b128 v[174:177], v237 offset:34816
	ds_read_b128 v[178:181], v237 offset:35840
	ds_read_b128 v[182:185], v237 offset:36864
	ds_read_b128 v[186:189], v237 offset:37888
	ds_read_b128 v[190:193], v237 offset:38912
	ds_read_b128 v[214:217], v237 offset:39936
	global_load_lds_dwordx4 v[8:9], off
	v_lshl_add_u64 v[8:9], s[8:9], 0, v[202:203]
	s_mov_b32 m0, s22
	s_nop 0
	global_load_lds_dwordx4 v[8:9], off
	s_waitcnt vmcnt(8) lgkmcnt(0)
	s_barrier
	s_setprio 1
	v_mfma_f32_16x16x32_bf16 v[126:129], v[134:137], v[166:169], v[126:129]
	v_mfma_f32_16x16x32_bf16 v[130:133], v[142:145], v[166:169], v[130:133]
	v_mfma_f32_16x16x32_bf16 v[114:117], v[134:137], v[174:177], v[114:117]
	v_mfma_f32_16x16x32_bf16 v[110:113], v[142:145], v[174:177], v[110:113]
	v_mfma_f32_16x16x32_bf16 v[98:101], v[134:137], v[182:185], v[98:101]
	v_mfma_f32_16x16x32_bf16 v[94:97], v[142:145], v[182:185], v[94:97]
	v_mfma_f32_16x16x32_bf16 v[82:85], v[134:137], v[190:193], v[82:85]
	v_mfma_f32_16x16x32_bf16 v[78:81], v[142:145], v[190:193], v[78:81]
	v_mfma_f32_16x16x32_bf16 v[126:129], v[138:141], v[170:173], v[126:129]
	v_mfma_f32_16x16x32_bf16 v[130:133], v[146:149], v[170:173], v[130:133]
	v_mfma_f32_16x16x32_bf16 v[114:117], v[138:141], v[178:181], v[114:117]
	v_mfma_f32_16x16x32_bf16 v[110:113], v[146:149], v[178:181], v[110:113]
	v_mfma_f32_16x16x32_bf16 v[98:101], v[138:141], v[186:189], v[98:101]
	v_mfma_f32_16x16x32_bf16 v[94:97], v[146:149], v[186:189], v[94:97]
	v_mfma_f32_16x16x32_bf16 v[82:85], v[138:141], v[214:217], v[82:85]
	v_mfma_f32_16x16x32_bf16 v[78:81], v[146:149], v[214:217], v[78:81]
	s_setprio 0
	s_setprio 1
	v_mfma_f32_16x16x32_bf16 v[122:125], v[150:153], v[166:169], v[122:125]
	v_mfma_f32_16x16x32_bf16 v[118:121], v[158:161], v[166:169], v[118:121]
	v_mfma_f32_16x16x32_bf16 v[106:109], v[150:153], v[174:177], v[106:109]
	v_mfma_f32_16x16x32_bf16 v[102:105], v[158:161], v[174:177], v[102:105]
	v_mfma_f32_16x16x32_bf16 v[90:93], v[150:153], v[182:185], v[90:93]
	v_mfma_f32_16x16x32_bf16 v[86:89], v[158:161], v[182:185], v[86:89]
	v_mfma_f32_16x16x32_bf16 v[74:77], v[150:153], v[190:193], v[74:77]
	v_mfma_f32_16x16x32_bf16 v[70:73], v[158:161], v[190:193], v[70:73]
	v_mfma_f32_16x16x32_bf16 v[122:125], v[154:157], v[170:173], v[122:125]
	v_mfma_f32_16x16x32_bf16 v[118:121], v[162:165], v[170:173], v[118:121]
	v_mfma_f32_16x16x32_bf16 v[106:109], v[154:157], v[178:181], v[106:109]
	v_mfma_f32_16x16x32_bf16 v[102:105], v[162:165], v[178:181], v[102:105]
	v_mfma_f32_16x16x32_bf16 v[90:93], v[154:157], v[186:189], v[90:93]
	v_mfma_f32_16x16x32_bf16 v[86:89], v[162:165], v[186:189], v[86:89]
	v_mfma_f32_16x16x32_bf16 v[74:77], v[154:157], v[214:217], v[74:77]
	v_mfma_f32_16x16x32_bf16 v[70:73], v[162:165], v[214:217], v[70:73]
	s_setprio 0
	s_barrier
	s_add_i32 s8, s52, s16
	v_lshl_add_u64 v[8:9], v[218:219], 0, s[10:11]
	s_mov_b32 m0, s8
	ds_read_b128 v[166:169], v237 offset:49152
	ds_read_b128 v[170:173], v237 offset:50176
	ds_read_b128 v[174:177], v237 offset:51200
	ds_read_b128 v[178:181], v237 offset:52224
	ds_read_b128 v[182:185], v237 offset:53248
	ds_read_b128 v[186:189], v237 offset:54272
	ds_read_b128 v[190:193], v237 offset:55296
	ds_read_b128 v[214:217], v237 offset:56320
	global_load_lds_dwordx4 v[8:9], off
	v_lshl_add_u64 v[8:9], v[220:221], 0, s[10:11]
	s_add_i32 m0, s8, 0x2000
	s_add_i32 s8, s53, s16
	global_load_lds_dwordx4 v[8:9], off
	v_lshl_add_u64 v[8:9], v[222:223], 0, s[10:11]
	s_mov_b32 m0, s8
	s_nop 0
	global_load_lds_dwordx4 v[8:9], off
	v_lshl_add_u64 v[8:9], v[224:225], 0, s[10:11]
	s_add_i32 m0, s8, 0x2000
	s_nop 0
	global_load_lds_dwordx4 v[8:9], off
	v_lshl_add_u64 v[8:9], v[238:239], 0, s[10:11]
	s_mov_b32 m0, s26
	s_nop 0
	global_load_lds_dwordx4 v[8:9], off
	v_lshl_add_u64 v[8:9], v[240:241], 0, s[10:11]
	s_mov_b32 m0, s27
	s_nop 0
	global_load_lds_dwordx4 v[8:9], off
	s_waitcnt vmcnt(8) lgkmcnt(0)
	s_barrier
	s_setprio 1
	v_mfma_f32_16x16x32_bf16 v[66:69], v[134:137], v[166:169], v[66:69]
	v_mfma_f32_16x16x32_bf16 v[62:65], v[142:145], v[166:169], v[62:65]
	v_mfma_f32_16x16x32_bf16 v[50:53], v[134:137], v[174:177], v[50:53]
	v_mfma_f32_16x16x32_bf16 v[46:49], v[142:145], v[174:177], v[46:49]
	v_mfma_f32_16x16x32_bf16 v[34:37], v[134:137], v[182:185], v[34:37]
	v_mfma_f32_16x16x32_bf16 v[30:33], v[142:145], v[182:185], v[30:33]
	v_mfma_f32_16x16x32_bf16 v[18:21], v[134:137], v[190:193], v[18:21]
	v_mfma_f32_16x16x32_bf16 v[14:17], v[142:145], v[190:193], v[14:17]
	v_mfma_f32_16x16x32_bf16 v[66:69], v[138:141], v[170:173], v[66:69]
	v_mfma_f32_16x16x32_bf16 v[62:65], v[146:149], v[170:173], v[62:65]
	v_mfma_f32_16x16x32_bf16 v[50:53], v[138:141], v[178:181], v[50:53]
	v_mfma_f32_16x16x32_bf16 v[46:49], v[146:149], v[178:181], v[46:49]
	v_mfma_f32_16x16x32_bf16 v[34:37], v[138:141], v[186:189], v[34:37]
	v_mfma_f32_16x16x32_bf16 v[30:33], v[146:149], v[186:189], v[30:33]
	v_mfma_f32_16x16x32_bf16 v[18:21], v[138:141], v[214:217], v[18:21]
	v_mfma_f32_16x16x32_bf16 v[14:17], v[146:149], v[214:217], v[14:17]
	s_setprio 0
	s_setprio 1
	v_mfma_f32_16x16x32_bf16 v[58:61], v[150:153], v[166:169], v[58:61]
	v_mfma_f32_16x16x32_bf16 v[54:57], v[158:161], v[166:169], v[54:57]
	v_mfma_f32_16x16x32_bf16 v[42:45], v[150:153], v[174:177], v[42:45]
	v_mfma_f32_16x16x32_bf16 v[38:41], v[158:161], v[174:177], v[38:41]
	v_mfma_f32_16x16x32_bf16 v[26:29], v[150:153], v[182:185], v[26:29]
	v_mfma_f32_16x16x32_bf16 v[22:25], v[158:161], v[182:185], v[22:25]
	v_mfma_f32_16x16x32_bf16 v[8:11], v[150:153], v[190:193], v[10:13]
	v_mfma_f32_16x16x32_bf16 v[4:7], v[158:161], v[190:193], v[4:7]
	v_mfma_f32_16x16x32_bf16 v[58:61], v[154:157], v[170:173], v[58:61]
	v_mfma_f32_16x16x32_bf16 v[54:57], v[162:165], v[170:173], v[54:57]
	v_mfma_f32_16x16x32_bf16 v[42:45], v[154:157], v[178:181], v[42:45]
	v_mfma_f32_16x16x32_bf16 v[38:41], v[162:165], v[178:181], v[38:41]
	v_mfma_f32_16x16x32_bf16 v[26:29], v[154:157], v[186:189], v[26:29]
	v_mfma_f32_16x16x32_bf16 v[22:25], v[162:165], v[186:189], v[22:25]
	v_mfma_f32_16x16x32_bf16 v[10:13], v[154:157], v[214:217], v[8:11]
	v_mfma_f32_16x16x32_bf16 v[6:9], v[162:165], v[214:217], v[4:7]
	s_setprio 0
	s_barrier
	s_add_u32 s6, s6, 0x100
	s_addc_u32 s7, s7, 0
	s_cmp_ge_i32 s51, s23
	s_cbranch_scc0 .LBB0_266
	v_readlane_b32 s54, v254, 25
	v_readlane_b32 s52, v254, 27
	v_readlane_b32 s55, v254, 26
	v_readlane_b32 s53, v254, 28
	v_readlane_b32 s47, v255, 0
	s_mov_b32 s50, s94

; #define PG8_STAGE(bufoff, gbase, voff) do { _Pragma("unroll") for (int _i = 0; _i < 2; ++_i) \
;         __builtin_amdgcn_global_load_lds((const unsigned*)((const char*)(gbase) + (voff)[_i]), (PG8_LAS unsigned*)(lds + (bufoff) + ldsw + _i * 8192), 16, 0, 0); } while (0)
; #define PG8_LDA(dst, b, h) do { _Pragma("unroll") for (int m = 0; m < 4; ++m) _Pragma("unroll") for (int k = 0; k < 2; ++k) dst[m][k] = *(const PG8_LAS bf16x8*)(lds + PG8_SA(b, h) + aoff + m * 2048 + k * 1024); } while (0)
; #define PG8_LDB(dst, b, h) do { _Pragma("unroll") for (int n = 0; n < 2; ++n) _Pragma("unroll") for (int k = 0; k < 2; ++k) dst[n][k] = *(const PG8_LAS bf16x8*)(lds + PG8_SB(b, h) + boff + n * 2048 + k * 1024); } while (0)
; #define PG8_MMA(ai, bj, At, Bt) do { __builtin_amdgcn_s_setprio(1); _Pragma("unroll") for (int m = 0; m < 4; ++m) _Pragma("unroll") for (int n = 0; n < 2; ++n) _Pragma("unroll") for (int k = 0; k < 2; ++k) \
;         acc[ai][bj][m][n] = __builtin_amdgcn_mfma_f32_16x16x32_bf16(Bt[n][k], At[m][k], acc[ai][bj][m][n], 0, 0, 0); __builtin_amdgcn_s_setprio(0); } while (0)
; #define PG8_WAIT_V(n) asm volatile("s_waitcnt vmcnt(" #n ")" ::: "memory")
; #define PG8_WAIT_L(n) asm volatile("s_waitcnt lgkmcnt(" #n ")" ::: "memory")
; #define PG8_BAR __builtin_amdgcn_s_barrier()
; template <class Epi, class Sched, bool ALIGN_EPI = false, bool SP2 = false, bool ACHUNK = false>
; __device__ __forceinline__ void gemm_phase(PG8_LAS unsigned char* lds, const Gemm g, const Sched& S, const Epi& E) {
;     ...
;             const char* a1 = cA + (size_t)(t + 1) * kstep;
;             const char* a2 = last ? nA : cA + (size_t)(t + 2) * kstep; const char* b2 = last ? nB : cB + (size_t)(t + 2) * kstep;
;             const char* a3 = a2 + kstep; const char* b3 = b2 + kstep;
;             if (last && has_next) S.a_ready(nxt);
;             if constexpr (SP2) {
;             PG8_LDB(B0, 0, 0); PG8_LDB(B1, 0, 1); PG8_SCHED; PG8_LDA(At, 0, 0); PG8_STAGE(PG8_SA(1, 1), a1 + hstepA, voffA);
;             PG8_WAIT_V(8); PG8_WAIT_L(0); PG8_BAR; PG8_MMA(0, 0, At, B0); PG8_MMA(0, 1, At, B1); PG8_BAR; PG8_SCHED;
;             PG8_LDA(At, 0, 1); PG8_STAGE(PG8_SB(0, 0), b2, voffB); PG8_STAGE(PG8_SB(0, 1), b2 + hstepB, voffB); PG8_STAGE(PG8_SA(0, 0), a2, voffA);
;             PG8_WAIT_V(8); PG8_WAIT_L(0); PG8_BAR; PG8_MMA(1, 0, At, B0); PG8_MMA(1, 1, At, B1); PG8_BAR; PG8_SCHED;
.LBB0_353:
	s_add_i32 s42, s20, 2
	s_add_u32 s43, s18, 0x80
	s_addc_u32 s21, s19, 0
	s_add_i32 s46, 0, 0x10000
	s_cmp_eq_u32 s33, s20
	s_cselect_b32 s21, s13, s21
	s_cselect_b32 s20, s12, s43
	v_add_u32_e32 v153, s46, v143
	s_cselect_b32 s45, s17, s41
	s_cselect_b32 s44, s16, s40
	s_add_i32 s43, 0, 0x14000
	ds_read_b128 v[154:157], v153
	ds_read_b128 v[158:161], v153 offset:1024
	ds_read_b128 v[162:165], v153 offset:2048
	ds_read_b128 v[166:169], v153 offset:3072
	v_add_u32_e32 v153, s43, v143
	ds_read_b128 v[170:173], v153
	ds_read_b128 v[174:177], v153 offset:1024
	ds_read_b128 v[178:181], v153 offset:2048
	ds_read_b128 v[182:185], v153 offset:3072
	v_lshl_add_u64 v[222:223], s[18:19], 0, v[138:139]
	s_add_i32 m0, s25, 0xc000
	ds_read_b128 v[186:189], v152
	ds_read_b128 v[190:193], v152 offset:1024
	ds_read_b128 v[198:201], v152 offset:2048
	ds_read_b128 v[202:205], v152 offset:3072
	ds_read_b128 v[206:209], v152 offset:4096
	ds_read_b128 v[210:213], v152 offset:5120
	ds_read_b128 v[214:217], v152 offset:6144
	ds_read_b128 v[218:221], v152 offset:7168
	global_load_lds_dwordx4 v[222:223], off
	v_lshl_add_u64 v[222:223], s[18:19], 0, v[140:141]
	s_add_i32 m0, s25, 0xe000
	s_nop 0
	global_load_lds_dwordx4 v[222:223], off
	s_waitcnt vmcnt(8) lgkmcnt(0)
	s_barrier
	s_setprio 1
	v_mfma_f32_16x16x32_bf16 v[124:127], v[154:157], v[186:189], v[124:127]
	v_mfma_f32_16x16x32_bf16 v[128:131], v[162:165], v[186:189], v[128:131]
	v_mfma_f32_16x16x32_bf16 v[112:115], v[154:157], v[198:201], v[112:115]
	v_mfma_f32_16x16x32_bf16 v[108:111], v[162:165], v[198:201], v[108:111]
	v_mfma_f32_16x16x32_bf16 v[96:99], v[154:157], v[206:209], v[96:99]
	v_mfma_f32_16x16x32_bf16 v[92:95], v[162:165], v[206:209], v[92:95]
	v_mfma_f32_16x16x32_bf16 v[80:83], v[154:157], v[214:217], v[80:83]
	v_mfma_f32_16x16x32_bf16 v[76:79], v[162:165], v[214:217], v[76:79]
	v_mfma_f32_16x16x32_bf16 v[124:127], v[158:161], v[190:193], v[124:127]
	v_mfma_f32_16x16x32_bf16 v[128:131], v[166:169], v[190:193], v[128:131]
	v_mfma_f32_16x16x32_bf16 v[112:115], v[158:161], v[202:205], v[112:115]
	v_mfma_f32_16x16x32_bf16 v[108:111], v[166:169], v[202:205], v[108:111]
	v_mfma_f32_16x16x32_bf16 v[96:99], v[158:161], v[210:213], v[96:99]
	v_mfma_f32_16x16x32_bf16 v[92:95], v[166:169], v[210:213], v[92:95]
	v_mfma_f32_16x16x32_bf16 v[80:83], v[158:161], v[218:221], v[80:83]
	v_mfma_f32_16x16x32_bf16 v[76:79], v[166:169], v[218:221], v[76:79]
	s_setprio 0
	s_setprio 1
	v_mfma_f32_16x16x32_bf16 v[120:123], v[170:173], v[186:189], v[120:123]
	v_mfma_f32_16x16x32_bf16 v[116:119], v[178:181], v[186:189], v[116:119]
	v_mfma_f32_16x16x32_bf16 v[104:107], v[170:173], v[198:201], v[104:107]
	v_mfma_f32_16x16x32_bf16 v[100:103], v[178:181], v[198:201], v[100:103]
	v_mfma_f32_16x16x32_bf16 v[88:91], v[170:173], v[206:209], v[88:91]
	v_mfma_f32_16x16x32_bf16 v[84:87], v[178:181], v[206:209], v[84:87]
	v_mfma_f32_16x16x32_bf16 v[72:75], v[170:173], v[214:217], v[72:75]
	v_mfma_f32_16x16x32_bf16 v[68:71], v[178:181], v[214:217], v[68:71]
	v_mfma_f32_16x16x32_bf16 v[120:123], v[174:177], v[190:193], v[120:123]
	v_mfma_f32_16x16x32_bf16 v[116:119], v[182:185], v[190:193], v[116:119]
	v_mfma_f32_16x16x32_bf16 v[104:107], v[174:177], v[202:205], v[104:107]
	v_mfma_f32_16x16x32_bf16 v[100:103], v[182:185], v[202:205], v[100:103]
	v_mfma_f32_16x16x32_bf16 v[88:91], v[174:177], v[210:213], v[88:91]
	v_mfma_f32_16x16x32_bf16 v[84:87], v[182:185], v[210:213], v[84:87]
	v_mfma_f32_16x16x32_bf16 v[72:75], v[174:177], v[218:221], v[72:75]
	v_mfma_f32_16x16x32_bf16 v[68:71], v[182:185], v[218:221], v[68:71]
	s_setprio 0
	s_barrier
	s_add_i32 s46, s46, s24
	v_lshl_add_u64 v[222:223], s[44:45], 0, v[2:3]
	s_mov_b32 m0, s46
	ds_read_b128 v[186:189], v152 offset:16384
	ds_read_b128 v[190:193], v152 offset:17408
	ds_read_b128 v[198:201], v152 offset:18432
	ds_read_b128 v[202:205], v152 offset:19456
	ds_read_b128 v[206:209], v152 offset:20480
	ds_read_b128 v[210:213], v152 offset:21504
	ds_read_b128 v[214:217], v152 offset:22528
	ds_read_b128 v[218:221], v152 offset:23552
	global_load_lds_dwordx4 v[222:223], off
	s_add_i32 m0, s46, 0x2000
	v_lshl_add_u64 v[224:225], s[44:45], 0, v[136:137]
	s_add_u32 s44, s44, s0
	s_addc_u32 s45, s45, s1
	s_add_i32 s43, s43, s24
	global_load_lds_dwordx4 v[224:225], off
	v_lshl_add_u64 v[232:233], s[44:45], 0, v[2:3]
	s_mov_b32 m0, s43
	v_lshl_add_u64 v[234:235], s[44:45], 0, v[136:137]
	global_load_lds_dwordx4 v[232:233], off
	s_add_i32 m0, s43, 0x2000
	v_lshl_add_u64 v[236:237], s[20:21], 0, v[132:133]
	global_load_lds_dwordx4 v[234:235], off
	s_mov_b32 m0, s25
	v_lshl_add_u64 v[238:239], s[20:21], 0, v[134:135]
	global_load_lds_dwordx4 v[236:237], off
	s_mov_b32 m0, s26
	s_nop 0
	global_load_lds_dwordx4 v[238:239], off
	s_waitcnt vmcnt(8) lgkmcnt(0)
	s_barrier
; #define PG8_STAGE(bufoff, gbase, voff) do { _Pragma("unroll") for (int _i = 0; _i < 2; ++_i) \
;         __builtin_amdgcn_global_load_lds((const unsigned*)((const char*)(gbase) + (voff)[_i]), (PG8_LAS unsigned*)(lds + (bufoff) + ldsw + _i * 8192), 16, 0, 0); } while (0)
; #define PG8_LDA(dst, b, h) do { _Pragma("unroll") for (int m = 0; m < 4; ++m) _Pragma("unroll") for (int k = 0; k < 2; ++k) dst[m][k] = *(const PG8_LAS bf16x8*)(lds + PG8_SA(b, h) + aoff + m * 2048 + k * 1024); } while (0)
; #define PG8_LDB(dst, b, h) do { _Pragma("unroll") for (int n = 0; n < 2; ++n) _Pragma("unroll") for (int k = 0; k < 2; ++k) dst[n][k] = *(const PG8_LAS bf16x8*)(lds + PG8_SB(b, h) + boff + n * 2048 + k * 1024); } while (0)
; #define PG8_MMA(ai, bj, At, Bt) do { __builtin_amdgcn_s_setprio(1); _Pragma("unroll") for (int m = 0; m < 4; ++m) _Pragma("unroll") for (int n = 0; n < 2; ++n) _Pragma("unroll") for (int k = 0; k < 2; ++k) \
;         acc[ai][bj][m][n] = __builtin_amdgcn_mfma_f32_16x16x32_bf16(Bt[n][k], At[m][k], acc[ai][bj][m][n], 0, 0, 0); __builtin_amdgcn_s_setprio(0); } while (0)
; #define PG8_WAIT_V(n) asm volatile("s_waitcnt vmcnt(" #n ")" ::: "memory")
; #define PG8_WAIT_L(n) asm volatile("s_waitcnt lgkmcnt(" #n ")" ::: "memory")
; #define PG8_BAR __builtin_amdgcn_s_barrier()
; #define PG8_SCHED __builtin_amdgcn_sched_barrier(0)
; template <class Epi, class Sched, bool ALIGN_EPI = false, bool SP2 = false, bool ACHUNK = false>
; __device__ __forceinline__ void gemm_phase(PG8_LAS unsigned char* lds, const Gemm g, const Sched& S, const Epi& E) {
;     ...
;             PG8_WAIT_V(8); PG8_WAIT_L(0); PG8_BAR; PG8_MMA(1, 0, At, B0); PG8_MMA(1, 1, At, B1); PG8_BAR; PG8_SCHED;
;             PG8_LDB(B0, 1, 0); PG8_LDB(B1, 1, 1); PG8_SCHED; PG8_LDA(At, 1, 0); PG8_STAGE(PG8_SA(0, 1), a2 + hstepA, voffA);
;             PG8_WAIT_V(8); PG8_WAIT_L(0); PG8_BAR; PG8_MMA(0, 0, At, B0); PG8_MMA(0, 1, At, B1); PG8_BAR; PG8_SCHED;
	s_setprio 1
	v_mfma_f32_16x16x32_bf16 v[64:67], v[154:157], v[186:189], v[64:67]
	v_mfma_f32_16x16x32_bf16 v[60:63], v[162:165], v[186:189], v[60:63]
	v_mfma_f32_16x16x32_bf16 v[48:51], v[154:157], v[198:201], v[48:51]
	v_mfma_f32_16x16x32_bf16 v[44:47], v[162:165], v[198:201], v[44:47]
	v_mfma_f32_16x16x32_bf16 v[32:35], v[154:157], v[206:209], v[32:35]
	v_mfma_f32_16x16x32_bf16 v[28:31], v[162:165], v[206:209], v[28:31]
	v_mfma_f32_16x16x32_bf16 v[16:19], v[154:157], v[214:217], v[16:19]
	v_mfma_f32_16x16x32_bf16 v[12:15], v[162:165], v[214:217], v[12:15]
	v_mfma_f32_16x16x32_bf16 v[64:67], v[158:161], v[190:193], v[64:67]
	v_mfma_f32_16x16x32_bf16 v[60:63], v[166:169], v[190:193], v[60:63]
	v_mfma_f32_16x16x32_bf16 v[48:51], v[158:161], v[202:205], v[48:51]
	v_mfma_f32_16x16x32_bf16 v[44:47], v[166:169], v[202:205], v[44:47]
	v_mfma_f32_16x16x32_bf16 v[32:35], v[158:161], v[210:213], v[32:35]
	v_mfma_f32_16x16x32_bf16 v[28:31], v[166:169], v[210:213], v[28:31]
	v_mfma_f32_16x16x32_bf16 v[16:19], v[158:161], v[218:221], v[16:19]
	v_mfma_f32_16x16x32_bf16 v[12:15], v[166:169], v[218:221], v[12:15]
	s_setprio 0
	s_setprio 1
	v_mfma_f32_16x16x32_bf16 v[56:59], v[170:173], v[186:189], v[56:59]
	v_mfma_f32_16x16x32_bf16 v[52:55], v[178:181], v[186:189], v[52:55]
	v_mfma_f32_16x16x32_bf16 v[40:43], v[170:173], v[198:201], v[40:43]
	v_mfma_f32_16x16x32_bf16 v[36:39], v[178:181], v[198:201], v[36:39]
	v_mfma_f32_16x16x32_bf16 v[24:27], v[170:173], v[206:209], v[24:27]
	v_mfma_f32_16x16x32_bf16 v[20:23], v[178:181], v[206:209], v[20:23]
	v_mfma_f32_16x16x32_bf16 v[8:11], v[170:173], v[214:217], v[8:11]
	v_mfma_f32_16x16x32_bf16 v[4:7], v[178:181], v[214:217], v[4:7]
	v_mfma_f32_16x16x32_bf16 v[56:59], v[174:177], v[190:193], v[56:59]
	v_mfma_f32_16x16x32_bf16 v[52:55], v[182:185], v[190:193], v[52:55]
	v_mfma_f32_16x16x32_bf16 v[40:43], v[174:177], v[202:205], v[40:43]
	v_mfma_f32_16x16x32_bf16 v[36:39], v[182:185], v[202:205], v[36:39]
	v_mfma_f32_16x16x32_bf16 v[24:27], v[174:177], v[210:213], v[24:27]
	v_mfma_f32_16x16x32_bf16 v[20:23], v[182:185], v[210:213], v[20:23]
	v_mfma_f32_16x16x32_bf16 v[8:11], v[174:177], v[218:221], v[8:11]
	v_mfma_f32_16x16x32_bf16 v[4:7], v[182:185], v[218:221], v[4:7]
	s_setprio 0
	s_barrier
	s_add_i32 s43, 0, 0x18000
	v_add_u32_e32 v153, s43, v143
	s_add_i32 s44, 0, 0x1c000
	ds_read_b128 v[154:157], v153
	ds_read_b128 v[158:161], v153 offset:1024
	ds_read_b128 v[162:165], v153 offset:2048
	ds_read_b128 v[166:169], v153 offset:3072
	v_add_u32_e32 v153, s44, v143
	ds_read_b128 v[170:173], v153
	ds_read_b128 v[174:177], v153 offset:1024
	ds_read_b128 v[178:181], v153 offset:2048
	ds_read_b128 v[182:185], v153 offset:3072
	s_add_u32 s20, s20, s0
	s_addc_u32 s21, s21, s1
	s_mov_b32 m0, s27
	v_lshl_add_u64 v[240:241], s[20:21], 0, v[132:133]
	ds_read_b128 v[186:189], v152 offset:32768
	ds_read_b128 v[190:193], v152 offset:33792
	ds_read_b128 v[198:201], v152 offset:34816
	ds_read_b128 v[202:205], v152 offset:35840
	ds_read_b128 v[206:209], v152 offset:36864
	ds_read_b128 v[210:213], v152 offset:37888
	ds_read_b128 v[214:217], v152 offset:38912
	ds_read_b128 v[218:221], v152 offset:39936
	global_load_lds_dwordx4 v[240:241], off
	v_lshl_add_u64 v[240:241], s[20:21], 0, v[134:135]
	s_mov_b32 m0, s28
	s_nop 0
	global_load_lds_dwordx4 v[240:241], off
	s_waitcnt vmcnt(8) lgkmcnt(0)
	s_barrier
	s_setprio 1
	v_mfma_f32_16x16x32_bf16 v[124:127], v[154:157], v[186:189], v[124:127]
	v_mfma_f32_16x16x32_bf16 v[128:131], v[162:165], v[186:189], v[128:131]
	v_mfma_f32_16x16x32_bf16 v[112:115], v[154:157], v[198:201], v[112:115]
	v_mfma_f32_16x16x32_bf16 v[108:111], v[162:165], v[198:201], v[108:111]
	v_mfma_f32_16x16x32_bf16 v[96:99], v[154:157], v[206:209], v[96:99]
	v_mfma_f32_16x16x32_bf16 v[92:95], v[162:165], v[206:209], v[92:95]
	v_mfma_f32_16x16x32_bf16 v[80:83], v[154:157], v[214:217], v[80:83]
	v_mfma_f32_16x16x32_bf16 v[76:79], v[162:165], v[214:217], v[76:79]
	v_mfma_f32_16x16x32_bf16 v[124:127], v[158:161], v[190:193], v[124:127]
	v_mfma_f32_16x16x32_bf16 v[128:131], v[166:169], v[190:193], v[128:131]
	v_mfma_f32_16x16x32_bf16 v[112:115], v[158:161], v[202:205], v[112:115]
	v_mfma_f32_16x16x32_bf16 v[108:111], v[166:169], v[202:205], v[108:111]
	v_mfma_f32_16x16x32_bf16 v[96:99], v[158:161], v[210:213], v[96:99]
	v_mfma_f32_16x16x32_bf16 v[92:95], v[166:169], v[210:213], v[92:95]
	v_mfma_f32_16x16x32_bf16 v[80:83], v[158:161], v[218:221], v[80:83]
	v_mfma_f32_16x16x32_bf16 v[76:79], v[166:169], v[218:221], v[76:79]
	s_setprio 0
	s_setprio 1
	v_mfma_f32_16x16x32_bf16 v[120:123], v[170:173], v[186:189], v[120:123]
	v_mfma_f32_16x16x32_bf16 v[116:119], v[178:181], v[186:189], v[116:119]
	v_mfma_f32_16x16x32_bf16 v[104:107], v[170:173], v[198:201], v[104:107]
	v_mfma_f32_16x16x32_bf16 v[100:103], v[178:181], v[198:201], v[100:103]
	v_mfma_f32_16x16x32_bf16 v[88:91], v[170:173], v[206:209], v[88:91]
	v_mfma_f32_16x16x32_bf16 v[84:87], v[178:181], v[206:209], v[84:87]
	v_mfma_f32_16x16x32_bf16 v[72:75], v[170:173], v[214:217], v[72:75]
	v_mfma_f32_16x16x32_bf16 v[68:71], v[178:181], v[214:217], v[68:71]
	v_mfma_f32_16x16x32_bf16 v[120:123], v[174:177], v[190:193], v[120:123]
	v_mfma_f32_16x16x32_bf16 v[116:119], v[182:185], v[190:193], v[116:119]
	v_mfma_f32_16x16x32_bf16 v[104:107], v[174:177], v[202:205], v[104:107]
	v_mfma_f32_16x16x32_bf16 v[100:103], v[182:185], v[202:205], v[100:103]
	v_mfma_f32_16x16x32_bf16 v[88:91], v[174:177], v[210:213], v[88:91]
	v_mfma_f32_16x16x32_bf16 v[84:87], v[182:185], v[210:213], v[84:87]
	v_mfma_f32_16x16x32_bf16 v[72:75], v[174:177], v[218:221], v[72:75]
	v_mfma_f32_16x16x32_bf16 v[68:71], v[182:185], v[218:221], v[68:71]
	s_setprio 0
	s_barrier
; #define PG8_STAGE(bufoff, gbase, voff) do { _Pragma("unroll") for (int _i = 0; _i < 2; ++_i) \
;         __builtin_amdgcn_global_load_lds((const unsigned*)((const char*)(gbase) + (voff)[_i]), (PG8_LAS unsigned*)(lds + (bufoff) + ldsw + _i * 8192), 16, 0, 0); } while (0)
; #define PG8_LDA(dst, b, h) do { _Pragma("unroll") for (int m = 0; m < 4; ++m) _Pragma("unroll") for (int k = 0; k < 2; ++k) dst[m][k] = *(const PG8_LAS bf16x8*)(lds + PG8_SA(b, h) + aoff + m * 2048 + k * 1024); } while (0)
; #define PG8_MMA(ai, bj, At, Bt) do { __builtin_amdgcn_s_setprio(1); _Pragma("unroll") for (int m = 0; m < 4; ++m) _Pragma("unroll") for (int n = 0; n < 2; ++n) _Pragma("unroll") for (int k = 0; k < 2; ++k) \
;         acc[ai][bj][m][n] = __builtin_amdgcn_mfma_f32_16x16x32_bf16(Bt[n][k], At[m][k], acc[ai][bj][m][n], 0, 0, 0); __builtin_amdgcn_s_setprio(0); } while (0)
; #define PG8_WAIT_V(n) asm volatile("s_waitcnt vmcnt(" #n ")" ::: "memory")
; #define PG8_WAIT_L(n) asm volatile("s_waitcnt lgkmcnt(" #n ")" ::: "memory")
; #define PG8_BAR __builtin_amdgcn_s_barrier()
; #define PG8_SCHED __builtin_amdgcn_sched_barrier(0)
; template <class Epi, class Sched, bool ALIGN_EPI = false, bool SP2 = false, bool ACHUNK = false>
; __device__ __forceinline__ void gemm_phase(PG8_LAS unsigned char* lds, const Gemm g, const Sched& S, const Epi& E) {
;     ...
;             PG8_LDA(At, 1, 1); PG8_STAGE(PG8_SB(1, 0), b3, voffB); PG8_STAGE(PG8_SB(1, 1), b3 + hstepB, voffB); PG8_STAGE(PG8_SA(1, 0), a3, voffA);
;             PG8_WAIT_V(8); PG8_WAIT_L(0); PG8_BAR; PG8_MMA(1, 0, At, B0); PG8_MMA(1, 1, At, B1); PG8_BAR; PG8_SCHED;
	s_add_i32 s20, s43, s24
	v_lshl_add_u64 v[222:223], v[222:223], 0, s[10:11]
	s_mov_b32 m0, s20
	ds_read_b128 v[186:189], v152 offset:49152
	ds_read_b128 v[190:193], v152 offset:50176
	ds_read_b128 v[198:201], v152 offset:51200
	ds_read_b128 v[202:205], v152 offset:52224
	ds_read_b128 v[206:209], v152 offset:53248
	ds_read_b128 v[210:213], v152 offset:54272
	ds_read_b128 v[214:217], v152 offset:55296
	ds_read_b128 v[218:221], v152 offset:56320
	global_load_lds_dwordx4 v[222:223], off
	v_lshl_add_u64 v[222:223], v[224:225], 0, s[10:11]
	s_add_i32 m0, s20, 0x2000
	s_add_i32 s20, s44, s24
	global_load_lds_dwordx4 v[222:223], off
	v_lshl_add_u64 v[222:223], v[232:233], 0, s[10:11]
	s_mov_b32 m0, s20
	s_nop 0
	global_load_lds_dwordx4 v[222:223], off
	v_lshl_add_u64 v[222:223], v[234:235], 0, s[10:11]
	s_add_i32 m0, s20, 0x2000
	s_nop 0
	global_load_lds_dwordx4 v[222:223], off
	v_lshl_add_u64 v[222:223], v[236:237], 0, s[10:11]
	s_mov_b32 m0, s29
	s_nop 0
	global_load_lds_dwordx4 v[222:223], off
	v_lshl_add_u64 v[222:223], v[238:239], 0, s[10:11]
	s_mov_b32 m0, s30
	s_nop 0
	global_load_lds_dwordx4 v[222:223], off
	s_waitcnt vmcnt(8) lgkmcnt(0)
	s_barrier
	s_setprio 1
	v_mfma_f32_16x16x32_bf16 v[64:67], v[154:157], v[186:189], v[64:67]
	v_mfma_f32_16x16x32_bf16 v[60:63], v[162:165], v[186:189], v[60:63]
	v_mfma_f32_16x16x32_bf16 v[48:51], v[154:157], v[198:201], v[48:51]
	v_mfma_f32_16x16x32_bf16 v[44:47], v[162:165], v[198:201], v[44:47]
	v_mfma_f32_16x16x32_bf16 v[32:35], v[154:157], v[206:209], v[32:35]
	v_mfma_f32_16x16x32_bf16 v[28:31], v[162:165], v[206:209], v[28:31]
	v_mfma_f32_16x16x32_bf16 v[16:19], v[154:157], v[214:217], v[16:19]
	v_mfma_f32_16x16x32_bf16 v[12:15], v[162:165], v[214:217], v[12:15]
	v_mfma_f32_16x16x32_bf16 v[64:67], v[158:161], v[190:193], v[64:67]
	v_mfma_f32_16x16x32_bf16 v[60:63], v[166:169], v[190:193], v[60:63]
	v_mfma_f32_16x16x32_bf16 v[48:51], v[158:161], v[202:205], v[48:51]
	v_mfma_f32_16x16x32_bf16 v[44:47], v[166:169], v[202:205], v[44:47]
	v_mfma_f32_16x16x32_bf16 v[32:35], v[158:161], v[210:213], v[32:35]
	v_mfma_f32_16x16x32_bf16 v[28:31], v[166:169], v[210:213], v[28:31]
	v_mfma_f32_16x16x32_bf16 v[16:19], v[158:161], v[218:221], v[16:19]
	v_mfma_f32_16x16x32_bf16 v[12:15], v[166:169], v[218:221], v[12:15]
	s_setprio 0
	s_setprio 1
	v_mfma_f32_16x16x32_bf16 v[56:59], v[170:173], v[186:189], v[56:59]
	v_mfma_f32_16x16x32_bf16 v[52:55], v[178:181], v[186:189], v[52:55]
	v_mfma_f32_16x16x32_bf16 v[40:43], v[170:173], v[198:201], v[40:43]
	v_mfma_f32_16x16x32_bf16 v[36:39], v[178:181], v[198:201], v[36:39]
	v_mfma_f32_16x16x32_bf16 v[24:27], v[170:173], v[206:209], v[24:27]
	v_mfma_f32_16x16x32_bf16 v[20:23], v[178:181], v[206:209], v[20:23]
	v_mfma_f32_16x16x32_bf16 v[8:11], v[170:173], v[214:217], v[8:11]
	v_mfma_f32_16x16x32_bf16 v[4:7], v[178:181], v[214:217], v[4:7]
	v_mfma_f32_16x16x32_bf16 v[56:59], v[174:177], v[190:193], v[56:59]
	v_mfma_f32_16x16x32_bf16 v[52:55], v[182:185], v[190:193], v[52:55]
	v_mfma_f32_16x16x32_bf16 v[40:43], v[174:177], v[202:205], v[40:43]
	v_mfma_f32_16x16x32_bf16 v[36:39], v[182:185], v[202:205], v[36:39]
	v_mfma_f32_16x16x32_bf16 v[24:27], v[174:177], v[210:213], v[24:27]
	v_mfma_f32_16x16x32_bf16 v[20:23], v[182:185], v[210:213], v[20:23]
	v_mfma_f32_16x16x32_bf16 v[8:11], v[174:177], v[218:221], v[8:11]
	v_mfma_f32_16x16x32_bf16 v[4:7], v[182:185], v[218:221], v[4:7]
	s_setprio 0
	s_barrier
	s_add_u32 s40, s40, 0x100
	s_addc_u32 s41, s41, 0
	s_add_u32 s18, s18, 0x100
	s_addc_u32 s19, s19, 0
	s_cmp_ge_i32 s42, s31
	s_mov_b32 s20, s42
	s_cbranch_scc0 .LBB0_353
	s_branch .LBB0_342

; #define PG8_STAGE(bufoff, gbase, voff) do { _Pragma("unroll") for (int _i = 0; _i < 2; ++_i) \
;         __builtin_amdgcn_global_load_lds((const unsigned*)((const char*)(gbase) + (voff)[_i]), (PG8_LAS unsigned*)(lds + (bufoff) + ldsw + _i * 8192), 16, 0, 0); } while (0)
; #define PG8_LDA(dst, b, h) do { _Pragma("unroll") for (int m = 0; m < 4; ++m) _Pragma("unroll") for (int k = 0; k < 2; ++k) dst[m][k] = *(const PG8_LAS bf16x8*)(lds + PG8_SA(b, h) + aoff + m * 2048 + k * 1024); } while (0)
; #define PG8_LDB(dst, b, h) do { _Pragma("unroll") for (int n = 0; n < 2; ++n) _Pragma("unroll") for (int k = 0; k < 2; ++k) dst[n][k] = *(const PG8_LAS bf16x8*)(lds + PG8_SB(b, h) + boff + n * 2048 + k * 1024); } while (0)
; #define PG8_MMA(ai, bj, At, Bt) do { __builtin_amdgcn_s_setprio(1); _Pragma("unroll") for (int m = 0; m < 4; ++m) _Pragma("unroll") for (int n = 0; n < 2; ++n) _Pragma("unroll") for (int k = 0; k < 2; ++k) \
;         acc[ai][bj][m][n] = __builtin_amdgcn_mfma_f32_16x16x32_bf16(Bt[n][k], At[m][k], acc[ai][bj][m][n], 0, 0, 0); __builtin_amdgcn_s_setprio(0); } while (0)
; #define PG8_WAIT_V(n) asm volatile("s_waitcnt vmcnt(" #n ")" ::: "memory")
; #define PG8_WAIT_L(n) asm volatile("s_waitcnt lgkmcnt(" #n ")" ::: "memory")
; #define PG8_BAR __builtin_amdgcn_s_barrier()
; template <class Epi, class Sched, bool ALIGN_EPI = false, bool SP2 = false, bool ACHUNK = false>
; __device__ __forceinline__ void gemm_phase(PG8_LAS unsigned char* lds, const Gemm g, const Sched& S, const Epi& E) {
;     ...
;             const char* a1 = cA + (size_t)(t + 1) * kstep;
;             const char* a2 = last ? nA : cA + (size_t)(t + 2) * kstep; const char* b2 = last ? nB : cB + (size_t)(t + 2) * kstep;
;             const char* a3 = a2 + kstep; const char* b3 = b2 + kstep;
;             if (last && has_next) S.a_ready(nxt);
;             if constexpr (SP2) {
;             PG8_LDB(B0, 0, 0); PG8_LDB(B1, 0, 1); PG8_SCHED; PG8_LDA(At, 0, 0); PG8_STAGE(PG8_SA(1, 1), a1 + hstepA, voffA);
;             PG8_WAIT_V(8); PG8_WAIT_L(0); PG8_BAR; PG8_MMA(0, 0, At, B0); PG8_MMA(0, 1, At, B1); PG8_BAR; PG8_SCHED;
;             PG8_LDA(At, 0, 1); PG8_STAGE(PG8_SB(0, 0), b2, voffB); PG8_STAGE(PG8_SB(0, 1), b2 + hstepB, voffB); PG8_STAGE(PG8_SA(0, 0), a2, voffA);
;             PG8_WAIT_V(8); PG8_WAIT_L(0); PG8_BAR; PG8_MMA(1, 0, At, B0); PG8_MMA(1, 1, At, B1); PG8_BAR; PG8_SCHED;
.LBB0_377:
	s_add_i32 s48, s6, 2
	s_add_u32 s49, s4, 0x80
	s_addc_u32 s7, s5, 0
	s_add_i32 s52, 0, 0x10000
	s_cmp_eq_u32 s27, s6
	s_cselect_b32 s7, s1, s7
	s_cselect_b32 s6, s0, s49
	v_add_u32_e32 v2, s52, v175
	s_cselect_b32 s51, s43, s9
	s_cselect_b32 s50, s42, s8
	s_add_i32 s49, 0, 0x14000
	s_waitcnt lgkmcnt(0)
	ds_read_b128 v[146:149], v2
	ds_read_b128 v[150:153], v2 offset:1024
	ds_read_b128 v[154:157], v2 offset:2048
	ds_read_b128 v[158:161], v2 offset:3072
	v_add_u32_e32 v2, s49, v175
	ds_read_b128 v[162:165], v2
	ds_read_b128 v[166:169], v2 offset:1024
	ds_read_b128 v[170:173], v2 offset:2048
	ds_read_b128 v[180:183], v2 offset:3072
	v_lshl_add_u64 v[192:193], s[4:5], 0, v[142:143]
	s_add_i32 m0, s20, 0xc000
	ds_read_b128 v[184:187], v179
	ds_read_b128 v[188:191], v179 offset:1024
	ds_read_b128 v[198:201], v179 offset:2048
	ds_read_b128 v[202:205], v179 offset:3072
	ds_read_b128 v[206:209], v179 offset:4096
	ds_read_b128 v[210:213], v179 offset:5120
	ds_read_b128 v[214:217], v179 offset:6144
	ds_read_b128 v[218:221], v179 offset:7168
	global_load_lds_dwordx4 v[192:193], off
	v_lshl_add_u64 v[192:193], s[4:5], 0, v[144:145]
	s_add_i32 m0, s20, 0xe000
	s_nop 0
	global_load_lds_dwordx4 v[192:193], off
	s_waitcnt vmcnt(8) lgkmcnt(0)
	s_barrier
	s_setprio 1
	v_mfma_f32_16x16x32_bf16 v[124:127], v[146:149], v[184:187], v[124:127]
	v_mfma_f32_16x16x32_bf16 v[116:119], v[154:157], v[184:187], v[116:119]
	v_mfma_f32_16x16x32_bf16 v[108:111], v[146:149], v[198:201], v[108:111]
	v_mfma_f32_16x16x32_bf16 v[100:103], v[154:157], v[198:201], v[100:103]
	v_mfma_f32_16x16x32_bf16 v[92:95], v[146:149], v[206:209], v[92:95]
	v_mfma_f32_16x16x32_bf16 v[84:87], v[154:157], v[206:209], v[84:87]
	v_mfma_f32_16x16x32_bf16 v[76:79], v[146:149], v[214:217], v[76:79]
	v_mfma_f32_16x16x32_bf16 v[68:71], v[154:157], v[214:217], v[68:71]
	v_mfma_f32_16x16x32_bf16 v[124:127], v[150:153], v[188:191], v[124:127]
	v_mfma_f32_16x16x32_bf16 v[116:119], v[158:161], v[188:191], v[116:119]
	v_mfma_f32_16x16x32_bf16 v[108:111], v[150:153], v[202:205], v[108:111]
	v_mfma_f32_16x16x32_bf16 v[100:103], v[158:161], v[202:205], v[100:103]
	v_mfma_f32_16x16x32_bf16 v[92:95], v[150:153], v[210:213], v[92:95]
	v_mfma_f32_16x16x32_bf16 v[84:87], v[158:161], v[210:213], v[84:87]
	v_mfma_f32_16x16x32_bf16 v[76:79], v[150:153], v[218:221], v[76:79]
	v_mfma_f32_16x16x32_bf16 v[68:71], v[158:161], v[218:221], v[68:71]
	s_setprio 0
	s_setprio 1
	v_mfma_f32_16x16x32_bf16 v[128:131], v[162:165], v[184:187], v[128:131]
	v_mfma_f32_16x16x32_bf16 v[120:123], v[170:173], v[184:187], v[120:123]
	v_mfma_f32_16x16x32_bf16 v[112:115], v[162:165], v[198:201], v[112:115]
	v_mfma_f32_16x16x32_bf16 v[104:107], v[170:173], v[198:201], v[104:107]
	v_mfma_f32_16x16x32_bf16 v[96:99], v[162:165], v[206:209], v[96:99]
	v_mfma_f32_16x16x32_bf16 v[88:91], v[170:173], v[206:209], v[88:91]
	v_mfma_f32_16x16x32_bf16 v[80:83], v[162:165], v[214:217], v[80:83]
	v_mfma_f32_16x16x32_bf16 v[72:75], v[170:173], v[214:217], v[72:75]
	v_mfma_f32_16x16x32_bf16 v[128:131], v[166:169], v[188:191], v[128:131]
	v_mfma_f32_16x16x32_bf16 v[120:123], v[180:183], v[188:191], v[120:123]
	v_mfma_f32_16x16x32_bf16 v[112:115], v[166:169], v[202:205], v[112:115]
	v_mfma_f32_16x16x32_bf16 v[104:107], v[180:183], v[202:205], v[104:107]
	v_mfma_f32_16x16x32_bf16 v[96:99], v[166:169], v[210:213], v[96:99]
	v_mfma_f32_16x16x32_bf16 v[88:91], v[180:183], v[210:213], v[88:91]
	v_mfma_f32_16x16x32_bf16 v[80:83], v[166:169], v[218:221], v[80:83]
	v_mfma_f32_16x16x32_bf16 v[72:75], v[180:183], v[218:221], v[72:75]
	s_setprio 0
	s_barrier
	s_add_i32 s52, s52, s13
	v_lshl_add_u64 v[192:193], s[50:51], 0, v[134:135]
	s_mov_b32 m0, s52
	ds_read_b128 v[184:187], v179 offset:16384
	ds_read_b128 v[188:191], v179 offset:17408
	ds_read_b128 v[198:201], v179 offset:18432
	ds_read_b128 v[202:205], v179 offset:19456
	ds_read_b128 v[206:209], v179 offset:20480
	ds_read_b128 v[210:213], v179 offset:21504
	ds_read_b128 v[214:217], v179 offset:22528
	ds_read_b128 v[218:221], v179 offset:23552
	global_load_lds_dwordx4 v[192:193], off
	s_add_i32 m0, s52, 0x2000
	v_lshl_add_u64 v[222:223], s[50:51], 0, v[138:139]
	s_add_u32 s50, s50, s18
	s_addc_u32 s51, s51, s19
	s_add_i32 s49, s49, s13
	global_load_lds_dwordx4 v[222:223], off
	v_lshl_add_u64 v[224:225], s[50:51], 0, v[134:135]
	s_mov_b32 m0, s49
	v_lshl_add_u64 v[232:233], s[50:51], 0, v[138:139]
	global_load_lds_dwordx4 v[224:225], off
	s_add_i32 m0, s49, 0x2000
	v_lshl_add_u64 v[234:235], s[6:7], 0, v[132:133]
	global_load_lds_dwordx4 v[232:233], off
	s_mov_b32 m0, s20
	v_lshl_add_u64 v[236:237], s[6:7], 0, v[136:137]
	global_load_lds_dwordx4 v[234:235], off
	s_mov_b32 m0, s21
	s_nop 0
	global_load_lds_dwordx4 v[236:237], off
	s_waitcnt vmcnt(8) lgkmcnt(0)
	s_barrier
; #define PG8_STAGE(bufoff, gbase, voff) do { _Pragma("unroll") for (int _i = 0; _i < 2; ++_i) \
;         __builtin_amdgcn_global_load_lds((const unsigned*)((const char*)(gbase) + (voff)[_i]), (PG8_LAS unsigned*)(lds + (bufoff) + ldsw + _i * 8192), 16, 0, 0); } while (0)
; #define PG8_LDA(dst, b, h) do { _Pragma("unroll") for (int m = 0; m < 4; ++m) _Pragma("unroll") for (int k = 0; k < 2; ++k) dst[m][k] = *(const PG8_LAS bf16x8*)(lds + PG8_SA(b, h) + aoff + m * 2048 + k * 1024); } while (0)
; #define PG8_LDB(dst, b, h) do { _Pragma("unroll") for (int n = 0; n < 2; ++n) _Pragma("unroll") for (int k = 0; k < 2; ++k) dst[n][k] = *(const PG8_LAS bf16x8*)(lds + PG8_SB(b, h) + boff + n * 2048 + k * 1024); } while (0)
; #define PG8_MMA(ai, bj, At, Bt) do { __builtin_amdgcn_s_setprio(1); _Pragma("unroll") for (int m = 0; m < 4; ++m) _Pragma("unroll") for (int n = 0; n < 2; ++n) _Pragma("unroll") for (int k = 0; k < 2; ++k) \
;         acc[ai][bj][m][n] = __builtin_amdgcn_mfma_f32_16x16x32_bf16(Bt[n][k], At[m][k], acc[ai][bj][m][n], 0, 0, 0); __builtin_amdgcn_s_setprio(0); } while (0)
; #define PG8_WAIT_V(n) asm volatile("s_waitcnt vmcnt(" #n ")" ::: "memory")
; #define PG8_WAIT_L(n) asm volatile("s_waitcnt lgkmcnt(" #n ")" ::: "memory")
; #define PG8_BAR __builtin_amdgcn_s_barrier()
; #define PG8_SCHED __builtin_amdgcn_sched_barrier(0)
; template <class Epi, class Sched, bool ALIGN_EPI = false, bool SP2 = false, bool ACHUNK = false>
; __device__ __forceinline__ void gemm_phase(PG8_LAS unsigned char* lds, const Gemm g, const Sched& S, const Epi& E) {
;     ...
;             PG8_WAIT_V(8); PG8_WAIT_L(0); PG8_BAR; PG8_MMA(1, 0, At, B0); PG8_MMA(1, 1, At, B1); PG8_BAR; PG8_SCHED;
;             PG8_LDB(B0, 1, 0); PG8_LDB(B1, 1, 1); PG8_SCHED; PG8_LDA(At, 1, 0); PG8_STAGE(PG8_SA(0, 1), a2 + hstepA, voffA);
;             PG8_WAIT_V(8); PG8_WAIT_L(0); PG8_BAR; PG8_MMA(0, 0, At, B0); PG8_MMA(0, 1, At, B1); PG8_BAR; PG8_SCHED;
	s_setprio 1
	v_mfma_f32_16x16x32_bf16 v[60:63], v[146:149], v[184:187], v[60:63]
	v_mfma_f32_16x16x32_bf16 v[52:55], v[154:157], v[184:187], v[52:55]
	v_mfma_f32_16x16x32_bf16 v[44:47], v[146:149], v[198:201], v[44:47]
	v_mfma_f32_16x16x32_bf16 v[36:39], v[154:157], v[198:201], v[36:39]
	v_mfma_f32_16x16x32_bf16 v[28:31], v[146:149], v[206:209], v[28:31]
	v_mfma_f32_16x16x32_bf16 v[20:23], v[154:157], v[206:209], v[20:23]
	v_mfma_f32_16x16x32_bf16 v[12:15], v[146:149], v[214:217], v[12:15]
	v_mfma_f32_16x16x32_bf16 v[4:7], v[154:157], v[214:217], v[4:7]
	v_mfma_f32_16x16x32_bf16 v[60:63], v[150:153], v[188:191], v[60:63]
	v_mfma_f32_16x16x32_bf16 v[52:55], v[158:161], v[188:191], v[52:55]
	v_mfma_f32_16x16x32_bf16 v[44:47], v[150:153], v[202:205], v[44:47]
	v_mfma_f32_16x16x32_bf16 v[36:39], v[158:161], v[202:205], v[36:39]
	v_mfma_f32_16x16x32_bf16 v[28:31], v[150:153], v[210:213], v[28:31]
	v_mfma_f32_16x16x32_bf16 v[20:23], v[158:161], v[210:213], v[20:23]
	v_mfma_f32_16x16x32_bf16 v[12:15], v[150:153], v[218:221], v[12:15]
	v_mfma_f32_16x16x32_bf16 v[4:7], v[158:161], v[218:221], v[4:7]
	s_setprio 0
	s_setprio 1
	v_mfma_f32_16x16x32_bf16 v[64:67], v[162:165], v[184:187], v[64:67]
	v_mfma_f32_16x16x32_bf16 v[56:59], v[170:173], v[184:187], v[56:59]
	v_mfma_f32_16x16x32_bf16 v[48:51], v[162:165], v[198:201], v[48:51]
	v_mfma_f32_16x16x32_bf16 v[40:43], v[170:173], v[198:201], v[40:43]
	v_mfma_f32_16x16x32_bf16 v[32:35], v[162:165], v[206:209], v[32:35]
	v_mfma_f32_16x16x32_bf16 v[24:27], v[170:173], v[206:209], v[24:27]
	v_mfma_f32_16x16x32_bf16 v[16:19], v[162:165], v[214:217], v[16:19]
	v_mfma_f32_16x16x32_bf16 v[8:11], v[170:173], v[214:217], v[8:11]
	v_mfma_f32_16x16x32_bf16 v[64:67], v[166:169], v[188:191], v[64:67]
	v_mfma_f32_16x16x32_bf16 v[56:59], v[180:183], v[188:191], v[56:59]
	v_mfma_f32_16x16x32_bf16 v[48:51], v[166:169], v[202:205], v[48:51]
	v_mfma_f32_16x16x32_bf16 v[40:43], v[180:183], v[202:205], v[40:43]
	v_mfma_f32_16x16x32_bf16 v[32:35], v[166:169], v[210:213], v[32:35]
	v_mfma_f32_16x16x32_bf16 v[24:27], v[180:183], v[210:213], v[24:27]
	v_mfma_f32_16x16x32_bf16 v[16:19], v[166:169], v[218:221], v[16:19]
	v_mfma_f32_16x16x32_bf16 v[8:11], v[180:183], v[218:221], v[8:11]
	s_setprio 0
	s_barrier
	s_add_i32 s49, 0, 0x18000
	v_add_u32_e32 v2, s49, v175
	s_add_i32 s50, 0, 0x1c000
	ds_read_b128 v[146:149], v2
	ds_read_b128 v[150:153], v2 offset:1024
	ds_read_b128 v[154:157], v2 offset:2048
	ds_read_b128 v[158:161], v2 offset:3072
	v_add_u32_e32 v2, s50, v175
	ds_read_b128 v[162:165], v2
	ds_read_b128 v[166:169], v2 offset:1024
	ds_read_b128 v[170:173], v2 offset:2048
	ds_read_b128 v[180:183], v2 offset:3072
	s_add_u32 s6, s6, s18
	s_addc_u32 s7, s7, s19
	s_mov_b32 m0, s22
	v_lshl_add_u64 v[238:239], s[6:7], 0, v[132:133]
	ds_read_b128 v[184:187], v179 offset:32768
	ds_read_b128 v[188:191], v179 offset:33792
	ds_read_b128 v[198:201], v179 offset:34816
	ds_read_b128 v[202:205], v179 offset:35840
	ds_read_b128 v[206:209], v179 offset:36864
	ds_read_b128 v[210:213], v179 offset:37888
	ds_read_b128 v[214:217], v179 offset:38912
	ds_read_b128 v[218:221], v179 offset:39936
	global_load_lds_dwordx4 v[238:239], off
	v_lshl_add_u64 v[238:239], s[6:7], 0, v[136:137]
	s_mov_b32 m0, s23
	s_nop 0
	global_load_lds_dwordx4 v[238:239], off
	s_waitcnt vmcnt(8) lgkmcnt(0)
	s_barrier
	s_setprio 1
	v_mfma_f32_16x16x32_bf16 v[124:127], v[146:149], v[184:187], v[124:127]
	v_mfma_f32_16x16x32_bf16 v[116:119], v[154:157], v[184:187], v[116:119]
	v_mfma_f32_16x16x32_bf16 v[108:111], v[146:149], v[198:201], v[108:111]
	v_mfma_f32_16x16x32_bf16 v[100:103], v[154:157], v[198:201], v[100:103]
	v_mfma_f32_16x16x32_bf16 v[92:95], v[146:149], v[206:209], v[92:95]
	v_mfma_f32_16x16x32_bf16 v[84:87], v[154:157], v[206:209], v[84:87]
	v_mfma_f32_16x16x32_bf16 v[76:79], v[146:149], v[214:217], v[76:79]
	v_mfma_f32_16x16x32_bf16 v[68:71], v[154:157], v[214:217], v[68:71]
	v_mfma_f32_16x16x32_bf16 v[124:127], v[150:153], v[188:191], v[124:127]
	v_mfma_f32_16x16x32_bf16 v[116:119], v[158:161], v[188:191], v[116:119]
	v_mfma_f32_16x16x32_bf16 v[108:111], v[150:153], v[202:205], v[108:111]
	v_mfma_f32_16x16x32_bf16 v[100:103], v[158:161], v[202:205], v[100:103]
	v_mfma_f32_16x16x32_bf16 v[92:95], v[150:153], v[210:213], v[92:95]
	v_mfma_f32_16x16x32_bf16 v[84:87], v[158:161], v[210:213], v[84:87]
	v_mfma_f32_16x16x32_bf16 v[76:79], v[150:153], v[218:221], v[76:79]
	v_mfma_f32_16x16x32_bf16 v[68:71], v[158:161], v[218:221], v[68:71]
	s_setprio 0
	s_setprio 1
	v_mfma_f32_16x16x32_bf16 v[128:131], v[162:165], v[184:187], v[128:131]
	v_mfma_f32_16x16x32_bf16 v[120:123], v[170:173], v[184:187], v[120:123]
	v_mfma_f32_16x16x32_bf16 v[112:115], v[162:165], v[198:201], v[112:115]
	v_mfma_f32_16x16x32_bf16 v[104:107], v[170:173], v[198:201], v[104:107]
	v_mfma_f32_16x16x32_bf16 v[96:99], v[162:165], v[206:209], v[96:99]
	v_mfma_f32_16x16x32_bf16 v[88:91], v[170:173], v[206:209], v[88:91]
	v_mfma_f32_16x16x32_bf16 v[80:83], v[162:165], v[214:217], v[80:83]
	v_mfma_f32_16x16x32_bf16 v[72:75], v[170:173], v[214:217], v[72:75]
	v_mfma_f32_16x16x32_bf16 v[128:131], v[166:169], v[188:191], v[128:131]
	v_mfma_f32_16x16x32_bf16 v[120:123], v[180:183], v[188:191], v[120:123]
	v_mfma_f32_16x16x32_bf16 v[112:115], v[166:169], v[202:205], v[112:115]
	v_mfma_f32_16x16x32_bf16 v[104:107], v[180:183], v[202:205], v[104:107]
	v_mfma_f32_16x16x32_bf16 v[96:99], v[166:169], v[210:213], v[96:99]
	v_mfma_f32_16x16x32_bf16 v[88:91], v[180:183], v[210:213], v[88:91]
	v_mfma_f32_16x16x32_bf16 v[80:83], v[166:169], v[218:221], v[80:83]
	v_mfma_f32_16x16x32_bf16 v[72:75], v[180:183], v[218:221], v[72:75]
	s_setprio 0
	s_barrier
; #define PG8_STAGE(bufoff, gbase, voff) do { _Pragma("unroll") for (int _i = 0; _i < 2; ++_i) \
;         __builtin_amdgcn_global_load_lds((const unsigned*)((const char*)(gbase) + (voff)[_i]), (PG8_LAS unsigned*)(lds + (bufoff) + ldsw + _i * 8192), 16, 0, 0); } while (0)
; #define PG8_LDA(dst, b, h) do { _Pragma("unroll") for (int m = 0; m < 4; ++m) _Pragma("unroll") for (int k = 0; k < 2; ++k) dst[m][k] = *(const PG8_LAS bf16x8*)(lds + PG8_SA(b, h) + aoff + m * 2048 + k * 1024); } while (0)
; #define PG8_MMA(ai, bj, At, Bt) do { __builtin_amdgcn_s_setprio(1); _Pragma("unroll") for (int m = 0; m < 4; ++m) _Pragma("unroll") for (int n = 0; n < 2; ++n) _Pragma("unroll") for (int k = 0; k < 2; ++k) \
;         acc[ai][bj][m][n] = __builtin_amdgcn_mfma_f32_16x16x32_bf16(Bt[n][k], At[m][k], acc[ai][bj][m][n], 0, 0, 0); __builtin_amdgcn_s_setprio(0); } while (0)
; #define PG8_WAIT_V(n) asm volatile("s_waitcnt vmcnt(" #n ")" ::: "memory")
; #define PG8_WAIT_L(n) asm volatile("s_waitcnt lgkmcnt(" #n ")" ::: "memory")
; #define PG8_BAR __builtin_amdgcn_s_barrier()
; #define PG8_SCHED __builtin_amdgcn_sched_barrier(0)
; template <class Epi, class Sched, bool ALIGN_EPI = false, bool SP2 = false, bool ACHUNK = false>
; __device__ __forceinline__ void gemm_phase(PG8_LAS unsigned char* lds, const Gemm g, const Sched& S, const Epi& E) {
;     ...
;             PG8_LDA(At, 1, 1); PG8_STAGE(PG8_SB(1, 0), b3, voffB); PG8_STAGE(PG8_SB(1, 1), b3 + hstepB, voffB); PG8_STAGE(PG8_SA(1, 0), a3, voffA);
;             PG8_WAIT_V(8); PG8_WAIT_L(0); PG8_BAR; PG8_MMA(1, 0, At, B0); PG8_MMA(1, 1, At, B1); PG8_BAR; PG8_SCHED;
	s_add_i32 s6, s49, s13
	v_lshl_add_u64 v[192:193], v[192:193], 0, s[10:11]
	s_mov_b32 m0, s6
	ds_read_b128 v[184:187], v179 offset:49152
	ds_read_b128 v[188:191], v179 offset:50176
	ds_read_b128 v[198:201], v179 offset:51200
	ds_read_b128 v[202:205], v179 offset:52224
	ds_read_b128 v[206:209], v179 offset:53248
	ds_read_b128 v[210:213], v179 offset:54272
	ds_read_b128 v[214:217], v179 offset:55296
	ds_read_b128 v[218:221], v179 offset:56320
	global_load_lds_dwordx4 v[192:193], off
	v_lshl_add_u64 v[192:193], v[222:223], 0, s[10:11]
	s_add_i32 m0, s6, 0x2000
	s_add_i32 s6, s50, s13
	global_load_lds_dwordx4 v[192:193], off
	v_lshl_add_u64 v[192:193], v[224:225], 0, s[10:11]
	s_mov_b32 m0, s6
	s_nop 0
	global_load_lds_dwordx4 v[192:193], off
	v_lshl_add_u64 v[192:193], v[232:233], 0, s[10:11]
	s_add_i32 m0, s6, 0x2000
	s_nop 0
	global_load_lds_dwordx4 v[192:193], off
	v_lshl_add_u64 v[192:193], v[234:235], 0, s[10:11]
	s_mov_b32 m0, s25
	s_nop 0
	global_load_lds_dwordx4 v[192:193], off
	v_lshl_add_u64 v[192:193], v[236:237], 0, s[10:11]
	s_mov_b32 m0, s26
	s_nop 0
	global_load_lds_dwordx4 v[192:193], off
	s_waitcnt vmcnt(8) lgkmcnt(0)
	s_barrier
	s_setprio 1
	v_mfma_f32_16x16x32_bf16 v[60:63], v[146:149], v[184:187], v[60:63]
	v_mfma_f32_16x16x32_bf16 v[52:55], v[154:157], v[184:187], v[52:55]
	v_mfma_f32_16x16x32_bf16 v[44:47], v[146:149], v[198:201], v[44:47]
	v_mfma_f32_16x16x32_bf16 v[36:39], v[154:157], v[198:201], v[36:39]
	v_mfma_f32_16x16x32_bf16 v[28:31], v[146:149], v[206:209], v[28:31]
	v_mfma_f32_16x16x32_bf16 v[20:23], v[154:157], v[206:209], v[20:23]
	v_mfma_f32_16x16x32_bf16 v[12:15], v[146:149], v[214:217], v[12:15]
	v_mfma_f32_16x16x32_bf16 v[4:7], v[154:157], v[214:217], v[4:7]
	v_mfma_f32_16x16x32_bf16 v[60:63], v[150:153], v[188:191], v[60:63]
	v_mfma_f32_16x16x32_bf16 v[52:55], v[158:161], v[188:191], v[52:55]
	v_mfma_f32_16x16x32_bf16 v[44:47], v[150:153], v[202:205], v[44:47]
	v_mfma_f32_16x16x32_bf16 v[36:39], v[158:161], v[202:205], v[36:39]
	v_mfma_f32_16x16x32_bf16 v[28:31], v[150:153], v[210:213], v[28:31]
	v_mfma_f32_16x16x32_bf16 v[20:23], v[158:161], v[210:213], v[20:23]
	v_mfma_f32_16x16x32_bf16 v[12:15], v[150:153], v[218:221], v[12:15]
	v_mfma_f32_16x16x32_bf16 v[4:7], v[158:161], v[218:221], v[4:7]
	s_setprio 0
	s_setprio 1
	v_mfma_f32_16x16x32_bf16 v[64:67], v[162:165], v[184:187], v[64:67]
	v_mfma_f32_16x16x32_bf16 v[56:59], v[170:173], v[184:187], v[56:59]
	v_mfma_f32_16x16x32_bf16 v[48:51], v[162:165], v[198:201], v[48:51]
	v_mfma_f32_16x16x32_bf16 v[40:43], v[170:173], v[198:201], v[40:43]
	v_mfma_f32_16x16x32_bf16 v[32:35], v[162:165], v[206:209], v[32:35]
	v_mfma_f32_16x16x32_bf16 v[24:27], v[170:173], v[206:209], v[24:27]
	v_mfma_f32_16x16x32_bf16 v[16:19], v[162:165], v[214:217], v[16:19]
	v_mfma_f32_16x16x32_bf16 v[8:11], v[170:173], v[214:217], v[8:11]
	v_mfma_f32_16x16x32_bf16 v[64:67], v[166:169], v[188:191], v[64:67]
	v_mfma_f32_16x16x32_bf16 v[56:59], v[180:183], v[188:191], v[56:59]
	v_mfma_f32_16x16x32_bf16 v[48:51], v[166:169], v[202:205], v[48:51]
	v_mfma_f32_16x16x32_bf16 v[40:43], v[180:183], v[202:205], v[40:43]
	v_mfma_f32_16x16x32_bf16 v[32:35], v[166:169], v[210:213], v[32:35]
	v_mfma_f32_16x16x32_bf16 v[24:27], v[180:183], v[210:213], v[24:27]
	v_mfma_f32_16x16x32_bf16 v[16:19], v[166:169], v[218:221], v[16:19]
	v_mfma_f32_16x16x32_bf16 v[8:11], v[180:183], v[218:221], v[8:11]
	s_setprio 0
	s_barrier
	s_add_u32 s4, s4, 0x100
	s_addc_u32 s5, s5, 0
	s_add_u32 s8, s8, 0x100
	s_addc_u32 s9, s9, 0
	s_cmp_ge_i32 s48, s24
	s_mov_b32 s6, s48
	s_cbranch_scc0 .LBB0_377
	v_readlane_b32 s52, v254, 27
	v_readlane_b32 s53, v254, 28
	s_mov_b32 s50, s94

; #define PG8_STAGE(bufoff, gbase, voff) do { _Pragma("unroll") for (int _i = 0; _i < 2; ++_i) \
;         __builtin_amdgcn_global_load_lds((const unsigned*)((const char*)(gbase) + (voff)[_i]), (PG8_LAS unsigned*)(lds + (bufoff) + ldsw + _i * 8192), 16, 0, 0); } while (0)
; #define PG8_LDA(dst, b, h) do { _Pragma("unroll") for (int m = 0; m < 4; ++m) _Pragma("unroll") for (int k = 0; k < 2; ++k) dst[m][k] = *(const PG8_LAS bf16x8*)(lds + PG8_SA(b, h) + aoff + m * 2048 + k * 1024); } while (0)
; #define PG8_LDB(dst, b, h) do { _Pragma("unroll") for (int n = 0; n < 2; ++n) _Pragma("unroll") for (int k = 0; k < 2; ++k) dst[n][k] = *(const PG8_LAS bf16x8*)(lds + PG8_SB(b, h) + boff + n * 2048 + k * 1024); } while (0)
; #define PG8_MMA(ai, bj, At, Bt) do { __builtin_amdgcn_s_setprio(1); _Pragma("unroll") for (int m = 0; m < 4; ++m) _Pragma("unroll") for (int n = 0; n < 2; ++n) _Pragma("unroll") for (int k = 0; k < 2; ++k) \
;         acc[ai][bj][m][n] = __builtin_amdgcn_mfma_f32_16x16x32_bf16(Bt[n][k], At[m][k], acc[ai][bj][m][n], 0, 0, 0); __builtin_amdgcn_s_setprio(0); } while (0)
; #define PG8_WAIT_V(n) asm volatile("s_waitcnt vmcnt(" #n ")" ::: "memory")
; #define PG8_WAIT_L(n) asm volatile("s_waitcnt lgkmcnt(" #n ")" ::: "memory")
; #define PG8_BAR __builtin_amdgcn_s_barrier()
; #define PG8_SCHED __builtin_amdgcn_sched_barrier(0)
; template <class Epi, class Sched, bool ALIGN_EPI = false, bool SP2 = false, bool ACHUNK = false>
; __device__ __forceinline__ void gemm_phase(PG8_LAS unsigned char* lds, const Gemm g, const Sched& S, const Epi& E) {
;     ...
;             PG8_LDB(B0, 0, 0); PG8_LDB(B1, 0, 1); PG8_SCHED; PG8_LDA(At, 0, 0); PG8_STAGE(PG8_SA(1, 1), a1 + hstepA, voffA);
;             PG8_WAIT_V(8); PG8_WAIT_L(0); PG8_BAR; PG8_MMA(0, 0, At, B0); PG8_MMA(0, 1, At, B1); PG8_BAR; PG8_SCHED;
;             PG8_LDA(At, 0, 1); PG8_STAGE(PG8_SB(0, 0), b2, voffB); PG8_STAGE(PG8_SB(0, 1), b2 + hstepB, voffB); PG8_STAGE(PG8_SA(0, 0), a2, voffA);
;             PG8_WAIT_V(8); PG8_WAIT_L(0); PG8_BAR; PG8_MMA(1, 0, At, B0); PG8_MMA(1, 1, At, B1); PG8_BAR; PG8_SCHED;
.Lnl_pl:
	s_add_i32 s9, 0, 0x14000
	v_add_u32_e32 v144, s15, v221
	v_add_u32_e32 v160, s9, v221
	ds_read_b128 v[132:135], v144
	ds_read_b128 v[136:139], v144 offset:1024
	ds_read_b128 v[140:143], v144 offset:2048
	ds_read_b128 v[144:147], v144 offset:3072
	ds_read_b128 v[148:151], v160
	ds_read_b128 v[152:155], v160 offset:1024
	ds_read_b128 v[156:159], v160 offset:2048
	ds_read_b128 v[160:163], v160 offset:3072
	v_lshl_add_u64 v[214:215], s[0:1], 0, v[174:175]
	s_add_i32 m0, s27, 0xc000
	ds_read_b128 v[178:181], v223
	ds_read_b128 v[182:185], v223 offset:1024
	ds_read_b128 v[186:189], v223 offset:2048
	ds_read_b128 v[190:193], v223 offset:3072
	ds_read_b128 v[198:201], v223 offset:4096
	ds_read_b128 v[202:205], v223 offset:5120
	ds_read_b128 v[206:209], v223 offset:6144
	ds_read_b128 v[210:213], v223 offset:7168
	global_load_lds_dwordx4 v[214:215], off
	v_lshl_add_u64 v[214:215], s[0:1], 0, v[176:177]
	s_add_i32 m0, s27, 0xe000
	s_nop 0
	global_load_lds_dwordx4 v[214:215], off
	s_waitcnt vmcnt(8) lgkmcnt(0)
	s_barrier
	s_setprio 1
	v_mfma_f32_16x16x32_bf16 v[128:131], v[132:135], v[178:181], v[128:131]
	v_mfma_f32_16x16x32_bf16 v[124:127], v[140:143], v[178:181], v[124:127]
	v_mfma_f32_16x16x32_bf16 v[112:115], v[132:135], v[186:189], v[112:115]
	v_mfma_f32_16x16x32_bf16 v[108:111], v[140:143], v[186:189], v[108:111]
	v_mfma_f32_16x16x32_bf16 v[96:99], v[132:135], v[198:201], v[96:99]
	v_mfma_f32_16x16x32_bf16 v[92:95], v[140:143], v[198:201], v[92:95]
	v_mfma_f32_16x16x32_bf16 v[80:83], v[132:135], v[206:209], v[80:83]
	v_mfma_f32_16x16x32_bf16 v[76:79], v[140:143], v[206:209], v[76:79]
	v_mfma_f32_16x16x32_bf16 v[128:131], v[136:139], v[182:185], v[128:131]
	v_mfma_f32_16x16x32_bf16 v[124:127], v[144:147], v[182:185], v[124:127]
	v_mfma_f32_16x16x32_bf16 v[112:115], v[136:139], v[190:193], v[112:115]
	v_mfma_f32_16x16x32_bf16 v[108:111], v[144:147], v[190:193], v[108:111]
	v_mfma_f32_16x16x32_bf16 v[96:99], v[136:139], v[202:205], v[96:99]
	v_mfma_f32_16x16x32_bf16 v[92:95], v[144:147], v[202:205], v[92:95]
	v_mfma_f32_16x16x32_bf16 v[80:83], v[136:139], v[210:213], v[80:83]
	v_mfma_f32_16x16x32_bf16 v[76:79], v[144:147], v[210:213], v[76:79]
	s_setprio 0
	s_setprio 1
	v_mfma_f32_16x16x32_bf16 v[120:123], v[148:151], v[178:181], v[120:123]
	v_mfma_f32_16x16x32_bf16 v[116:119], v[156:159], v[178:181], v[116:119]
	v_mfma_f32_16x16x32_bf16 v[104:107], v[148:151], v[186:189], v[104:107]
	v_mfma_f32_16x16x32_bf16 v[100:103], v[156:159], v[186:189], v[100:103]
	v_mfma_f32_16x16x32_bf16 v[88:91], v[148:151], v[198:201], v[88:91]
	v_mfma_f32_16x16x32_bf16 v[84:87], v[156:159], v[198:201], v[84:87]
	v_mfma_f32_16x16x32_bf16 v[72:75], v[148:151], v[206:209], v[72:75]
	v_mfma_f32_16x16x32_bf16 v[68:71], v[156:159], v[206:209], v[68:71]
	v_mfma_f32_16x16x32_bf16 v[120:123], v[152:155], v[182:185], v[120:123]
	v_mfma_f32_16x16x32_bf16 v[116:119], v[160:163], v[182:185], v[116:119]
	v_mfma_f32_16x16x32_bf16 v[104:107], v[152:155], v[190:193], v[104:107]
	v_mfma_f32_16x16x32_bf16 v[100:103], v[160:163], v[190:193], v[100:103]
	v_mfma_f32_16x16x32_bf16 v[88:91], v[152:155], v[202:205], v[88:91]
	v_mfma_f32_16x16x32_bf16 v[84:87], v[160:163], v[202:205], v[84:87]
	v_mfma_f32_16x16x32_bf16 v[72:75], v[152:155], v[210:213], v[72:75]
	v_mfma_f32_16x16x32_bf16 v[68:71], v[160:163], v[210:213], v[68:71]
	s_setprio 0
	s_barrier
	s_add_i32 s15, s15, s26
	v_lshl_add_u64 v[214:215], s[16:17], 0, v[2:3]
	s_mov_b32 m0, s15
	ds_read_b128 v[178:181], v223 offset:16384
	ds_read_b128 v[182:185], v223 offset:17408
	ds_read_b128 v[186:189], v223 offset:18432
	ds_read_b128 v[190:193], v223 offset:19456
	ds_read_b128 v[198:201], v223 offset:20480
	ds_read_b128 v[202:205], v223 offset:21504
	ds_read_b128 v[206:209], v223 offset:22528
	ds_read_b128 v[210:213], v223 offset:23552
	global_load_lds_dwordx4 v[214:215], off
	s_add_i32 m0, s15, 0x2000
	v_lshl_add_u64 v[216:217], s[16:17], 0, v[168:169]
	s_add_u32 s16, s16, s18
	s_addc_u32 s17, s17, s19
	s_add_i32 s9, s9, s26
	global_load_lds_dwordx4 v[216:217], off
	v_lshl_add_u64 v[218:219], s[16:17], 0, v[2:3]
	s_mov_b32 m0, s9
	v_lshl_add_u64 v[232:233], s[16:17], 0, v[168:169]
	global_load_lds_dwordx4 v[218:219], off
	s_add_i32 m0, s9, 0x2000
	v_lshl_add_u64 v[234:235], s[4:5], 0, v[164:165]
	global_load_lds_dwordx4 v[232:233], off
	s_mov_b32 m0, s27
	v_lshl_add_u64 v[236:237], s[4:5], 0, v[166:167]
	global_load_lds_dwordx4 v[234:235], off
	s_mov_b32 m0, s36
	s_nop 0
	global_load_lds_dwordx4 v[236:237], off
	s_waitcnt vmcnt(8) lgkmcnt(0)
	s_barrier
; #define PG8_STAGE(bufoff, gbase, voff) do { _Pragma("unroll") for (int _i = 0; _i < 2; ++_i) \
;         __builtin_amdgcn_global_load_lds((const unsigned*)((const char*)(gbase) + (voff)[_i]), (PG8_LAS unsigned*)(lds + (bufoff) + ldsw + _i * 8192), 16, 0, 0); } while (0)
; #define PG8_LDA(dst, b, h) do { _Pragma("unroll") for (int m = 0; m < 4; ++m) _Pragma("unroll") for (int k = 0; k < 2; ++k) dst[m][k] = *(const PG8_LAS bf16x8*)(lds + PG8_SA(b, h) + aoff + m * 2048 + k * 1024); } while (0)
; #define PG8_LDB(dst, b, h) do { _Pragma("unroll") for (int n = 0; n < 2; ++n) _Pragma("unroll") for (int k = 0; k < 2; ++k) dst[n][k] = *(const PG8_LAS bf16x8*)(lds + PG8_SB(b, h) + boff + n * 2048 + k * 1024); } while (0)
; #define PG8_MMA(ai, bj, At, Bt) do { __builtin_amdgcn_s_setprio(1); _Pragma("unroll") for (int m = 0; m < 4; ++m) _Pragma("unroll") for (int n = 0; n < 2; ++n) _Pragma("unroll") for (int k = 0; k < 2; ++k) \
;         acc[ai][bj][m][n] = __builtin_amdgcn_mfma_f32_16x16x32_bf16(Bt[n][k], At[m][k], acc[ai][bj][m][n], 0, 0, 0); __builtin_amdgcn_s_setprio(0); } while (0)
; #define PG8_WAIT_V(n) asm volatile("s_waitcnt vmcnt(" #n ")" ::: "memory")
; #define PG8_WAIT_L(n) asm volatile("s_waitcnt lgkmcnt(" #n ")" ::: "memory")
; #define PG8_BAR __builtin_amdgcn_s_barrier()
; #define PG8_SCHED __builtin_amdgcn_sched_barrier(0)
; template <class Epi, class Sched, bool ALIGN_EPI = false, bool SP2 = false, bool ACHUNK = false>
; __device__ __forceinline__ void gemm_phase(PG8_LAS unsigned char* lds, const Gemm g, const Sched& S, const Epi& E) {
;     ...
;             PG8_WAIT_V(8); PG8_WAIT_L(0); PG8_BAR; PG8_MMA(1, 0, At, B0); PG8_MMA(1, 1, At, B1); PG8_BAR; PG8_SCHED;
;             PG8_LDB(B0, 1, 0); PG8_LDB(B1, 1, 1); PG8_SCHED; PG8_LDA(At, 1, 0); PG8_STAGE(PG8_SA(0, 1), a2 + hstepA, voffA);
;             PG8_WAIT_V(8); PG8_WAIT_L(0); PG8_BAR; PG8_MMA(0, 0, At, B0); PG8_MMA(0, 1, At, B1); PG8_BAR; PG8_SCHED;
	s_setprio 1
	v_mfma_f32_16x16x32_bf16 v[64:67], v[132:135], v[178:181], v[64:67]
	v_mfma_f32_16x16x32_bf16 v[60:63], v[140:143], v[178:181], v[60:63]
	v_mfma_f32_16x16x32_bf16 v[48:51], v[132:135], v[186:189], v[48:51]
	v_mfma_f32_16x16x32_bf16 v[44:47], v[140:143], v[186:189], v[44:47]
	v_mfma_f32_16x16x32_bf16 v[32:35], v[132:135], v[198:201], v[32:35]
	v_mfma_f32_16x16x32_bf16 v[28:31], v[140:143], v[198:201], v[28:31]
	v_mfma_f32_16x16x32_bf16 v[16:19], v[132:135], v[206:209], v[16:19]
	v_mfma_f32_16x16x32_bf16 v[12:15], v[140:143], v[206:209], v[12:15]
	v_mfma_f32_16x16x32_bf16 v[64:67], v[136:139], v[182:185], v[64:67]
	v_mfma_f32_16x16x32_bf16 v[60:63], v[144:147], v[182:185], v[60:63]
	v_mfma_f32_16x16x32_bf16 v[48:51], v[136:139], v[190:193], v[48:51]
	v_mfma_f32_16x16x32_bf16 v[44:47], v[144:147], v[190:193], v[44:47]
	v_mfma_f32_16x16x32_bf16 v[32:35], v[136:139], v[202:205], v[32:35]
	v_mfma_f32_16x16x32_bf16 v[28:31], v[144:147], v[202:205], v[28:31]
	v_mfma_f32_16x16x32_bf16 v[16:19], v[136:139], v[210:213], v[16:19]
	v_mfma_f32_16x16x32_bf16 v[12:15], v[144:147], v[210:213], v[12:15]
	s_setprio 0
	s_setprio 1
	v_mfma_f32_16x16x32_bf16 v[56:59], v[148:151], v[178:181], v[56:59]
	v_mfma_f32_16x16x32_bf16 v[52:55], v[156:159], v[178:181], v[52:55]
	v_mfma_f32_16x16x32_bf16 v[40:43], v[148:151], v[186:189], v[40:43]
	v_mfma_f32_16x16x32_bf16 v[36:39], v[156:159], v[186:189], v[36:39]
	v_mfma_f32_16x16x32_bf16 v[24:27], v[148:151], v[198:201], v[24:27]
	v_mfma_f32_16x16x32_bf16 v[20:23], v[156:159], v[198:201], v[20:23]
	v_mfma_f32_16x16x32_bf16 v[8:11], v[148:151], v[206:209], v[8:11]
	v_mfma_f32_16x16x32_bf16 v[4:7], v[156:159], v[206:209], v[4:7]
	v_mfma_f32_16x16x32_bf16 v[56:59], v[152:155], v[182:185], v[56:59]
	v_mfma_f32_16x16x32_bf16 v[52:55], v[160:163], v[182:185], v[52:55]
	v_mfma_f32_16x16x32_bf16 v[40:43], v[152:155], v[190:193], v[40:43]
	v_mfma_f32_16x16x32_bf16 v[36:39], v[160:163], v[190:193], v[36:39]
	v_mfma_f32_16x16x32_bf16 v[24:27], v[152:155], v[202:205], v[24:27]
	v_mfma_f32_16x16x32_bf16 v[20:23], v[160:163], v[202:205], v[20:23]
	v_mfma_f32_16x16x32_bf16 v[8:11], v[152:155], v[210:213], v[8:11]
	v_mfma_f32_16x16x32_bf16 v[4:7], v[160:163], v[210:213], v[4:7]
	s_setprio 0
	s_barrier
	s_add_i32 s9, 0, 0x18000
	s_add_i32 s15, 0, 0x1c000
	v_add_u32_e32 v144, s9, v221
	v_add_u32_e32 v160, s15, v221
	ds_read_b128 v[132:135], v144
	ds_read_b128 v[136:139], v144 offset:1024
	ds_read_b128 v[140:143], v144 offset:2048
	ds_read_b128 v[144:147], v144 offset:3072
	ds_read_b128 v[148:151], v160
	ds_read_b128 v[152:155], v160 offset:1024
	ds_read_b128 v[156:159], v160 offset:2048
	ds_read_b128 v[160:163], v160 offset:3072
	s_add_u32 s4, s4, s18
	s_addc_u32 s5, s5, s19
	s_mov_b32 m0, s37
	v_lshl_add_u64 v[238:239], s[4:5], 0, v[164:165]
	ds_read_b128 v[178:181], v223 offset:32768
	ds_read_b128 v[182:185], v223 offset:33792
	ds_read_b128 v[186:189], v223 offset:34816
	ds_read_b128 v[190:193], v223 offset:35840
	ds_read_b128 v[198:201], v223 offset:36864
	ds_read_b128 v[202:205], v223 offset:37888
	ds_read_b128 v[206:209], v223 offset:38912
	ds_read_b128 v[210:213], v223 offset:39936
	global_load_lds_dwordx4 v[238:239], off
	v_lshl_add_u64 v[238:239], s[4:5], 0, v[166:167]
	s_mov_b32 m0, s76
	s_nop 0
	global_load_lds_dwordx4 v[238:239], off
	s_waitcnt vmcnt(8) lgkmcnt(0)
	s_barrier
	s_setprio 1
	v_mfma_f32_16x16x32_bf16 v[128:131], v[132:135], v[178:181], v[128:131]
	v_mfma_f32_16x16x32_bf16 v[124:127], v[140:143], v[178:181], v[124:127]
	v_mfma_f32_16x16x32_bf16 v[112:115], v[132:135], v[186:189], v[112:115]
	v_mfma_f32_16x16x32_bf16 v[108:111], v[140:143], v[186:189], v[108:111]
	v_mfma_f32_16x16x32_bf16 v[96:99], v[132:135], v[198:201], v[96:99]
	v_mfma_f32_16x16x32_bf16 v[92:95], v[140:143], v[198:201], v[92:95]
	v_mfma_f32_16x16x32_bf16 v[80:83], v[132:135], v[206:209], v[80:83]
	v_mfma_f32_16x16x32_bf16 v[76:79], v[140:143], v[206:209], v[76:79]
	v_mfma_f32_16x16x32_bf16 v[128:131], v[136:139], v[182:185], v[128:131]
	v_mfma_f32_16x16x32_bf16 v[124:127], v[144:147], v[182:185], v[124:127]
	v_mfma_f32_16x16x32_bf16 v[112:115], v[136:139], v[190:193], v[112:115]
	v_mfma_f32_16x16x32_bf16 v[108:111], v[144:147], v[190:193], v[108:111]
	v_mfma_f32_16x16x32_bf16 v[96:99], v[136:139], v[202:205], v[96:99]
	v_mfma_f32_16x16x32_bf16 v[92:95], v[144:147], v[202:205], v[92:95]
	v_mfma_f32_16x16x32_bf16 v[80:83], v[136:139], v[210:213], v[80:83]
	v_mfma_f32_16x16x32_bf16 v[76:79], v[144:147], v[210:213], v[76:79]
	s_setprio 0
	s_setprio 1
	v_mfma_f32_16x16x32_bf16 v[120:123], v[148:151], v[178:181], v[120:123]
	v_mfma_f32_16x16x32_bf16 v[116:119], v[156:159], v[178:181], v[116:119]
	v_mfma_f32_16x16x32_bf16 v[104:107], v[148:151], v[186:189], v[104:107]
	v_mfma_f32_16x16x32_bf16 v[100:103], v[156:159], v[186:189], v[100:103]
	v_mfma_f32_16x16x32_bf16 v[88:91], v[148:151], v[198:201], v[88:91]
	v_mfma_f32_16x16x32_bf16 v[84:87], v[156:159], v[198:201], v[84:87]
	v_mfma_f32_16x16x32_bf16 v[72:75], v[148:151], v[206:209], v[72:75]
	v_mfma_f32_16x16x32_bf16 v[68:71], v[156:159], v[206:209], v[68:71]
	v_mfma_f32_16x16x32_bf16 v[120:123], v[152:155], v[182:185], v[120:123]
	v_mfma_f32_16x16x32_bf16 v[116:119], v[160:163], v[182:185], v[116:119]
	v_mfma_f32_16x16x32_bf16 v[104:107], v[152:155], v[190:193], v[104:107]
	v_mfma_f32_16x16x32_bf16 v[100:103], v[160:163], v[190:193], v[100:103]
	v_mfma_f32_16x16x32_bf16 v[88:91], v[152:155], v[202:205], v[88:91]
	v_mfma_f32_16x16x32_bf16 v[84:87], v[160:163], v[202:205], v[84:87]
	v_mfma_f32_16x16x32_bf16 v[72:75], v[152:155], v[210:213], v[72:75]
	v_mfma_f32_16x16x32_bf16 v[68:71], v[160:163], v[210:213], v[68:71]
	s_setprio 0
	s_barrier
; #define PG8_STAGE(bufoff, gbase, voff) do { _Pragma("unroll") for (int _i = 0; _i < 2; ++_i) \
;         __builtin_amdgcn_global_load_lds((const unsigned*)((const char*)(gbase) + (voff)[_i]), (PG8_LAS unsigned*)(lds + (bufoff) + ldsw + _i * 8192), 16, 0, 0); } while (0)
; #define PG8_LDA(dst, b, h) do { _Pragma("unroll") for (int m = 0; m < 4; ++m) _Pragma("unroll") for (int k = 0; k < 2; ++k) dst[m][k] = *(const PG8_LAS bf16x8*)(lds + PG8_SA(b, h) + aoff + m * 2048 + k * 1024); } while (0)
; #define PG8_MMA(ai, bj, At, Bt) do { __builtin_amdgcn_s_setprio(1); _Pragma("unroll") for (int m = 0; m < 4; ++m) _Pragma("unroll") for (int n = 0; n < 2; ++n) _Pragma("unroll") for (int k = 0; k < 2; ++k) \
;         acc[ai][bj][m][n] = __builtin_amdgcn_mfma_f32_16x16x32_bf16(Bt[n][k], At[m][k], acc[ai][bj][m][n], 0, 0, 0); __builtin_amdgcn_s_setprio(0); } while (0)
; #define PG8_WAIT_V(n) asm volatile("s_waitcnt vmcnt(" #n ")" ::: "memory")
; #define PG8_WAIT_L(n) asm volatile("s_waitcnt lgkmcnt(" #n ")" ::: "memory")
; #define PG8_BAR __builtin_amdgcn_s_barrier()
; #define PG8_SCHED __builtin_amdgcn_sched_barrier(0)
; template <class Epi, class Sched, bool ALIGN_EPI = false, bool SP2 = false, bool ACHUNK = false>
; __device__ __forceinline__ void gemm_phase(PG8_LAS unsigned char* lds, const Gemm g, const Sched& S, const Epi& E) {
;     ...
;             PG8_LDA(At, 1, 1); PG8_STAGE(PG8_SB(1, 0), b3, voffB); PG8_STAGE(PG8_SB(1, 1), b3 + hstepB, voffB); PG8_STAGE(PG8_SA(1, 0), a3, voffA);
;             PG8_WAIT_V(8); PG8_WAIT_L(0); PG8_BAR; PG8_MMA(1, 0, At, B0); PG8_MMA(1, 1, At, B1); PG8_BAR; PG8_SCHED;
	s_add_i32 s4, s9, s26
	v_lshl_add_u64 v[214:215], v[214:215], 0, s[10:11]
	s_mov_b32 m0, s4
	ds_read_b128 v[178:181], v223 offset:49152
	ds_read_b128 v[182:185], v223 offset:50176
	ds_read_b128 v[186:189], v223 offset:51200
	ds_read_b128 v[190:193], v223 offset:52224
	ds_read_b128 v[198:201], v223 offset:53248
	ds_read_b128 v[202:205], v223 offset:54272
	ds_read_b128 v[206:209], v223 offset:55296
	ds_read_b128 v[210:213], v223 offset:56320
	global_load_lds_dwordx4 v[214:215], off
	v_lshl_add_u64 v[214:215], v[216:217], 0, s[10:11]
	s_add_i32 m0, s4, 0x2000
	s_add_i32 s4, s15, s26
	global_load_lds_dwordx4 v[214:215], off
	v_lshl_add_u64 v[214:215], v[218:219], 0, s[10:11]
	s_mov_b32 m0, s4
	s_nop 0
	global_load_lds_dwordx4 v[214:215], off
	v_lshl_add_u64 v[214:215], v[232:233], 0, s[10:11]
	s_add_i32 m0, s4, 0x2000
	s_nop 0
	global_load_lds_dwordx4 v[214:215], off
	v_lshl_add_u64 v[214:215], v[234:235], 0, s[10:11]
	s_mov_b32 m0, s77
	s_nop 0
	global_load_lds_dwordx4 v[214:215], off
	v_lshl_add_u64 v[214:215], v[236:237], 0, s[10:11]
	s_mov_b32 m0, s78
	s_nop 0
	global_load_lds_dwordx4 v[214:215], off
	s_waitcnt vmcnt(8) lgkmcnt(0)
	s_barrier
	s_setprio 1
	v_mfma_f32_16x16x32_bf16 v[64:67], v[132:135], v[178:181], v[64:67]
	v_mfma_f32_16x16x32_bf16 v[60:63], v[140:143], v[178:181], v[60:63]
	v_mfma_f32_16x16x32_bf16 v[48:51], v[132:135], v[186:189], v[48:51]
	v_mfma_f32_16x16x32_bf16 v[44:47], v[140:143], v[186:189], v[44:47]
	v_mfma_f32_16x16x32_bf16 v[32:35], v[132:135], v[198:201], v[32:35]
	v_mfma_f32_16x16x32_bf16 v[28:31], v[140:143], v[198:201], v[28:31]
	v_mfma_f32_16x16x32_bf16 v[16:19], v[132:135], v[206:209], v[16:19]
	v_mfma_f32_16x16x32_bf16 v[12:15], v[140:143], v[206:209], v[12:15]
	v_mfma_f32_16x16x32_bf16 v[64:67], v[136:139], v[182:185], v[64:67]
	v_mfma_f32_16x16x32_bf16 v[60:63], v[144:147], v[182:185], v[60:63]
	v_mfma_f32_16x16x32_bf16 v[48:51], v[136:139], v[190:193], v[48:51]
	v_mfma_f32_16x16x32_bf16 v[44:47], v[144:147], v[190:193], v[44:47]
	v_mfma_f32_16x16x32_bf16 v[32:35], v[136:139], v[202:205], v[32:35]
	v_mfma_f32_16x16x32_bf16 v[28:31], v[144:147], v[202:205], v[28:31]
	v_mfma_f32_16x16x32_bf16 v[16:19], v[136:139], v[210:213], v[16:19]
	v_mfma_f32_16x16x32_bf16 v[12:15], v[144:147], v[210:213], v[12:15]
	s_setprio 0
	s_setprio 1
	v_mfma_f32_16x16x32_bf16 v[56:59], v[148:151], v[178:181], v[56:59]
	v_mfma_f32_16x16x32_bf16 v[52:55], v[156:159], v[178:181], v[52:55]
	v_mfma_f32_16x16x32_bf16 v[40:43], v[148:151], v[186:189], v[40:43]
	v_mfma_f32_16x16x32_bf16 v[36:39], v[156:159], v[186:189], v[36:39]
	v_mfma_f32_16x16x32_bf16 v[24:27], v[148:151], v[198:201], v[24:27]
	v_mfma_f32_16x16x32_bf16 v[20:23], v[156:159], v[198:201], v[20:23]
	v_mfma_f32_16x16x32_bf16 v[8:11], v[148:151], v[206:209], v[8:11]
	v_mfma_f32_16x16x32_bf16 v[4:7], v[156:159], v[206:209], v[4:7]
	v_mfma_f32_16x16x32_bf16 v[56:59], v[152:155], v[182:185], v[56:59]
	v_mfma_f32_16x16x32_bf16 v[52:55], v[160:163], v[182:185], v[52:55]
	v_mfma_f32_16x16x32_bf16 v[40:43], v[152:155], v[190:193], v[40:43]
	v_mfma_f32_16x16x32_bf16 v[36:39], v[160:163], v[190:193], v[36:39]
	v_mfma_f32_16x16x32_bf16 v[24:27], v[152:155], v[202:205], v[24:27]
	v_mfma_f32_16x16x32_bf16 v[20:23], v[160:163], v[202:205], v[20:23]
	v_mfma_f32_16x16x32_bf16 v[8:11], v[152:155], v[210:213], v[8:11]
	v_mfma_f32_16x16x32_bf16 v[4:7], v[160:163], v[210:213], v[4:7]
	s_setprio 0
	s_barrier
	s_add_u32 s0, s0, 0x100
	s_addc_u32 s1, s1, 0
	s_add_u32 s6, s6, 0x100
	s_addc_u32 s7, s7, 0
	s_cmp_ge_i32 s8, s80
	s_mov_b32 s4, s8
	s_cbranch_scc0 .LBB0_431
